# nt hint on the attention/pooling phase's dwordx4 loads of the projection buffer (read essentially once), on top of v44
# speedup vs baseline: 1.0074x; 1.0074x over previous
; __device__ __forceinline__ void attn_macro(const Params& p, int l, LAS unsigned char* lds, int b, int cg, int kvh) {
;     ...
;     const int c0 = 4 * cg;
;     const long rowb = (long)b * SEQ;
;     const int gq = wid >> 1, half = wid & 1, h = kvh * 4 + gq, tq = half * 32 + q32;
;     u32x4 qraw[4];
; #pragma unroll
;     for (int i = 0; i < 4; ++i) qraw[i] = *(const u32x4*)(P + (size_t)(rowb + c0 * 64 + half * 32 + i * 8 + (lane >> 3)) * INW + h * 64 + (lane & 7) * 8);
;     u32x4 kraw[6], vraw[6];
; #pragma unroll
;     for (int it = 0; it < 6; ++it) {
;         const int idx = it * 512 + tid, j = idx >> 3, ch = idx & 7, tk = c0 * 64 - 128 + j;
;         kraw[it] = (u32x4){0u, 0u, 0u, 0u}; vraw[it] = kraw[it];
;         if (tk >= 0) { const size_t o = (size_t)(rowb + tk) * INW + kvh * 64 + ch * 8; kraw[it] = *(const u32x4*)(P + o + 512); vraw[it] = *(const u32x4*)(P + o + 640); }
;     }
.LBB0_287:
	s_cmp_gt_i32 s23, 15
	s_mov_b64 s[0:1], -1
	s_cbranch_scc0 .LBB0_413
	s_add_i32 s10, s23, -16
	v_mov_b32_e32 v136, v222
	s_bfe_u32 s12, s10, 0x10006
	s_xor_b32 s12, s12, 1
	s_lshr_b32 s7, s10, 7
	v_readfirstlane_b32 s0, v136
	s_and_b32 s11, s10, 63
	s_ashr_i32 s13, s0, 6
	s_ashr_i32 s14, s0, 7
	s_lshl_b32 s0, s12, 2
	s_lshl_b32 s15, s7, 14
	s_add_i32 s14, s14, s0
	s_lshl_b32 s0, s13, 5
	s_lshl_b32 s17, s11, 8
	s_and_b32 s16, s0, 32
	s_or_b32 s0, s17, s15
	s_or_b32 s96, s0, s16
	s_lshl_b32 s0, s14, 6
	v_and_b32_e32 v137, 63, v136
	s_ashr_i32 s1, s0, 31
	s_lshl_b64 s[2:3], s[0:1], 1
	v_lshlrev_b32_e32 v0, 3, v137
	v_ashrrev_i32_e32 v126, 3, v137
	s_add_u32 s0, s84, s2
	v_and_b32_e32 v0, 56, v0
	v_ashrrev_i32_e32 v127, 31, v126
	s_addc_u32 s1, s85, s3
	v_lshlrev_b32_e32 v56, 1, v0
	v_mov_b32_e32 v57, v97
	v_lshl_add_u64 v[0:1], s[0:1], 0, v[56:57]
	v_lshl_add_u64 v[2:3], s[96:97], 0, v[126:127]
	v_mad_u64_u32 v[4:5], s[8:9], v2, s89, v[0:1]
	s_or_b32 s8, s96, 8
	s_mov_b32 s9, s97
	v_mad_i32_i24 v5, v3, s89, v5
	v_lshl_add_u64 v[2:3], s[8:9], 0, v[126:127]
	v_mad_u64_u32 v[6:7], s[8:9], v2, s89, v[0:1]
	s_or_b32 s8, s96, 16
	s_mov_b32 s9, s97
	v_mad_i32_i24 v7, v3, s89, v7
	v_lshl_add_u64 v[2:3], s[8:9], 0, v[126:127]
	global_load_dwordx4 v[98:101], v[4:5], off nt
	global_load_dwordx4 v[102:105], v[6:7], off nt
	v_mad_u64_u32 v[4:5], s[8:9], v2, s89, v[0:1]
	s_or_b32 s96, s96, 24
	v_mad_i32_i24 v5, v3, s89, v5
	v_lshl_add_u64 v[2:3], s[96:97], 0, v[126:127]
	v_mad_u64_u32 v[0:1], s[8:9], v2, s89, v[0:1]
	v_mad_i32_i24 v1, v3, s89, v1
	global_load_dwordx4 v[106:109], v[4:5], off nt
	global_load_dwordx4 v[110:113], v[0:1], off nt
	s_addk_i32 s17, 0xff80
	v_lshlrev_b32_e32 v138, 3, v136
	s_lshl_b32 s8, s12, 7
	v_and_b32_e32 v57, 56, v138
	s_add_u32 s8, s84, s8
	v_ashrrev_i32_e32 v73, 3, v136
	s_addc_u32 s9, s85, 0
	v_lshlrev_b32_e32 v96, 1, v57
	v_add_u32_e32 v0, s17, v73
	v_lshl_add_u64 v[48:49], s[8:9], 0, v[96:97]
	v_cmp_lt_i32_e32 vcc, -1, v0
	v_mov_b32_e32 v32, 0
	v_mov_b32_e32 v44, 0
	v_mov_b32_e32 v45, 0
	v_mov_b32_e32 v46, 0
	v_mov_b32_e32 v47, 0
	v_mov_b32_e32 v40, 0
	v_mov_b32_e32 v41, 0
	v_mov_b32_e32 v42, 0
	v_mov_b32_e32 v43, 0
	s_and_saveexec_b64 s[8:9], vcc
	s_cbranch_execz .LBB0_290
	v_add_u32_e32 v0, s15, v0
	v_mad_u64_u32 v[0:1], s[40:41], v0, s89, v[48:49]
	global_load_dwordx4 v[40:43], v[0:1], off offset:1024 nt
	global_load_dwordx4 v[44:47], v[0:1], off offset:1280 nt
.LBB0_290:
	s_or_b64 exec, exec, s[8:9]
	v_add_u32_e32 v0, 0x200, v136
	v_ashrrev_i32_e32 v72, 3, v0
	v_add_u32_e32 v0, s17, v72
	v_cmp_lt_i32_e32 vcc, -1, v0
	v_mov_b32_e32 v33, 0
	v_mov_b32_e32 v34, 0
	v_mov_b32_e32 v35, 0
	v_mov_b32_e32 v36, 0
	v_mov_b32_e32 v37, 0
	v_mov_b32_e32 v38, 0
	v_mov_b32_e32 v39, 0
	s_and_saveexec_b64 s[8:9], vcc
	s_cbranch_execz .LBB0_292
	v_add_u32_e32 v0, s15, v0
	v_mad_u64_u32 v[0:1], s[40:41], v0, s89, v[48:49]
	global_load_dwordx4 v[36:39], v[0:1], off offset:1024 nt
	global_load_dwordx4 v[32:35], v[0:1], off offset:1280 nt
.LBB0_292:
	s_or_b64 exec, exec, s[8:9]
	v_add_u32_e32 v0, 0x400, v136
	v_ashrrev_i32_e32 v71, 3, v0
	v_add_u32_e32 v0, s17, v71
	v_cmp_lt_i32_e32 vcc, -1, v0
	v_mov_b32_e32 v16, 0
	v_mov_b32_e32 v24, 0
	v_mov_b32_e32 v25, 0
	v_mov_b32_e32 v26, 0
	v_mov_b32_e32 v27, 0
	v_mov_b32_e32 v28, 0
	v_mov_b32_e32 v29, 0
	v_mov_b32_e32 v30, 0
	v_mov_b32_e32 v31, 0
	s_and_saveexec_b64 s[8:9], vcc
	s_cbranch_execz .LBB0_294
	v_add_u32_e32 v0, s15, v0
	v_mad_u64_u32 v[0:1], s[40:41], v0, s89, v[48:49]
	global_load_dwordx4 v[28:31], v[0:1], off offset:1024 nt
	global_load_dwordx4 v[24:27], v[0:1], off offset:1280 nt
.LBB0_294:
	s_or_b64 exec, exec, s[8:9]
	v_add_u32_e32 v0, 0x600, v136
	v_ashrrev_i32_e32 v65, 3, v0
	v_add_u32_e32 v0, s17, v65
	v_cmp_lt_i32_e32 vcc, -1, v0
	v_mov_b32_e32 v17, 0
	v_mov_b32_e32 v18, 0
	v_mov_b32_e32 v19, 0
	v_mov_b32_e32 v20, 0
	v_mov_b32_e32 v21, 0
	v_mov_b32_e32 v22, 0
	v_mov_b32_e32 v23, 0
	s_and_saveexec_b64 s[8:9], vcc
	s_cbranch_execz .LBB0_296
	v_add_u32_e32 v0, s15, v0
	v_mad_u64_u32 v[0:1], s[40:41], v0, s89, v[48:49]
	global_load_dwordx4 v[20:23], v[0:1], off offset:1024 nt
	global_load_dwordx4 v[16:19], v[0:1], off offset:1280 nt
.LBB0_296:
	s_or_b64 exec, exec, s[8:9]
	v_add_u32_e32 v0, 0x800, v136
	v_ashrrev_i32_e32 v61, 3, v0
	v_add_u32_e32 v1, s17, v61
	v_cmp_lt_i32_e32 vcc, -1, v1
	v_mov_b32_e32 v0, 0
	v_mov_b32_e32 v8, 0
	v_mov_b32_e32 v9, 0
	v_mov_b32_e32 v10, 0
	v_mov_b32_e32 v11, 0
	v_mov_b32_e32 v12, 0
	v_mov_b32_e32 v13, 0
	v_mov_b32_e32 v14, 0
	v_mov_b32_e32 v15, 0
	s_and_saveexec_b64 s[8:9], vcc
	s_cbranch_execz .LBB0_298
	v_add_u32_e32 v1, s15, v1
	v_mad_u64_u32 v[2:3], s[40:41], v1, s89, v[48:49]
	global_load_dwordx4 v[12:15], v[2:3], off offset:1024 nt
	global_load_dwordx4 v[8:11], v[2:3], off offset:1280 nt
.LBB0_298:
	s_or_b64 exec, exec, s[8:9]
	v_add_u32_e32 v1, 0xa00, v136
	v_ashrrev_i32_e32 v59, 3, v1
	v_add_u32_e32 v50, s17, v59
	v_cmp_lt_i32_e32 vcc, -1, v50
	v_mov_b32_e32 v1, 0
	v_mov_b32_e32 v2, 0
	v_mov_b32_e32 v3, 0
	v_mov_b32_e32 v4, 0
	v_mov_b32_e32 v5, 0
	v_mov_b32_e32 v6, 0
	v_mov_b32_e32 v7, 0
	s_and_saveexec_b64 s[8:9], vcc
	s_cbranch_execz .LBB0_300
	v_add_u32_e32 v0, s15, v50
	v_mad_u64_u32 v[0:1], s[40:41], v0, s89, v[48:49]
	global_load_dwordx4 v[4:7], v[0:1], off offset:1024 nt
	s_nop 0
	global_load_dwordx4 v[0:3], v[0:1], off offset:1280 nt
; #define LAS __attribute__((address_space(3)))
; __device__ __forceinline__ unsigned cvt_pk_bf16(float lo, float hi) { unsigned r; asm volatile("v_cvt_pk_bf16_f32 %0, %1, %2" : "=v"(r) : "v"(lo), "v"(hi)); return r; }
; __device__ __forceinline__ void unpack8(const u32x4 w, float* f) { f[0] = bf_lo(w.x); f[1] = bf_hi(w.x); f[2] = bf_lo(w.y); f[3] = bf_hi(w.y); f[4] = bf_lo(w.z); f[5] = bf_hi(w.z); f[6] = bf_lo(w.w); f[7] = bf_hi(w.w); }
; __device__ __forceinline__ u32x4 pack8(const float* f) { u32x4 w; w.x = cvt_pk_bf16(f[0], f[1]); w.y = cvt_pk_bf16(f[2], f[3]); w.z = cvt_pk_bf16(f[4], f[5]); w.w = cvt_pk_bf16(f[6], f[7]); return w; }
; __device__ __forceinline__ void attn_macro(const Params& p, int l, LAS unsigned char* lds, int b, int cg, int kvh) {
;     ...
; #pragma unroll
;     for (int it = 0; it < 6; ++it) {
;         const int idx = it * 512 + tid, j = idx >> 3, ch = idx & 7;
;         float kf[8], vf[8]; unpack8(kraw[it], kf); unpack8(vraw[it], vf);
;         float ss = 0.f;
; #pragma unroll
;         for (int i = 0; i < 8; ++i) ss += kf[i] * kf[i];
;         ss += __shfl_xor(ss, 1); ss += __shfl_xor(ss, 2); ss += __shfl_xor(ss, 4);
;         const float sc = __builtin_amdgcn_rsqf(ss * (1.0f / 64.0f) + EPS);
; #pragma unroll
;         for (int i = 0; i < 8; ++i) kf[i] = kf[i] * sc * knorm[ch * 8 + i];
;         *(LAS u32x4*)(Ks + j * MK_LD + ch * 8) = pack8(kf);
;         const int js = j ^ (ch << 3);
; #pragma unroll
;         for (int i = 0; i < 8; i += 2) { const unsigned w = cvt_pk_bf16(vf[i], vf[i + 1]); Vt[(ch * 8 + i) * MV_LD + js] = (bf16_t)(w & 0xffffu); Vt[(ch * 8 + i + 1) * MV_LD + js] = (bf16_t)(w >> 16); }
;         if (cg == 63 && j >= 256) {
;             const size_t o = ((((size_t)l * 2 + b) * 128 + (j - 256)) * 2 + kvh) * 64 + ch * 8; float* kd = p.out + O_KP + o; float* vd = p.out + O_VP + o;
;             *(f32x4*)kd = (f32x4){kf[0], kf[1], kf[2], kf[3]}; *(f32x4*)(kd + 4) = (f32x4){kf[4], kf[5], kf[6], kf[7]};
;             *(f32x4*)vd = (f32x4){vf[0], vf[1], vf[2], vf[3]}; *(f32x4*)(vd + 4) = (f32x4){vf[4], vf[5], vf[6], vf[7]};
;         }
.LBB0_300:
	s_or_b64 exec, exec, s[8:9]
	v_lshlrev_b32_e32 v96, 2, v57
	global_load_dwordx4 v[52:55], v96, s[50:51] nt
	global_load_dwordx4 v[74:77], v96, s[50:51] offset:16 nt
	v_and_b32_e32 v60, 64, v225
	v_xor_b32_e32 v63, 1, v225
	s_waitcnt vmcnt(0) lgkmcnt(0)
	v_lshlrev_b32_e32 v78, 16, v40
	v_and_b32_e32 v79, 0xffff0000, v40
	v_add_u32_e32 v60, 64, v60
	v_lshlrev_b32_e32 v40, 16, v41
	v_and_b32_e32 v41, 0xffff0000, v41
	v_pk_mul_f32 v[66:67], v[78:79], v[78:79]
	v_cmp_lt_i32_e32 vcc, v63, v60
	v_pk_mul_f32 v[68:69], v[40:41], v[40:41]
	v_add_f32_e32 v66, v66, v67
	v_cndmask_b32_e32 v63, v225, v63, vcc
	v_lshlrev_b32_e32 v80, 16, v42
	v_and_b32_e32 v81, 0xffff0000, v42
	v_lshlrev_b32_e32 v64, 2, v63
	v_add_f32_e32 v63, v68, v66
	v_pk_mul_f32 v[82:83], v[80:81], v[80:81]
	v_add_f32_e32 v63, v69, v63
	v_lshlrev_b32_e32 v42, 16, v43
	v_and_b32_e32 v43, 0xffff0000, v43
	v_add_f32_e32 v63, v82, v63
	v_pk_mul_f32 v[84:85], v[42:43], v[42:43]
	v_add_f32_e32 v63, v83, v63
	v_add_f32_e32 v63, v84, v63
	v_add_f32_e32 v63, v85, v63
	ds_bpermute_b32 v67, v64, v63
	v_xor_b32_e32 v70, 2, v225
	v_cmp_lt_i32_e32 vcc, v70, v60
	v_xor_b32_e32 v86, 4, v225
	s_lshl_b32 s8, s12, 6
	v_cndmask_b32_e32 v66, v225, v70, vcc
	v_lshlrev_b32_e32 v66, 2, v66
	s_waitcnt lgkmcnt(0)
	v_add_f32_e32 v67, v63, v67
	ds_bpermute_b32 v69, v66, v67
	v_cmp_lt_i32_e32 vcc, v86, v60
	v_lshl_add_u32 v58, v57, 1, 0
	v_or_b32_e32 v62, s8, v57
	v_cndmask_b32_e32 v68, v225, v86, vcc
	v_lshlrev_b32_e32 v68, 2, v68
	s_waitcnt lgkmcnt(0)
	v_add_f32_e32 v67, v67, v69
	ds_bpermute_b32 v69, v68, v67
	v_mad_u64_u32 v[82:83], s[8:9], v73, s83, v[58:59]
	v_xor_b32_e32 v87, v57, v73
	s_movk_i32 s8, 0x30e
	s_waitcnt lgkmcnt(0)
	v_add_f32_e32 v67, v67, v69
	v_fmamk_f32 v67, v67, 0x3c800000, v223
	v_rsq_f32_e32 v70, v67
	v_mad_u32_u24 v63, v57, s8, v58
	v_lshlrev_b32_e32 v83, 1, v87
	v_lshlrev_b32_e32 v48, 16, v44
	v_pk_mul_f32 v[78:79], v[70:71], v[78:79] op_sel_hi:[0,1]
	v_pk_mul_f32 v[40:41], v[70:71], v[40:41] op_sel_hi:[0,1]
	v_pk_mul_f32 v[80:81], v[70:71], v[80:81] op_sel_hi:[0,1]
	v_pk_mul_f32 v[42:43], v[70:71], v[42:43] op_sel_hi:[0,1]
	v_and_b32_e32 v49, 0xffff0000, v44
	v_add_u32_e32 v84, v63, v83
	v_add_u32_e32 v67, 0x620, v63
	v_lshlrev_b32_e32 v50, 16, v45
	v_and_b32_e32 v51, 0xffff0000, v45
	v_add_u32_e32 v69, v67, v83
	s_cmp_eq_u32 s11, 63
	v_lshlrev_b32_e32 v44, 16, v46
	v_and_b32_e32 v45, 0xffff0000, v46
	s_cselect_b64 s[8:9], -1, 0
	s_and_b32 s15, s10, 0xffffff80
	s_movk_i32 s10, 0xff
	v_cmp_lt_i32_e32 vcc, s10, v73
	v_lshlrev_b32_e32 v46, 16, v47
	v_and_b32_e32 v47, 0xffff0000, v47
	s_add_i32 s15, s15, s18
	s_and_b64 s[40:41], s[8:9], vcc
	v_pk_mul_f32 v[52:53], v[52:53], v[78:79]
	v_pk_mul_f32 v[54:55], v[54:55], v[40:41]
	v_pk_mul_f32 v[40:41], v[74:75], v[80:81]
	v_pk_mul_f32 v[42:43], v[42:43], v[76:77]
	v_cvt_pk_bf16_f32 v74, v52, v53
	v_cvt_pk_bf16_f32 v75, v54, v55
	v_cvt_pk_bf16_f32 v76, v40, v41
	s_nop 0
	v_cvt_pk_bf16_f32 v77, v42, v43
	ds_write_b128 v82, v[74:77]
	v_cvt_pk_bf16_f32 v70, v48, v49
	ds_write_b16 v84, v70 offset:55296
	ds_write_b16_d16_hi v84, v70 offset:56080
	v_cvt_pk_bf16_f32 v70, v50, v51
	ds_write_b16 v69, v70 offset:55296
	ds_write_b16_d16_hi v69, v70 offset:56080
	v_add_u32_e32 v69, 0xc40, v63
	v_cvt_pk_bf16_f32 v70, v44, v45
	v_add_u32_e32 v74, v69, v83
	ds_write_b16 v74, v70 offset:55296
	ds_write_b16_d16_hi v74, v70 offset:56080
	v_add_u32_e32 v70, 0x1260, v63
	v_cvt_pk_bf16_f32 v74, v46, v47
	v_add_u32_e32 v75, v70, v83
	ds_write_b16 v75, v74 offset:55296
	ds_write_b16_d16_hi v75, v74 offset:56080
	s_and_saveexec_b64 s[10:11], s[40:41]
	s_cbranch_execz .LBB0_302
	v_add_u32_e32 v73, s15, v73
	v_add_u32_e32 v74, 0xffffff00, v73
	v_mov_b32_e32 v75, v97
	v_lshlrev_b64 v[74:75], 9, v[74:75]
	v_lshl_or_b32 v74, v62, 2, v74
	v_lshl_add_u64 v[76:77], s[54:55], 0, v[74:75]
	v_lshl_add_u64 v[74:75], s[56:57], 0, v[74:75]
	global_store_dwordx4 v[76:77], v[52:55], off
	global_store_dwordx4 v[76:77], v[40:43], off offset:16
	global_store_dwordx4 v[74:75], v[48:51], off
	global_store_dwordx4 v[74:75], v[44:47], off offset:16
.LBB0_302:
	s_or_b64 exec, exec, s[10:11]
	v_lshl_add_u64 v[48:49], s[50:51], 0, v[96:97]
	global_load_dwordx4 v[44:47], v[48:49], off nt
	global_load_dwordx4 v[50:53], v[48:49], off offset:16 nt
	v_lshlrev_b32_e32 v54, 16, v36
	v_and_b32_e32 v55, 0xffff0000, v36
	v_lshlrev_b32_e32 v36, 16, v37
	v_and_b32_e32 v37, 0xffff0000, v37
	v_pk_mul_f32 v[42:43], v[54:55], v[54:55]
	v_lshlrev_b32_e32 v40, 16, v32
	v_and_b32_e32 v41, 0xffff0000, v32
	v_pk_mul_f32 v[76:77], v[36:37], v[36:37]
	v_add_f32_e32 v32, v42, v43
	v_lshlrev_b32_e32 v74, 16, v38
	v_and_b32_e32 v75, 0xffff0000, v38
	v_add_f32_e32 v32, v76, v32
	v_pk_mul_f32 v[78:79], v[74:75], v[74:75]
	v_add_f32_e32 v32, v77, v32
	v_lshlrev_b32_e32 v38, 16, v39
	v_and_b32_e32 v39, 0xffff0000, v39
	v_add_f32_e32 v32, v78, v32
	v_pk_mul_f32 v[80:81], v[38:39], v[38:39]
	v_add_f32_e32 v32, v79, v32
	v_add_f32_e32 v32, v80, v32
	v_add_f32_e32 v73, v81, v32
	ds_bpermute_b32 v76, v64, v73
	v_lshlrev_b32_e32 v42, 16, v33
	v_and_b32_e32 v43, 0xffff0000, v33
	v_lshlrev_b32_e32 v32, 16, v34
	v_and_b32_e32 v33, 0xffff0000, v34
	s_waitcnt lgkmcnt(0)
	v_add_f32_e32 v73, v73, v76
	ds_bpermute_b32 v78, v66, v73
	v_mad_u64_u32 v[76:77], s[10:11], v72, s83, v[58:59]
	s_movk_i32 s10, 0xff
	s_nop 0
	v_cmp_lt_i32_e32 vcc, s10, v72
	s_waitcnt lgkmcnt(0)
	v_add_f32_e32 v73, v73, v78
	ds_bpermute_b32 v77, v68, v73
	v_xor_b32_e32 v78, v72, v57
	v_lshlrev_b32_e32 v79, 1, v78
	v_add_u32_e32 v80, v63, v79
	v_lshlrev_b32_e32 v34, 16, v35
	s_waitcnt lgkmcnt(0)
	v_add_f32_e32 v73, v73, v77
	v_fmamk_f32 v73, v73, 0x3c800000, v223
	v_rsq_f32_e32 v78, v73
	v_add_u32_e32 v73, v67, v79
	v_add_u32_e32 v77, v69, v79
	v_add_u32_e32 v79, v70, v79
	v_pk_mul_f32 v[54:55], v[78:79], v[54:55] op_sel_hi:[0,1]
	v_pk_mul_f32 v[36:37], v[78:79], v[36:37] op_sel_hi:[0,1]
	v_pk_mul_f32 v[74:75], v[78:79], v[74:75] op_sel_hi:[0,1]
	v_pk_mul_f32 v[38:39], v[78:79], v[38:39] op_sel_hi:[0,1]
	v_and_b32_e32 v35, 0xffff0000, v35
	s_and_b64 s[40:41], s[8:9], vcc
	s_waitcnt vmcnt(0)
	v_pk_mul_f32 v[44:45], v[44:45], v[54:55]
	v_pk_mul_f32 v[46:47], v[46:47], v[36:37]
	v_pk_mul_f32 v[36:37], v[50:51], v[74:75]
	v_cvt_pk_bf16_f32 v50, v44, v45
	v_pk_mul_f32 v[38:39], v[38:39], v[52:53]
	v_cvt_pk_bf16_f32 v51, v46, v47
	v_cvt_pk_bf16_f32 v52, v36, v37
	s_nop 0
	v_cvt_pk_bf16_f32 v53, v38, v39
	ds_write_b128 v76, v[50:53]
	v_cvt_pk_bf16_f32 v50, v40, v41
	ds_write_b16 v80, v50 offset:55296
	ds_write_b16_d16_hi v80, v50 offset:56080
	v_cvt_pk_bf16_f32 v50, v42, v43
	ds_write_b16 v73, v50 offset:55296
	ds_write_b16_d16_hi v73, v50 offset:56080
	v_cvt_pk_bf16_f32 v50, v32, v33
	ds_write_b16 v77, v50 offset:55296
	ds_write_b16_d16_hi v77, v50 offset:56080
	v_cvt_pk_bf16_f32 v50, v34, v35
	ds_write_b16 v79, v50 offset:55296
	ds_write_b16_d16_hi v79, v50 offset:56080
	s_and_saveexec_b64 s[10:11], s[40:41]
	s_cbranch_execz .LBB0_304
; #define LAS __attribute__((address_space(3)))
; __device__ __forceinline__ unsigned cvt_pk_bf16(float lo, float hi) { unsigned r; asm volatile("v_cvt_pk_bf16_f32 %0, %1, %2" : "=v"(r) : "v"(lo), "v"(hi)); return r; }
; __device__ __forceinline__ void unpack8(const u32x4 w, float* f) { f[0] = bf_lo(w.x); f[1] = bf_hi(w.x); f[2] = bf_lo(w.y); f[3] = bf_hi(w.y); f[4] = bf_lo(w.z); f[5] = bf_hi(w.z); f[6] = bf_lo(w.w); f[7] = bf_hi(w.w); }
; __device__ __forceinline__ u32x4 pack8(const float* f) { u32x4 w; w.x = cvt_pk_bf16(f[0], f[1]); w.y = cvt_pk_bf16(f[2], f[3]); w.z = cvt_pk_bf16(f[4], f[5]); w.w = cvt_pk_bf16(f[6], f[7]); return w; }
; __device__ __forceinline__ void attn_macro(const Params& p, int l, LAS unsigned char* lds, int b, int cg, int kvh) {
;     ...
; #pragma unroll
;     for (int it = 0; it < 6; ++it) {
;         const int idx = it * 512 + tid, j = idx >> 3, ch = idx & 7;
;         float kf[8], vf[8]; unpack8(kraw[it], kf); unpack8(vraw[it], vf);
;         float ss = 0.f;
; #pragma unroll
;         for (int i = 0; i < 8; ++i) ss += kf[i] * kf[i];
;         ss += __shfl_xor(ss, 1); ss += __shfl_xor(ss, 2); ss += __shfl_xor(ss, 4);
;         const float sc = __builtin_amdgcn_rsqf(ss * (1.0f / 64.0f) + EPS);
; #pragma unroll
;         for (int i = 0; i < 8; ++i) kf[i] = kf[i] * sc * knorm[ch * 8 + i];
;         *(LAS u32x4*)(Ks + j * MK_LD + ch * 8) = pack8(kf);
;         const int js = j ^ (ch << 3);
; #pragma unroll
;         for (int i = 0; i < 8; i += 2) { const unsigned w = cvt_pk_bf16(vf[i], vf[i + 1]); Vt[(ch * 8 + i) * MV_LD + js] = (bf16_t)(w & 0xffffu); Vt[(ch * 8 + i + 1) * MV_LD + js] = (bf16_t)(w >> 16); }
;         if (cg == 63 && j >= 256) {
;             const size_t o = ((((size_t)l * 2 + b) * 128 + (j - 256)) * 2 + kvh) * 64 + ch * 8; float* kd = p.out + O_KP + o; float* vd = p.out + O_VP + o;
;             *(f32x4*)kd = (f32x4){kf[0], kf[1], kf[2], kf[3]}; *(f32x4*)(kd + 4) = (f32x4){kf[4], kf[5], kf[6], kf[7]};
;             *(f32x4*)vd = (f32x4){vf[0], vf[1], vf[2], vf[3]}; *(f32x4*)(vd + 4) = (f32x4){vf[4], vf[5], vf[6], vf[7]};
;         }
	v_add_u32_e32 v50, s15, v72
	v_add_u32_e32 v96, 0xffffff00, v50
	v_lshlrev_b64 v[50:51], 9, v[96:97]
	v_lshl_or_b32 v50, v62, 2, v50
	v_lshl_add_u64 v[52:53], s[54:55], 0, v[50:51]
	v_lshl_add_u64 v[50:51], s[56:57], 0, v[50:51]
	global_store_dwordx4 v[52:53], v[44:47], off
	global_store_dwordx4 v[52:53], v[36:39], off offset:16
	global_store_dwordx4 v[50:51], v[40:43], off
	global_store_dwordx4 v[50:51], v[32:35], off offset:16
.LBB0_304:
	s_or_b64 exec, exec, s[10:11]
	global_load_dwordx4 v[36:39], v[48:49], off nt
	global_load_dwordx4 v[40:43], v[48:49], off offset:16 nt
	v_lshlrev_b32_e32 v44, 16, v28
	v_and_b32_e32 v45, 0xffff0000, v28
	v_lshlrev_b32_e32 v28, 16, v29
	v_and_b32_e32 v29, 0xffff0000, v29
	v_pk_mul_f32 v[34:35], v[44:45], v[44:45]
	v_lshlrev_b32_e32 v32, 16, v24
	v_and_b32_e32 v33, 0xffff0000, v24
	v_pk_mul_f32 v[50:51], v[28:29], v[28:29]
	v_add_f32_e32 v24, v34, v35
	v_lshlrev_b32_e32 v46, 16, v30
	v_and_b32_e32 v47, 0xffff0000, v30
	v_add_f32_e32 v24, v50, v24
	v_pk_mul_f32 v[52:53], v[46:47], v[46:47]
	v_add_f32_e32 v24, v51, v24
	v_lshlrev_b32_e32 v30, 16, v31
	v_and_b32_e32 v31, 0xffff0000, v31
	v_add_f32_e32 v24, v52, v24
	v_pk_mul_f32 v[54:55], v[30:31], v[30:31]
	v_add_f32_e32 v24, v53, v24
	v_add_f32_e32 v24, v54, v24
	v_add_f32_e32 v50, v55, v24
	ds_bpermute_b32 v51, v64, v50
	v_lshlrev_b32_e32 v34, 16, v25
	v_and_b32_e32 v35, 0xffff0000, v25
	v_lshlrev_b32_e32 v24, 16, v26
	v_and_b32_e32 v25, 0xffff0000, v26
	s_waitcnt lgkmcnt(0)
	v_add_f32_e32 v52, v50, v51
	ds_bpermute_b32 v53, v66, v52
	v_mad_u64_u32 v[50:51], s[10:11], v71, s83, v[58:59]
	s_movk_i32 s10, 0xff
	s_nop 0
	v_cmp_lt_i32_e32 vcc, s10, v71
	s_waitcnt lgkmcnt(0)
	v_add_f32_e32 v51, v52, v53
	ds_bpermute_b32 v52, v68, v51
	v_xor_b32_e32 v53, v71, v57
	v_lshlrev_b32_e32 v53, 1, v53
	v_add_u32_e32 v54, v63, v53
	v_add_u32_e32 v55, v69, v53
	s_waitcnt lgkmcnt(0)
	v_add_f32_e32 v51, v51, v52
	v_fmamk_f32 v51, v51, 0x3c800000, v223
	v_rsq_f32_e32 v52, v51
	v_add_u32_e32 v51, v67, v53
	v_add_u32_e32 v53, v70, v53
	v_lshlrev_b32_e32 v26, 16, v27
	v_pk_mul_f32 v[44:45], v[52:53], v[44:45] op_sel_hi:[0,1]
	v_pk_mul_f32 v[28:29], v[52:53], v[28:29] op_sel_hi:[0,1]
	v_pk_mul_f32 v[46:47], v[52:53], v[46:47] op_sel_hi:[0,1]
	v_pk_mul_f32 v[30:31], v[52:53], v[30:31] op_sel_hi:[0,1]
	v_and_b32_e32 v27, 0xffff0000, v27
	s_and_b64 s[40:41], s[8:9], vcc
	s_waitcnt vmcnt(0)
	v_pk_mul_f32 v[36:37], v[36:37], v[44:45]
	v_pk_mul_f32 v[38:39], v[38:39], v[28:29]
	v_pk_mul_f32 v[28:29], v[40:41], v[46:47]
	v_cvt_pk_bf16_f32 v40, v36, v37
	v_pk_mul_f32 v[30:31], v[30:31], v[42:43]
	v_cvt_pk_bf16_f32 v41, v38, v39
	v_cvt_pk_bf16_f32 v42, v28, v29
	s_nop 0
	v_cvt_pk_bf16_f32 v43, v30, v31
	ds_write_b128 v50, v[40:43]
	v_cvt_pk_bf16_f32 v40, v32, v33
	ds_write_b16 v54, v40 offset:55296
	ds_write_b16_d16_hi v54, v40 offset:56080
	v_cvt_pk_bf16_f32 v40, v34, v35
	ds_write_b16 v51, v40 offset:55296
	ds_write_b16_d16_hi v51, v40 offset:56080
	v_cvt_pk_bf16_f32 v40, v24, v25
	ds_write_b16 v55, v40 offset:55296
	ds_write_b16_d16_hi v55, v40 offset:56080
	v_cvt_pk_bf16_f32 v40, v26, v27
	ds_write_b16 v53, v40 offset:55296
	ds_write_b16_d16_hi v53, v40 offset:56080
	s_and_saveexec_b64 s[10:11], s[40:41]
	s_cbranch_execz .LBB0_306
	v_add_u32_e32 v40, s15, v71
	v_add_u32_e32 v96, 0xffffff00, v40
	v_lshlrev_b64 v[40:41], 9, v[96:97]
	v_lshl_or_b32 v40, v62, 2, v40
	v_lshl_add_u64 v[42:43], s[54:55], 0, v[40:41]
	v_lshl_add_u64 v[40:41], s[56:57], 0, v[40:41]
	global_store_dwordx4 v[42:43], v[36:39], off
	global_store_dwordx4 v[42:43], v[28:31], off offset:16
	global_store_dwordx4 v[40:41], v[32:35], off
	global_store_dwordx4 v[40:41], v[24:27], off offset:16
.LBB0_306:
	s_or_b64 exec, exec, s[10:11]
	global_load_dwordx4 v[28:31], v[48:49], off nt
	global_load_dwordx4 v[32:35], v[48:49], off offset:16 nt
	v_lshlrev_b32_e32 v36, 16, v20
	v_and_b32_e32 v37, 0xffff0000, v20
	v_lshlrev_b32_e32 v20, 16, v21
	v_and_b32_e32 v21, 0xffff0000, v21
	v_pk_mul_f32 v[26:27], v[36:37], v[36:37]
	v_lshlrev_b32_e32 v24, 16, v16
	v_and_b32_e32 v25, 0xffff0000, v16
	v_pk_mul_f32 v[40:41], v[20:21], v[20:21]
	v_add_f32_e32 v16, v26, v27
	v_lshlrev_b32_e32 v38, 16, v22
	v_and_b32_e32 v39, 0xffff0000, v22
	v_add_f32_e32 v16, v40, v16
	v_pk_mul_f32 v[42:43], v[38:39], v[38:39]
	v_add_f32_e32 v16, v41, v16
	v_lshlrev_b32_e32 v22, 16, v23
	v_and_b32_e32 v23, 0xffff0000, v23
	v_add_f32_e32 v16, v42, v16
	v_pk_mul_f32 v[44:45], v[22:23], v[22:23]
	v_add_f32_e32 v16, v43, v16
	v_add_f32_e32 v16, v44, v16
	v_add_f32_e32 v40, v45, v16
	ds_bpermute_b32 v41, v64, v40
	v_lshlrev_b32_e32 v26, 16, v17
	v_and_b32_e32 v27, 0xffff0000, v17
	v_lshlrev_b32_e32 v16, 16, v18
	v_and_b32_e32 v17, 0xffff0000, v18
	s_waitcnt lgkmcnt(0)
	v_add_f32_e32 v42, v40, v41
	ds_bpermute_b32 v43, v66, v42
	v_mad_u64_u32 v[40:41], s[10:11], v65, s83, v[58:59]
	s_movk_i32 s10, 0xff
	s_nop 0
	v_cmp_lt_i32_e32 vcc, s10, v65
	s_waitcnt lgkmcnt(0)
	v_add_f32_e32 v41, v42, v43
	ds_bpermute_b32 v42, v68, v41
	v_xor_b32_e32 v43, v65, v57
	v_lshlrev_b32_e32 v43, 1, v43
	v_add_u32_e32 v44, v63, v43
	v_add_u32_e32 v45, v69, v43
	s_waitcnt lgkmcnt(0)
	v_add_f32_e32 v41, v41, v42
	v_fmamk_f32 v41, v41, 0x3c800000, v223
	v_rsq_f32_e32 v42, v41
	v_add_u32_e32 v41, v67, v43
	v_add_u32_e32 v43, v70, v43
	v_lshlrev_b32_e32 v18, 16, v19
	v_pk_mul_f32 v[36:37], v[42:43], v[36:37] op_sel_hi:[0,1]
	v_pk_mul_f32 v[20:21], v[42:43], v[20:21] op_sel_hi:[0,1]
	v_pk_mul_f32 v[38:39], v[42:43], v[38:39] op_sel_hi:[0,1]
	v_pk_mul_f32 v[22:23], v[42:43], v[22:23] op_sel_hi:[0,1]
	v_and_b32_e32 v19, 0xffff0000, v19
	s_and_b64 s[40:41], s[8:9], vcc
	s_waitcnt vmcnt(0)
	v_pk_mul_f32 v[28:29], v[28:29], v[36:37]
	v_pk_mul_f32 v[30:31], v[30:31], v[20:21]
	v_pk_mul_f32 v[20:21], v[32:33], v[38:39]
	v_cvt_pk_bf16_f32 v32, v28, v29
	v_pk_mul_f32 v[22:23], v[22:23], v[34:35]
	v_cvt_pk_bf16_f32 v33, v30, v31
	v_cvt_pk_bf16_f32 v34, v20, v21
	s_nop 0
	v_cvt_pk_bf16_f32 v35, v22, v23
	ds_write_b128 v40, v[32:35]
	v_cvt_pk_bf16_f32 v32, v24, v25
	ds_write_b16 v44, v32 offset:55296
	ds_write_b16_d16_hi v44, v32 offset:56080
	v_cvt_pk_bf16_f32 v32, v26, v27
	ds_write_b16 v41, v32 offset:55296
	ds_write_b16_d16_hi v41, v32 offset:56080
	v_cvt_pk_bf16_f32 v32, v16, v17
	ds_write_b16 v45, v32 offset:55296
	ds_write_b16_d16_hi v45, v32 offset:56080
	v_cvt_pk_bf16_f32 v32, v18, v19
	ds_write_b16 v43, v32 offset:55296
	ds_write_b16_d16_hi v43, v32 offset:56080
	s_and_saveexec_b64 s[10:11], s[40:41]
	s_cbranch_execz .LBB0_308
	v_add_u32_e32 v32, s15, v65
	v_add_u32_e32 v96, 0xffffff00, v32
	v_lshlrev_b64 v[32:33], 9, v[96:97]
	v_lshl_or_b32 v32, v62, 2, v32
	v_lshl_add_u64 v[34:35], s[54:55], 0, v[32:33]
	v_lshl_add_u64 v[32:33], s[56:57], 0, v[32:33]
	global_store_dwordx4 v[34:35], v[28:31], off
	global_store_dwordx4 v[34:35], v[20:23], off offset:16
	global_store_dwordx4 v[32:33], v[24:27], off
	global_store_dwordx4 v[32:33], v[16:19], off offset:16
; #define LAS __attribute__((address_space(3)))
; __device__ __forceinline__ unsigned cvt_pk_bf16(float lo, float hi) { unsigned r; asm volatile("v_cvt_pk_bf16_f32 %0, %1, %2" : "=v"(r) : "v"(lo), "v"(hi)); return r; }
; __device__ __forceinline__ void unpack8(const u32x4 w, float* f) { f[0] = bf_lo(w.x); f[1] = bf_hi(w.x); f[2] = bf_lo(w.y); f[3] = bf_hi(w.y); f[4] = bf_lo(w.z); f[5] = bf_hi(w.z); f[6] = bf_lo(w.w); f[7] = bf_hi(w.w); }
; __device__ __forceinline__ u32x4 pack8(const float* f) { u32x4 w; w.x = cvt_pk_bf16(f[0], f[1]); w.y = cvt_pk_bf16(f[2], f[3]); w.z = cvt_pk_bf16(f[4], f[5]); w.w = cvt_pk_bf16(f[6], f[7]); return w; }
; __device__ __forceinline__ void attn_macro(const Params& p, int l, LAS unsigned char* lds, int b, int cg, int kvh) {
;     ...
; #pragma unroll
;     for (int it = 0; it < 6; ++it) {
;         const int idx = it * 512 + tid, j = idx >> 3, ch = idx & 7;
;         float kf[8], vf[8]; unpack8(kraw[it], kf); unpack8(vraw[it], vf);
;         float ss = 0.f;
; #pragma unroll
;         for (int i = 0; i < 8; ++i) ss += kf[i] * kf[i];
;         ss += __shfl_xor(ss, 1); ss += __shfl_xor(ss, 2); ss += __shfl_xor(ss, 4);
;         const float sc = __builtin_amdgcn_rsqf(ss * (1.0f / 64.0f) + EPS);
; #pragma unroll
;         for (int i = 0; i < 8; ++i) kf[i] = kf[i] * sc * knorm[ch * 8 + i];
;         *(LAS u32x4*)(Ks + j * MK_LD + ch * 8) = pack8(kf);
;         const int js = j ^ (ch << 3);
; #pragma unroll
;         for (int i = 0; i < 8; i += 2) { const unsigned w = cvt_pk_bf16(vf[i], vf[i + 1]); Vt[(ch * 8 + i) * MV_LD + js] = (bf16_t)(w & 0xffffu); Vt[(ch * 8 + i + 1) * MV_LD + js] = (bf16_t)(w >> 16); }
;         if (cg == 63 && j >= 256) {
;             const size_t o = ((((size_t)l * 2 + b) * 128 + (j - 256)) * 2 + kvh) * 64 + ch * 8; float* kd = p.out + O_KP + o; float* vd = p.out + O_VP + o;
;             *(f32x4*)kd = (f32x4){kf[0], kf[1], kf[2], kf[3]}; *(f32x4*)(kd + 4) = (f32x4){kf[4], kf[5], kf[6], kf[7]};
;             *(f32x4*)vd = (f32x4){vf[0], vf[1], vf[2], vf[3]}; *(f32x4*)(vd + 4) = (f32x4){vf[4], vf[5], vf[6], vf[7]};
;         }
.LBB0_308:
	s_or_b64 exec, exec, s[10:11]
	global_load_dwordx4 v[20:23], v[48:49], off nt
	global_load_dwordx4 v[24:27], v[48:49], off offset:16 nt
	v_lshlrev_b32_e32 v28, 16, v12
	v_and_b32_e32 v29, 0xffff0000, v12
	v_lshlrev_b32_e32 v12, 16, v13
	v_and_b32_e32 v13, 0xffff0000, v13
	v_pk_mul_f32 v[18:19], v[28:29], v[28:29]
	v_lshlrev_b32_e32 v16, 16, v8
	v_and_b32_e32 v17, 0xffff0000, v8
	v_pk_mul_f32 v[32:33], v[12:13], v[12:13]
	v_add_f32_e32 v8, v18, v19
	v_lshlrev_b32_e32 v30, 16, v14
	v_and_b32_e32 v31, 0xffff0000, v14
	v_add_f32_e32 v8, v32, v8
	v_pk_mul_f32 v[34:35], v[30:31], v[30:31]
	v_add_f32_e32 v8, v33, v8
	v_lshlrev_b32_e32 v14, 16, v15
	v_and_b32_e32 v15, 0xffff0000, v15
	v_add_f32_e32 v8, v34, v8
	v_pk_mul_f32 v[36:37], v[14:15], v[14:15]
	v_add_f32_e32 v8, v35, v8
	v_add_f32_e32 v8, v36, v8
	v_add_f32_e32 v32, v37, v8
	ds_bpermute_b32 v33, v64, v32
	v_lshlrev_b32_e32 v18, 16, v9
	v_and_b32_e32 v19, 0xffff0000, v9
	v_lshlrev_b32_e32 v8, 16, v10
	v_and_b32_e32 v9, 0xffff0000, v10
	s_waitcnt lgkmcnt(0)
	v_add_f32_e32 v34, v32, v33
	ds_bpermute_b32 v35, v66, v34
	v_mad_u64_u32 v[32:33], s[10:11], v61, s83, v[58:59]
	s_movk_i32 s10, 0xff
	s_nop 0
	v_cmp_lt_i32_e32 vcc, s10, v61
	s_waitcnt lgkmcnt(0)
	v_add_f32_e32 v33, v34, v35
	ds_bpermute_b32 v34, v68, v33
	v_xor_b32_e32 v35, v61, v57
	v_lshlrev_b32_e32 v35, 1, v35
	v_add_u32_e32 v36, v63, v35
	v_add_u32_e32 v37, v69, v35
	s_waitcnt lgkmcnt(0)
	v_add_f32_e32 v33, v33, v34
	v_fmamk_f32 v33, v33, 0x3c800000, v223
	v_rsq_f32_e32 v34, v33
	v_add_u32_e32 v33, v67, v35
	v_add_u32_e32 v35, v70, v35
	v_lshlrev_b32_e32 v10, 16, v11
	v_pk_mul_f32 v[28:29], v[34:35], v[28:29] op_sel_hi:[0,1]
	v_pk_mul_f32 v[12:13], v[34:35], v[12:13] op_sel_hi:[0,1]
	v_pk_mul_f32 v[30:31], v[34:35], v[30:31] op_sel_hi:[0,1]
	v_pk_mul_f32 v[14:15], v[34:35], v[14:15] op_sel_hi:[0,1]
	v_and_b32_e32 v11, 0xffff0000, v11
	s_and_b64 s[40:41], s[8:9], vcc
	s_waitcnt vmcnt(0)
	v_pk_mul_f32 v[20:21], v[20:21], v[28:29]
	v_pk_mul_f32 v[22:23], v[22:23], v[12:13]
	v_pk_mul_f32 v[12:13], v[24:25], v[30:31]
	v_cvt_pk_bf16_f32 v24, v20, v21
	v_pk_mul_f32 v[14:15], v[14:15], v[26:27]
	v_cvt_pk_bf16_f32 v25, v22, v23
	v_cvt_pk_bf16_f32 v26, v12, v13
	s_nop 0
	v_cvt_pk_bf16_f32 v27, v14, v15
	ds_write_b128 v32, v[24:27]
	v_cvt_pk_bf16_f32 v24, v16, v17
	ds_write_b16 v36, v24 offset:55296
	ds_write_b16_d16_hi v36, v24 offset:56080
	v_cvt_pk_bf16_f32 v24, v18, v19
	ds_write_b16 v33, v24 offset:55296
	ds_write_b16_d16_hi v33, v24 offset:56080
	v_cvt_pk_bf16_f32 v24, v8, v9
	ds_write_b16 v37, v24 offset:55296
	ds_write_b16_d16_hi v37, v24 offset:56080
	v_cvt_pk_bf16_f32 v24, v10, v11
	ds_write_b16 v35, v24 offset:55296
	ds_write_b16_d16_hi v35, v24 offset:56080
	s_and_saveexec_b64 s[10:11], s[40:41]
	s_cbranch_execz .LBB0_310
	v_add_u32_e32 v24, s15, v61
	v_add_u32_e32 v96, 0xffffff00, v24
	v_lshlrev_b64 v[24:25], 9, v[96:97]
	v_lshl_or_b32 v24, v62, 2, v24
	v_lshl_add_u64 v[26:27], s[54:55], 0, v[24:25]
	v_lshl_add_u64 v[24:25], s[56:57], 0, v[24:25]
	global_store_dwordx4 v[26:27], v[20:23], off
	global_store_dwordx4 v[26:27], v[12:15], off offset:16
	global_store_dwordx4 v[24:25], v[16:19], off
	global_store_dwordx4 v[24:25], v[8:11], off offset:16
.LBB0_310:
	s_or_b64 exec, exec, s[10:11]
	global_load_dwordx4 v[12:15], v[48:49], off nt
	global_load_dwordx4 v[16:19], v[48:49], off offset:16 nt
	v_lshlrev_b32_e32 v20, 16, v4
	v_and_b32_e32 v21, 0xffff0000, v4
	v_lshlrev_b32_e32 v4, 16, v5
	v_and_b32_e32 v5, 0xffff0000, v5
	v_pk_mul_f32 v[10:11], v[20:21], v[20:21]
	v_lshlrev_b32_e32 v8, 16, v0
	v_and_b32_e32 v9, 0xffff0000, v0
	v_pk_mul_f32 v[24:25], v[4:5], v[4:5]
	v_add_f32_e32 v0, v10, v11
	v_lshlrev_b32_e32 v22, 16, v6
	v_and_b32_e32 v23, 0xffff0000, v6
	v_add_f32_e32 v0, v24, v0
	v_pk_mul_f32 v[26:27], v[22:23], v[22:23]
	v_add_f32_e32 v0, v25, v0
	v_lshlrev_b32_e32 v6, 16, v7
	v_and_b32_e32 v7, 0xffff0000, v7
	v_add_f32_e32 v0, v26, v0
	v_pk_mul_f32 v[28:29], v[6:7], v[6:7]
	v_add_f32_e32 v0, v27, v0
	v_add_f32_e32 v0, v28, v0
	v_add_f32_e32 v24, v29, v0
	ds_bpermute_b32 v25, v64, v24
	v_lshlrev_b32_e32 v10, 16, v1
	v_and_b32_e32 v11, 0xffff0000, v1
	v_lshlrev_b32_e32 v0, 16, v2
	v_and_b32_e32 v1, 0xffff0000, v2
	s_waitcnt lgkmcnt(0)
	v_add_f32_e32 v26, v24, v25
	ds_bpermute_b32 v27, v66, v26
	v_mad_u64_u32 v[24:25], s[10:11], v59, s83, v[58:59]
	s_movk_i32 s10, 0xff
	s_nop 0
	v_cmp_lt_i32_e32 vcc, s10, v59
	s_waitcnt lgkmcnt(0)
	v_add_f32_e32 v25, v26, v27
	ds_bpermute_b32 v26, v68, v25
	v_xor_b32_e32 v27, v59, v57
	v_lshlrev_b32_e32 v27, 1, v27
	v_add_u32_e32 v28, v63, v27
	v_add_u32_e32 v29, v69, v27
	s_waitcnt lgkmcnt(0)
	v_add_f32_e32 v25, v25, v26
	v_fmamk_f32 v25, v25, 0x3c800000, v223
	v_rsq_f32_e32 v26, v25
	v_add_u32_e32 v25, v67, v27
	v_add_u32_e32 v27, v70, v27
	v_lshlrev_b32_e32 v2, 16, v3
	v_pk_mul_f32 v[20:21], v[26:27], v[20:21] op_sel_hi:[0,1]
	v_pk_mul_f32 v[4:5], v[26:27], v[4:5] op_sel_hi:[0,1]
	v_pk_mul_f32 v[22:23], v[26:27], v[22:23] op_sel_hi:[0,1]
	v_pk_mul_f32 v[6:7], v[26:27], v[6:7] op_sel_hi:[0,1]
	v_and_b32_e32 v3, 0xffff0000, v3
	s_and_b64 s[10:11], s[8:9], vcc
	s_waitcnt vmcnt(0)
	v_pk_mul_f32 v[12:13], v[12:13], v[20:21]
	v_pk_mul_f32 v[14:15], v[14:15], v[4:5]
	v_pk_mul_f32 v[4:5], v[16:17], v[22:23]
	v_cvt_pk_bf16_f32 v16, v12, v13
	v_pk_mul_f32 v[6:7], v[6:7], v[18:19]
	v_cvt_pk_bf16_f32 v17, v14, v15
	v_cvt_pk_bf16_f32 v18, v4, v5
	s_nop 0
	v_cvt_pk_bf16_f32 v19, v6, v7
	ds_write_b128 v24, v[16:19]
	v_cvt_pk_bf16_f32 v16, v8, v9
	ds_write_b16 v28, v16 offset:55296
	ds_write_b16_d16_hi v28, v16 offset:56080
	v_cvt_pk_bf16_f32 v16, v10, v11
	ds_write_b16 v25, v16 offset:55296
	ds_write_b16_d16_hi v25, v16 offset:56080
	v_cvt_pk_bf16_f32 v16, v0, v1
	ds_write_b16 v29, v16 offset:55296
	ds_write_b16_d16_hi v29, v16 offset:56080
	v_cvt_pk_bf16_f32 v16, v2, v3
	ds_write_b16 v27, v16 offset:55296
	ds_write_b16_d16_hi v27, v16 offset:56080
	s_and_saveexec_b64 s[8:9], s[10:11]
	s_cbranch_execz .LBB0_312
	v_add_u32_e32 v16, s15, v59
	v_add_u32_e32 v96, 0xffffff00, v16
	v_lshlrev_b64 v[16:17], 9, v[96:97]
	v_lshl_or_b32 v16, v62, 2, v16
	v_lshl_add_u64 v[18:19], s[54:55], 0, v[16:17]
	v_lshl_add_u64 v[16:17], s[56:57], 0, v[16:17]
	global_store_dwordx4 v[18:19], v[12:15], off
	global_store_dwordx4 v[18:19], v[4:7], off offset:16
	global_store_dwordx4 v[16:17], v[8:11], off
	global_store_dwordx4 v[16:17], v[0:3], off offset:16

; #define LAS __attribute__((address_space(3)))
; __device__ __forceinline__ void unpack8(const u32x4 w, float* f) { f[0] = bf_lo(w.x); f[1] = bf_hi(w.x); f[2] = bf_lo(w.y); f[3] = bf_hi(w.y); f[4] = bf_lo(w.z); f[5] = bf_hi(w.z); f[6] = bf_lo(w.w); f[7] = bf_hi(w.w); }
; __device__ __forceinline__ u32x4 pack8(const float* f) { u32x4 w; w.x = cvt_pk_bf16(f[0], f[1]); w.y = cvt_pk_bf16(f[2], f[3]); w.z = cvt_pk_bf16(f[4], f[5]); w.w = cvt_pk_bf16(f[6], f[7]); return w; }
; __device__ __forceinline__ void attn_macro(const Params& p, int l, LAS unsigned char* lds, int b, int cg, int kvh) {
;     ...
;         {
;             LAS bf16_t* qst = (LAS bf16_t*)(lds + M_OST) + wid * (32 * 72);
; #pragma unroll
;             for (int i = 0; i < 4; ++i) *(LAS u32x4*)(qst + (i * 8 + (lane_ >> 3)) * 72 + (lane_ & 7) * 8) = qraw[i];
;             asm volatile("s_waitcnt lgkmcnt(0)" ::: "memory");
;             float qv[4][8]; float ss = 0.f;
; #pragma unroll
;             for (int d0 = 0; d0 < 4; ++d0) { unpack8(*(const LAS u32x4*)(qst + q32 * 72 + d0 * 16 + hi * 8), qv[d0]);
; #pragma unroll
;                 for (int i = 0; i < 8; ++i) ss += qv[d0][i] * qv[d0][i]; }
;             asm volatile("s_waitcnt lgkmcnt(0)" ::: "memory");
;             ss += __shfl_xor(ss, 32);
;             const float sc = __builtin_amdgcn_rsqf(ss * (1.0f / 64.0f) + EPS) * (0.125f * LOG2E);
; #pragma unroll
;             for (int d0 = 0; d0 < 4; ++d0) { float t8[8];
; #pragma unroll
;                 for (int i = 0; i < 8; ++i) t8[i] = qv[d0][i] * sc * qn[d0 * 16 + hi * 8 + i];
;                 qf[d0] = __builtin_bit_cast(bf16x8, pack8(t8)); }
;         }
.LBB0_314:
	v_mov_b32_e32 v145, v137
	s_movk_i32 s40, 0x90
	v_lshlrev_b32_e32 v0, 3, v145
	v_ashrrev_i32_e32 v8, 3, v145
	v_and_b32_e32 v0, 56, v0
	v_lshlrev_b32_e32 v96, 1, v0
	v_mul_lo_u32 v0, v8, s27
	v_and_b32_e32 v144, 31, v145
	v_ashrrev_i32_e32 v143, 5, v145
	v_add3_u32 v0, s11, v96, v0
	s_waitcnt vmcnt(0)
	ds_write_b128 v0, v[98:101]
	ds_write_b128 v0, v[102:105] offset:1152
	ds_write_b128 v0, v[106:109] offset:2304
	ds_write_b128 v0, v[110:113] offset:3456
	v_mul_u32_u24_e32 v0, 0x90, v144
	v_lshlrev_b32_e32 v16, 4, v143
	s_waitcnt lgkmcnt(0)
	v_add3_u32 v10, s11, v0, v16
	ds_read_b128 v[0:3], v10
	ds_read_b128 v[4:7], v10 offset:32
	s_cmpk_eq_i32 s25, 0x180
	s_waitcnt lgkmcnt(0)
	v_and_b32_e32 v30, 0xffff0000, v0
	v_lshlrev_b32_e32 v14, 16, v0
	v_mul_f32_e32 v12, v30, v30
	v_lshlrev_b32_e32 v29, 16, v1
	v_fmac_f32_e32 v12, v14, v14
	v_and_b32_e32 v28, 0xffff0000, v1
	v_fmac_f32_e32 v12, v29, v29
	v_lshlrev_b32_e32 v26, 16, v2
	v_fmac_f32_e32 v12, v28, v28
	v_and_b32_e32 v25, 0xffff0000, v2
	v_fmac_f32_e32 v12, v26, v26
	v_lshlrev_b32_e32 v24, 16, v3
	v_fmac_f32_e32 v12, v25, v25
	v_and_b32_e32 v23, 0xffff0000, v3
	v_fmac_f32_e32 v12, v24, v24
	v_fmac_f32_e32 v12, v23, v23
	s_waitcnt lgkmcnt(0)
	v_lshlrev_b32_e32 v27, 16, v4
	v_and_b32_e32 v22, 0xffff0000, v4
	v_fmac_f32_e32 v12, v27, v27
	v_lshlrev_b32_e32 v21, 16, v5
	v_fmac_f32_e32 v12, v22, v22
	v_and_b32_e32 v20, 0xffff0000, v5
	v_fmac_f32_e32 v12, v21, v21
	ds_read_b128 v[0:3], v10 offset:64
	v_lshlrev_b32_e32 v19, 16, v6
	v_fmac_f32_e32 v12, v20, v20
	v_and_b32_e32 v18, 0xffff0000, v6
	v_fmac_f32_e32 v12, v19, v19
	v_lshlrev_b32_e32 v17, 16, v7
	v_fmac_f32_e32 v12, v18, v18
	v_and_b32_e32 v9, 0xffff0000, v7
	v_fmac_f32_e32 v12, v17, v17
	v_fmac_f32_e32 v12, v9, v9
	s_waitcnt lgkmcnt(0)
	v_lshlrev_b32_e32 v42, 16, v0
	v_and_b32_e32 v37, 0xffff0000, v0
	v_fmac_f32_e32 v12, v42, v42
	v_lshlrev_b32_e32 v36, 16, v1
	v_fmac_f32_e32 v12, v37, v37
	v_and_b32_e32 v35, 0xffff0000, v1
	v_lshlrev_b32_e32 v34, 16, v2
	v_and_b32_e32 v33, 0xffff0000, v2
	v_lshlrev_b32_e32 v32, 16, v3
	v_and_b32_e32 v31, 0xffff0000, v3
	v_fmac_f32_e32 v12, v36, v36
	ds_read_b128 v[0:3], v10 offset:96
	v_fmac_f32_e32 v12, v35, v35
	v_fmac_f32_e32 v12, v34, v34
	v_fmac_f32_e32 v12, v33, v33
	v_fmac_f32_e32 v12, v32, v32
	v_fmac_f32_e32 v12, v31, v31
	s_waitcnt lgkmcnt(0)
	v_lshlrev_b32_e32 v41, 16, v0
	v_and_b32_e32 v40, 0xffff0000, v0
	v_fmac_f32_e32 v12, v41, v41
	v_lshlrev_b32_e32 v39, 16, v1
	v_fmac_f32_e32 v12, v40, v40
	v_and_b32_e32 v38, 0xffff0000, v1
	v_fmac_f32_e32 v12, v39, v39
	v_and_b32_e32 v10, 0xffff0000, v2
	v_lshlrev_b32_e32 v11, 16, v2
	v_fmac_f32_e32 v12, v38, v38
	v_pk_mul_f32 v[0:1], v[10:11], v[10:11]
	v_lshlrev_b32_e32 v13, 16, v3
	v_add_f32_e32 v1, v1, v12
	v_and_b32_e32 v12, 0xffff0000, v3
	v_add_f32_e32 v2, v0, v1
	v_pk_mul_f32 v[0:1], v[12:13], v[12:13]
	s_waitcnt lgkmcnt(0)
	s_nop 0
	v_add_f32_e32 v1, v1, v2
	v_add_f32_e32 v0, v0, v1
	ds_bpermute_b32 v1, v141, v0
	s_waitcnt lgkmcnt(0)
	v_add_f32_e32 v0, v0, v1
	v_fmamk_f32 v0, v0, 0x3c800000, v223
	v_rsq_f32_e32 v0, v0
	s_nop 0
	v_mul_f32_e32 v43, 0x3e38aa3b, v0
	v_lshlrev_b32_e32 v0, 3, v143
	v_ashrrev_i32_e32 v1, 31, v0
	v_mul_f32_e32 v44, v43, v14
	v_lshl_add_u64 v[14:15], v[0:1], 2, s[58:59]
	global_load_dwordx4 v[0:3], v[14:15], off offset:16 nt
	global_load_dwordx4 v[4:7], v[14:15], off nt
	v_mul_f32_e32 v26, v43, v26
	v_mul_f32_e32 v30, v43, v30
	v_mul_f32_e32 v29, v43, v29
	v_mul_f32_e32 v28, v43, v28
	v_mul_f32_e32 v21, v43, v21
	v_mul_f32_e32 v20, v43, v20
	v_mul_f32_e32 v19, v43, v19
	v_mul_f32_e32 v18, v43, v18
	v_mul_f32_e32 v17, v43, v17
	v_mul_f32_e32 v9, v43, v9
	v_mul_f32_e32 v22, v43, v22
	v_mul_f32_e32 v10, v43, v10
	v_mul_f32_e32 v11, v43, v11
	s_waitcnt vmcnt(1)
	v_mul_f32_e32 v26, v0, v26
	v_mul_f32_e32 v0, v43, v25
	v_mul_f32_e32 v25, v1, v0
	v_mul_f32_e32 v0, v43, v24
	v_mul_f32_e32 v24, v2, v0
	v_mul_f32_e32 v0, v43, v23
	s_waitcnt vmcnt(0)
	v_mul_f32_e32 v4, v4, v44
	v_mul_f32_e32 v5, v5, v30
	v_mul_f32_e32 v6, v6, v29
	v_mul_f32_e32 v7, v7, v28
	v_mul_f32_e32 v3, v3, v0
	v_cvt_pk_bf16_f32 v0, v4, v5
	v_cvt_pk_bf16_f32 v1, v6, v7
	v_cvt_pk_bf16_f32 v2, v26, v25
	v_cvt_pk_bf16_f32 v3, v24, v3
	v_mul_f32_e32 v23, v43, v27
	global_load_dwordx4 v[4:7], v[14:15], off offset:80 nt
	global_load_dwordx4 v[24:27], v[14:15], off offset:64 nt
	s_waitcnt vmcnt(1)
	v_mul_f32_e32 v4, v4, v19
	s_waitcnt vmcnt(0)
	v_mul_f32_e32 v21, v26, v21
	v_mul_f32_e32 v20, v27, v20
	v_mul_f32_e32 v5, v5, v18
	v_mul_f32_e32 v6, v6, v17
	v_mul_f32_e32 v7, v7, v9
	v_mul_f32_e32 v23, v24, v23
	v_mul_f32_e32 v22, v25, v22
	v_cvt_pk_bf16_f32 v114, v23, v22
	v_cvt_pk_bf16_f32 v115, v21, v20
	v_cvt_pk_bf16_f32 v116, v4, v5
	v_cvt_pk_bf16_f32 v117, v6, v7
	global_load_dwordx4 v[4:7], v[14:15], off offset:144 nt
	global_load_dwordx4 v[18:21], v[14:15], off offset:128 nt
	v_mul_f32_e32 v9, v43, v42
	v_mul_f32_e32 v17, v43, v37
	s_waitcnt vmcnt(0)
	v_mul_f32_e32 v9, v18, v9
	v_mul_f32_e32 v18, v43, v36
	v_mul_f32_e32 v18, v20, v18
	v_mul_f32_e32 v20, v43, v34
	v_mul_f32_e32 v4, v4, v20
	v_mul_f32_e32 v20, v43, v33
	v_mul_f32_e32 v5, v5, v20
	v_mul_f32_e32 v20, v43, v32
	v_mul_f32_e32 v17, v19, v17
	v_mul_f32_e32 v19, v43, v35
	v_mul_f32_e32 v6, v6, v20
	v_mul_f32_e32 v20, v43, v31
	v_mul_f32_e32 v19, v21, v19
	v_mul_f32_e32 v7, v7, v20
	v_cvt_pk_bf16_f32 v118, v9, v17
	v_cvt_pk_bf16_f32 v119, v18, v19
	v_cvt_pk_bf16_f32 v120, v4, v5
	v_cvt_pk_bf16_f32 v121, v6, v7
	global_load_dwordx4 v[4:7], v[14:15], off offset:208 nt
	global_load_dwordx4 v[18:21], v[14:15], off offset:192 nt
	v_mul_f32_e32 v9, v43, v41
	v_mul_f32_e32 v14, v43, v40
	v_mul_f32_e32 v15, v43, v39
	v_mul_f32_e32 v17, v43, v38
	s_waitcnt vmcnt(1)
	v_mul_f32_e32 v5, v10, v5
	v_mul_f32_e32 v10, v43, v13
	v_mul_f32_e32 v6, v10, v6
	v_mul_f32_e32 v10, v43, v12
	s_waitcnt vmcnt(0)
	v_mul_f32_e32 v9, v9, v18
	v_mul_f32_e32 v14, v14, v19
	v_mul_f32_e32 v15, v15, v20
	v_mul_f32_e32 v17, v17, v21
	v_mul_f32_e32 v4, v11, v4
	v_mul_f32_e32 v7, v10, v7
	v_cvt_pk_bf16_f32 v122, v9, v14
	v_cvt_pk_bf16_f32 v123, v15, v17
	v_cvt_pk_bf16_f32 v124, v4, v5
	v_cvt_pk_bf16_f32 v125, v6, v7
	s_cbranch_scc1 .LBB0_316
; __device__ __forceinline__ void attn_macro(const Params& p, int l, LAS unsigned char* lds, int b, int cg, int kvh) {
;     ...
;         if (ci < 3) {
; #pragma unroll
;             for (int i = 0; i < 4; ++i) qraw[i] = *(const u32x4*)(P + (size_t)(row0 + 64 + half * 32 + i * 8 + (lane_ >> 3)) * INW + h * 64 + (lane_ & 7) * 8);
;         }
	s_add_i32 s27, s16, s17
	s_add_i32 s96, s27, 64
	v_ashrrev_i32_e32 v9, 31, v8
	v_lshl_add_u64 v[4:5], s[0:1], 0, v[96:97]
	v_lshl_add_u64 v[6:7], s[96:97], 0, v[8:9]
	v_mad_u64_u32 v[10:11], s[2:3], v6, s89, v[4:5]
	s_add_i32 s96, s27, 0x48
	v_mad_i32_i24 v11, v7, s89, v11
	v_lshl_add_u64 v[6:7], s[96:97], 0, v[8:9]
	v_mad_u64_u32 v[12:13], s[2:3], v6, s89, v[4:5]
	s_add_i32 s96, s27, 0x50
	v_mad_i32_i24 v13, v7, s89, v13
	v_lshl_add_u64 v[6:7], s[96:97], 0, v[8:9]
	global_load_dwordx4 v[98:101], v[10:11], off nt
	global_load_dwordx4 v[102:105], v[12:13], off nt
	v_mad_u64_u32 v[10:11], s[2:3], v6, s89, v[4:5]
	s_add_i32 s96, s27, 0x58
	v_mad_i32_i24 v11, v7, s89, v11
	v_lshl_add_u64 v[6:7], s[96:97], 0, v[8:9]
	v_mad_u64_u32 v[4:5], s[2:3], v6, s89, v[4:5]
	v_mad_i32_i24 v5, v7, s89, v5
	global_load_dwordx4 v[106:109], v[10:11], off nt
	global_load_dwordx4 v[110:113], v[4:5], off nt

; template <int W>
; __device__ __forceinline__ void pool_task_prompt(const Params& p, int l, int b, int c, int g, int rg, int ch, long row0) {
;     const bf16_t* P = (const bf16_t*)(p.ws + WS_PROJ);
;     bf16_t* AD = (bf16_t*)(p.ws + WS_AD);
;     const int col = g * 128 + ch * 8, tl0 = 4 * rg, t0 = c * 64 + tl0;
;     u32x4 raw[W + 3];
; #pragma unroll
;     for (int i = 0; i < W + 3; ++i) { const int tt = t0 - (W - 1) + i; raw[i] = (u32x4){0u, 0u, 0u, 0u};
;         if (tt >= 0) raw[i] = *(const u32x4*)(P + (size_t)((long)b * SEQ + tt) * INW + 768 + col); }
; __device__ __forceinline__ void attn_macro(const Params& p, int l, LAS unsigned char* lds, int b, int cg, int kvh) {
;     ...
;         const int gl = tid >> 8, g = kvh * 2 + gl, rg = (tid >> 4) & 15, ch = tid & 15;
; #pragma unroll 1
;         for (int ci = 0; ci < 4; ++ci) {
;             const int c = c0 + ci; const long row0 = rowb + (long)c * 64;
;             if (g == 0) pool_task_prompt<2>(p, l, b, c, g, rg, ch, row0);
;             else if (g == 1) pool_task_prompt<4>(p, l, b, c, g, rg, ch, row0);
;             else if (g == 2) pool_task_prompt<8>(p, l, b, c, g, rg, ch, row0);
;             else pool_task_prompt<16>(p, l, b, c, g, rg, ch, row0);
.LBB0_320:
	v_add_u32_e32 v101, s25, v99
	v_cmp_lt_i32_e32 vcc, 0, v98
	s_mov_b64 s[2:3], 0
	s_mov_b64 s[0:1], 0
	s_mov_b64 s[8:9], 0
	s_and_saveexec_b64 s[10:11], vcc
	s_xor_b64 s[10:11], exec, s[10:11]
	s_cbranch_execz .LBB0_399
	v_cmp_lt_i32_e32 vcc, 1, v98
	s_mov_b64 s[12:13], 0
	s_mov_b64 s[14:15], 0
	s_and_saveexec_b64 s[0:1], vcc
	s_xor_b64 s[8:9], exec, s[0:1]
	s_cbranch_execz .LBB0_345
	v_cmp_eq_u32_e32 vcc, 2, v98
	s_mov_b64 s[0:1], -1
	s_and_saveexec_b64 s[12:13], vcc
	s_cbranch_execz .LBB0_344
	v_cmp_lt_u32_e32 vcc, 6, v101
	v_mov_b32_e32 v4, 0
	v_lshlrev_b32_e32 v40, 1, v78
	v_mov_b32_e32 v12, 0
	v_mov_b32_e32 v13, 0
	v_mov_b32_e32 v14, 0
	v_mov_b32_e32 v15, 0
	s_and_saveexec_b64 s[0:1], vcc
	s_cbranch_execz .LBB0_325
	v_add3_u32 v2, v100, s25, -7
	v_mov_b64_e32 v[0:1], s[86:87]
	v_mad_u64_u32 v[0:1], s[14:15], v2, s89, v[0:1]
	v_mov_b32_e32 v41, v97
	v_lshl_add_u64 v[0:1], v[0:1], 0, v[40:41]
	v_add_co_u32_e32 v0, vcc, 0xfb00000, v0
	s_nop 1
	v_addc_co_u32_e32 v1, vcc, 0, v1, vcc
	global_load_dwordx4 v[12:15], v[0:1], off offset:1536 nt
.LBB0_325:
	s_or_b64 exec, exec, s[0:1]
	v_cmp_lt_u32_e32 vcc, 5, v101
	v_mov_b32_e32 v5, 0
	v_mov_b32_e32 v6, 0
	v_mov_b32_e32 v7, 0
	s_and_saveexec_b64 s[0:1], vcc
	s_cbranch_execz .LBB0_327
	v_add3_u32 v2, v100, s25, -6
	v_mov_b64_e32 v[0:1], s[86:87]
	v_mad_u64_u32 v[0:1], s[14:15], v2, s89, v[0:1]
	v_mov_b32_e32 v41, v97
	v_lshl_add_u64 v[0:1], v[0:1], 0, v[40:41]
	v_add_co_u32_e32 v0, vcc, 0xfb00000, v0
	s_nop 1
	v_addc_co_u32_e32 v1, vcc, 0, v1, vcc
	global_load_dwordx4 v[4:7], v[0:1], off offset:1536 nt
.LBB0_327:
	s_or_b64 exec, exec, s[0:1]
	v_cmp_lt_u32_e32 vcc, 4, v101
	v_mov_b32_e32 v16, 0
	v_mov_b32_e32 v20, 0
	v_mov_b32_e32 v21, 0
	v_mov_b32_e32 v22, 0
	v_mov_b32_e32 v23, 0
	s_and_saveexec_b64 s[0:1], vcc
	s_cbranch_execz .LBB0_329
	v_add3_u32 v2, v100, s25, -5
	v_mov_b64_e32 v[0:1], s[86:87]
	v_mad_u64_u32 v[0:1], s[14:15], v2, s89, v[0:1]
	v_mov_b32_e32 v41, v97
	v_lshl_add_u64 v[0:1], v[0:1], 0, v[40:41]
	v_add_co_u32_e32 v0, vcc, 0xfb00000, v0
	s_nop 1
	v_addc_co_u32_e32 v1, vcc, 0, v1, vcc
	global_load_dwordx4 v[20:23], v[0:1], off offset:1536 nt
.LBB0_329:
	s_or_b64 exec, exec, s[0:1]
	v_cmp_ne_u32_e64 s[0:1], 0, v101
	v_mov_b32_e32 v17, 0
	v_mov_b32_e32 v18, 0
	v_mov_b32_e32 v19, 0
	s_and_saveexec_b64 s[14:15], s[0:1]
	s_cbranch_execz .LBB0_331
	v_add3_u32 v2, v100, s25, -4
	v_mov_b64_e32 v[0:1], s[86:87]
	v_mad_u64_u32 v[0:1], s[16:17], v2, s89, v[0:1]
	v_mov_b32_e32 v41, v97
	v_lshl_add_u64 v[0:1], v[0:1], 0, v[40:41]
	v_add_co_u32_e32 v0, vcc, 0xfb00000, v0
	s_nop 1
	v_addc_co_u32_e32 v1, vcc, 0, v1, vcc
	global_load_dwordx4 v[16:19], v[0:1], off offset:1536 nt
.LBB0_331:
	s_or_b64 exec, exec, s[14:15]
	v_mov_b32_e32 v28, 0
	v_mov_b32_e32 v32, 0
	v_mov_b32_e32 v33, 0
	v_mov_b32_e32 v34, 0
	v_mov_b32_e32 v35, 0
	s_and_saveexec_b64 s[14:15], s[0:1]
	s_cbranch_execz .LBB0_333
	v_add3_u32 v2, v100, s25, -3
	v_mov_b64_e32 v[0:1], s[86:87]
	v_mad_u64_u32 v[0:1], s[16:17], v2, s89, v[0:1]
	v_mov_b32_e32 v41, v97
	v_lshl_add_u64 v[0:1], v[0:1], 0, v[40:41]
	v_add_co_u32_e32 v0, vcc, 0xfb00000, v0
	s_nop 1
	v_addc_co_u32_e32 v1, vcc, 0, v1, vcc
	global_load_dwordx4 v[32:35], v[0:1], off offset:1536 nt
.LBB0_333:
	s_or_b64 exec, exec, s[14:15]
	v_mov_b32_e32 v29, 0
	v_mov_b32_e32 v30, 0
	v_mov_b32_e32 v31, 0
	s_and_saveexec_b64 s[14:15], s[0:1]
	s_cbranch_execz .LBB0_335
	v_add3_u32 v2, v100, s25, -2
	v_mov_b64_e32 v[0:1], s[86:87]
	v_mad_u64_u32 v[0:1], s[16:17], v2, s89, v[0:1]
	v_mov_b32_e32 v41, v97
	v_lshl_add_u64 v[0:1], v[0:1], 0, v[40:41]
	v_add_co_u32_e32 v0, vcc, 0xfb00000, v0
	s_nop 1
	v_addc_co_u32_e32 v1, vcc, 0, v1, vcc
	global_load_dwordx4 v[28:31], v[0:1], off offset:1536 nt
.LBB0_335:
	s_or_b64 exec, exec, s[14:15]
	v_mov_b32_e32 v36, 0
	v_mov_b32_e32 v37, 0
	v_mov_b32_e32 v38, 0
	v_mov_b32_e32 v39, 0
	s_and_saveexec_b64 s[14:15], s[0:1]
	s_cbranch_execz .LBB0_337
	v_add3_u32 v2, v100, s25, -1
	v_mov_b64_e32 v[0:1], s[86:87]
	v_mad_u64_u32 v[0:1], s[0:1], v2, s89, v[0:1]
	v_mov_b32_e32 v41, v97
	v_lshl_add_u64 v[0:1], v[0:1], 0, v[40:41]
	v_add_co_u32_e32 v0, vcc, 0xfb00000, v0
	s_nop 1
	v_addc_co_u32_e32 v1, vcc, 0, v1, vcc
	global_load_dwordx4 v[36:39], v[0:1], off offset:1536 nt
; __device__ __forceinline__ void unpack8(const u32x4 w, float* f) { f[0] = bf_lo(w.x); f[1] = bf_hi(w.x); f[2] = bf_lo(w.y); f[3] = bf_hi(w.y); f[4] = bf_lo(w.z); f[5] = bf_hi(w.z); f[6] = bf_lo(w.w); f[7] = bf_hi(w.w); }
; __device__ __forceinline__ u32x4 pack8(const float* f) { u32x4 w; w.x = cvt_pk_bf16(f[0], f[1]); w.y = cvt_pk_bf16(f[2], f[3]); w.z = cvt_pk_bf16(f[4], f[5]); w.w = cvt_pk_bf16(f[6], f[7]); return w; }
; template <int W>
; __device__ __forceinline__ void pool_task_prompt(const Params& p, int l, int b, int c, int g, int rg, int ch, long row0) {
;     ...
;     float a[4][8], cur[4][8];
; #pragma unroll
;     for (int k = 0; k < 8; ++k) a[0][k] = 0.f;
; #pragma unroll
;     for (int i = 0; i < W; ++i) { float x[8]; unpack8(raw[i], x);
; #pragma unroll
;         for (int k = 0; k < 8; ++k) { a[0][k] += x[k]; if (i == W - 1) cur[0][k] = x[k]; } }
; #pragma unroll
;     for (int r = 1; r < 4; ++r) { float xin[8], xout[8]; unpack8(raw[W - 1 + r], xin); unpack8(raw[r - 1], xout);
; #pragma unroll
;         for (int k = 0; k < 8; ++k) { a[r][k] = a[r - 1][k] + (xin[k] - xout[k]); cur[r][k] = xin[k]; } }
; #pragma unroll
;     for (int r = 0; r < 4; ++r) {
;         const int t = t0 + r;
;         const float inv = 1.0f / (float)((t + 1) < W ? (t + 1) : W);
;         float d[8];
; #pragma unroll
;         for (int k = 0; k < 8; ++k) d[k] = a[r][k] * inv - cur[r][k];
;         *(u32x4*)(AD + (size_t)(row0 + tl0 + r) * DM + 512 + col) = pack8(d);
;         if (t >= SEQ - 15) { float* pd = p.out + O_PP + (((size_t)l * 2 + b) * 15 + (t - (SEQ - 15))) * 512 + col;
;             *(f32x4*)pd = (f32x4){cur[r][0], cur[r][1], cur[r][2], cur[r][3]}; *(f32x4*)(pd + 4) = (f32x4){cur[r][4], cur[r][5], cur[r][6], cur[r][7]}; }
.LBB0_337:
	s_or_b64 exec, exec, s[14:15]
	v_lshl_add_u64 v[0:1], s[86:87], 0, v[96:97]
	v_mov_b32_e32 v41, v97
	v_lshl_add_u64 v[0:1], v[0:1], 0, v[40:41]
	v_add_co_u32_e32 v2, vcc, 0xfb00000, v0
	s_waitcnt vmcnt(0) lgkmcnt(0)
	v_lshlrev_b32_e32 v61, 16, v12
	v_addc_co_u32_e32 v3, vcc, 0, v1, vcc
	v_add_co_u32_e32 v8, vcc, 0xfb02000, v0
	v_and_b32_e32 v62, 0xffff0000, v12
	s_nop 0
	v_addc_co_u32_e32 v9, vcc, 0, v1, vcc
	global_load_dwordx4 v[64:67], v[2:3], off offset:1536 nt
	global_load_dwordx4 v[24:27], v[8:9], off nt
	v_add_co_u32_e32 v2, vcc, 0xfb03000, v0
	v_lshlrev_b32_e32 v60, 16, v13
	s_nop 0
	v_addc_co_u32_e32 v3, vcc, 0, v1, vcc
	v_add_co_u32_e32 v0, vcc, 0xfb05000, v0
	v_and_b32_e32 v59, 0xffff0000, v13
	s_nop 0
	v_addc_co_u32_e32 v1, vcc, 0, v1, vcc
	global_load_dwordx4 v[8:11], v[2:3], off offset:2560 nt
	s_nop 0
	global_load_dwordx4 v[0:3], v[0:1], off offset:1024 nt
	v_lshlrev_b32_e32 v58, 16, v14
	v_and_b32_e32 v57, 0xffff0000, v14
	v_lshlrev_b32_e32 v56, 16, v15
	v_and_b32_e32 v55, 0xffff0000, v15
	v_add_f32_e32 v13, 0, v61
	v_add_f32_e32 v12, 0, v62
	v_lshlrev_b32_e32 v53, 16, v4
	v_and_b32_e32 v54, 0xffff0000, v4
	v_add_f32_e32 v14, 0, v60
	v_add_f32_e32 v15, 0, v59
	v_add_f32_e32 v42, 0, v58
	v_add_f32_e32 v43, 0, v57
	v_add_f32_e32 v44, 0, v56
	v_add_f32_e32 v45, 0, v55
	v_lshlrev_b32_e32 v52, 16, v5
	v_and_b32_e32 v51, 0xffff0000, v5
	v_lshlrev_b32_e32 v50, 16, v6
	v_and_b32_e32 v49, 0xffff0000, v6
	v_lshlrev_b32_e32 v48, 16, v7
	v_and_b32_e32 v47, 0xffff0000, v7
	v_add_f32_e32 v5, v13, v53
	v_add_f32_e32 v4, v12, v54
	v_lshlrev_b32_e32 v46, 16, v20
	v_and_b32_e32 v20, 0xffff0000, v20
	v_add_f32_e32 v6, v14, v52
	v_add_f32_e32 v7, v15, v51
	v_add_f32_e32 v12, v42, v50
	v_add_f32_e32 v13, v43, v49
	v_add_f32_e32 v14, v44, v48
	v_add_f32_e32 v15, v45, v47
	v_lshlrev_b32_e32 v45, 16, v21
	v_and_b32_e32 v44, 0xffff0000, v21
	v_lshlrev_b32_e32 v43, 16, v22
	v_and_b32_e32 v42, 0xffff0000, v22
	v_lshlrev_b32_e32 v22, 16, v23
	v_and_b32_e32 v21, 0xffff0000, v23
	v_add_f32_e32 v5, v5, v46
	v_add_f32_e32 v4, v4, v20
	v_lshlrev_b32_e32 v23, 16, v16
	v_and_b32_e32 v16, 0xffff0000, v16
	v_add_f32_e32 v5, v5, v23
	v_add_f32_e32 v4, v4, v16
	v_lshlrev_b32_e32 v16, 16, v32
	v_add_f32_e32 v12, v12, v43
	v_add_f32_e32 v15, v15, v21
	v_lshlrev_b32_e32 v68, 16, v18
	v_lshlrev_b32_e32 v69, 16, v19
	v_and_b32_e32 v19, 0xffff0000, v19
	v_add_f32_e32 v5, v5, v16
	v_and_b32_e32 v16, 0xffff0000, v32
	v_add_f32_e32 v12, v12, v68
	v_add_f32_e32 v15, v15, v19
	v_lshlrev_b32_e32 v19, 16, v34
	v_add_f32_e32 v4, v4, v16
	v_lshlrev_b32_e32 v16, 16, v28
	v_add_f32_e32 v12, v12, v19
	v_lshlrev_b32_e32 v19, 16, v30
	v_add_f32_e32 v5, v5, v16
	v_and_b32_e32 v16, 0xffff0000, v28
	v_add_f32_e32 v4, v4, v16
	v_add_f32_e32 v12, v12, v19
	v_lshlrev_b32_e32 v16, 16, v36
	v_lshlrev_b32_e32 v19, 16, v38
	v_add_f32_e32 v16, v5, v16
	v_add_f32_e32 v19, v12, v19
	v_add_f32_e32 v6, v6, v45
	v_add_f32_e32 v7, v7, v44
	s_waitcnt vmcnt(0) lgkmcnt(0)
	v_lshlrev_b32_e32 v12, 16, v64
	v_add_f32_e32 v32, v16, v12
	v_min_i32_e32 v16, 7, v101
	v_add_f32_e32 v13, v13, v42
	v_add_f32_e32 v14, v14, v22
	v_lshlrev_b32_e32 v63, 16, v17
	v_and_b32_e32 v17, 0xffff0000, v17
	v_and_b32_e32 v18, 0xffff0000, v18
	v_add_u32_e32 v16, 1, v16
	v_add_f32_e32 v6, v6, v63
	v_add_f32_e32 v7, v7, v17
	v_add_f32_e32 v13, v13, v18
	v_add_f32_e32 v14, v14, v69
	v_lshlrev_b32_e32 v17, 16, v33
	v_and_b32_e32 v18, 0xffff0000, v33
	v_lshlrev_b32_e32 v33, 16, v35
	v_cvt_f32_u32_e32 v16, v16
	v_and_b32_e32 v23, 0xffff0000, v34
	v_and_b32_e32 v34, 0xffff0000, v35
	v_add_f32_e32 v6, v6, v17
	v_add_f32_e32 v7, v7, v18
	v_add_f32_e32 v14, v14, v33
	v_lshlrev_b32_e32 v17, 16, v29
	v_and_b32_e32 v18, 0xffff0000, v29
	v_lshlrev_b32_e32 v29, 16, v31
	v_add_f32_e32 v13, v13, v23
	v_add_f32_e32 v15, v15, v34
	v_and_b32_e32 v23, 0xffff0000, v30
	v_and_b32_e32 v30, 0xffff0000, v31
	v_add_f32_e32 v6, v6, v17
	v_add_f32_e32 v14, v14, v29
	v_lshlrev_b32_e32 v17, 16, v37
	v_lshlrev_b32_e32 v28, 16, v39
	v_add_f32_e32 v7, v7, v18
	v_add_f32_e32 v15, v15, v30
	v_and_b32_e32 v18, 0xffff0000, v37
	v_and_b32_e32 v29, 0xffff0000, v39
	v_add_f32_e32 v17, v6, v17
	v_add_f32_e32 v28, v14, v28
	v_lshlrev_b32_e32 v14, 16, v65
	v_add_f32_e32 v18, v7, v18
	v_add_f32_e32 v35, v15, v29
	v_and_b32_e32 v15, 0xffff0000, v65
	v_add_f32_e32 v29, v17, v14
	v_div_scale_f32 v17, s[0:1], v16, v16, 1.0
	v_add_f32_e32 v34, v18, v15
	v_rcp_f32_e32 v18, v17
	v_and_b32_e32 v5, 0xffff0000, v36
	v_add_f32_e32 v30, v4, v5
	v_lshlrev_b32_e32 v4, 16, v66
	v_add_f32_e32 v13, v13, v23
	v_and_b32_e32 v23, 0xffff0000, v38
	v_add_f32_e32 v33, v19, v4
	v_fma_f32 v19, -v17, v18, 1.0
	v_add_f32_e32 v23, v13, v23
	v_and_b32_e32 v13, 0xffff0000, v64
	v_and_b32_e32 v5, 0xffff0000, v66
	v_and_b32_e32 v7, 0xffff0000, v67
	v_fmac_f32_e32 v18, v19, v18
	v_div_scale_f32 v19, vcc, 1.0, v16, 1.0
	v_add_f32_e32 v31, v30, v13
	v_add_f32_e32 v30, v23, v5
	v_add_f32_e32 v23, v35, v7
	v_mul_f32_e32 v35, v19, v18
	v_fma_f32 v36, -v17, v35, v19
	v_fmac_f32_e32 v35, v36, v18
	v_fma_f32 v17, -v17, v35, v19
	v_lshlrev_b32_e32 v6, 16, v67
	v_div_fmas_f32 v17, v17, v18, v35
	v_add_f32_e32 v28, v28, v6
	v_div_fixup_f32 v16, v17, v16, 1.0
	v_fma_f32 v17, v16, v32, -v12
	v_fma_f32 v18, v16, v31, -v13
	v_fma_f32 v19, v16, v29, -v14
	v_fma_f32 v35, v16, v34, -v15
	v_fma_f32 v38, v16, v33, -v4
	v_fma_f32 v39, v16, v30, -v5
	v_fma_f32 v63, v16, v28, -v6
	v_fma_f32 v16, v16, v23, -v7
	v_mov_b32_e32 v93, v97
	v_cvt_pk_bf16_f32 v36, v17, v18
	v_cvt_pk_bf16_f32 v37, v19, v35
	v_cvt_pk_bf16_f32 v38, v38, v39
	v_cvt_pk_bf16_f32 v39, v63, v16
	v_lshl_add_u64 v[16:17], s[86:87], 0, v[92:93]
	v_lshl_add_u64 v[18:19], v[16:17], 0, v[40:41]
	v_add_co_u32_e32 v64, vcc, 0x7900000, v18
	s_movk_i32 s0, 0x3ff0
	s_nop 0
	v_addc_co_u32_e32 v65, vcc, 0, v19, vcc
	v_cmp_lt_u32_e32 vcc, s0, v101
	global_store_dwordx4 v[64:65], v[36:39], off offset:1024
	s_and_saveexec_b64 s[0:1], vcc
	s_cbranch_execz .LBB0_339
	v_add_u32_e32 v35, s7, v101
	v_add_u32_e32 v36, 0xffffc00f, v35
	v_mov_b32_e32 v37, v97
	v_lshlrev_b64 v[36:37], 11, v[36:37]
	v_lshl_add_u64 v[36:37], v[88:89], 0, v[36:37]
	global_store_dwordx4 v[36:37], v[12:15], off
	global_store_dwordx4 v[36:37], v[4:7], off offset:16

; __device__ __forceinline__ void unpack8(const u32x4 w, float* f) { f[0] = bf_lo(w.x); f[1] = bf_hi(w.x); f[2] = bf_lo(w.y); f[3] = bf_hi(w.y); f[4] = bf_lo(w.z); f[5] = bf_hi(w.z); f[6] = bf_lo(w.w); f[7] = bf_hi(w.w); }
; __device__ __forceinline__ u32x4 pack8(const float* f) { u32x4 w; w.x = cvt_pk_bf16(f[0], f[1]); w.y = cvt_pk_bf16(f[2], f[3]); w.z = cvt_pk_bf16(f[4], f[5]); w.w = cvt_pk_bf16(f[6], f[7]); return w; }
; template <int W>
; __device__ __forceinline__ void pool_task_prompt(const Params& p, int l, int b, int c, int g, int rg, int ch, long row0) {
;     ...
;     u32x4 raw[W + 3];
; #pragma unroll
;     for (int i = 0; i < W + 3; ++i) { const int tt = t0 - (W - 1) + i; raw[i] = (u32x4){0u, 0u, 0u, 0u};
;         if (tt >= 0) raw[i] = *(const u32x4*)(P + (size_t)((long)b * SEQ + tt) * INW + 768 + col); }
;     float a[4][8], cur[4][8];
; #pragma unroll
;     for (int k = 0; k < 8; ++k) a[0][k] = 0.f;
; #pragma unroll
;     for (int i = 0; i < W; ++i) { float x[8]; unpack8(raw[i], x);
; #pragma unroll
;         for (int k = 0; k < 8; ++k) { a[0][k] += x[k]; if (i == W - 1) cur[0][k] = x[k]; } }
; #pragma unroll
;     for (int r = 1; r < 4; ++r) { float xin[8], xout[8]; unpack8(raw[W - 1 + r], xin); unpack8(raw[r - 1], xout);
; #pragma unroll
;         for (int k = 0; k < 8; ++k) { a[r][k] = a[r - 1][k] + (xin[k] - xout[k]); cur[r][k] = xin[k]; } }
; #pragma unroll
;     for (int r = 0; r < 4; ++r) {
;         const int t = t0 + r;
;         const float inv = 1.0f / (float)((t + 1) < W ? (t + 1) : W);
;         float d[8];
; #pragma unroll
;         for (int k = 0; k < 8; ++k) d[k] = a[r][k] * inv - cur[r][k];
;         *(u32x4*)(AD + (size_t)(row0 + tl0 + r) * DM + 512 + col) = pack8(d);
;         if (t >= SEQ - 15) { float* pd = p.out + O_PP + (((size_t)l * 2 + b) * 15 + (t - (SEQ - 15))) * 512 + col;
;             *(f32x4*)pd = (f32x4){cur[r][0], cur[r][1], cur[r][2], cur[r][3]}; *(f32x4*)(pd + 4) = (f32x4){cur[r][4], cur[r][5], cur[r][6], cur[r][7]}; }
.LBB0_345:
	s_or_saveexec_b64 s[8:9], s[8:9]
	v_mov_b64_e32 v[8:9], v[78:79]
	s_xor_b64 exec, exec, s[8:9]
	s_cbranch_execz .LBB0_359
	v_mov_b32_e32 v0, 0
	v_cmp_ne_u32_e64 s[0:1], 0, v101
	v_lshlrev_b32_e32 v20, 1, v80
	v_mov_b32_e32 v4, 0
	v_mov_b32_e32 v5, 0
	v_mov_b32_e32 v6, 0
	v_mov_b32_e32 v7, 0
	s_and_saveexec_b64 s[16:17], s[0:1]
	s_cbranch_execz .LBB0_348
	v_add3_u32 v1, v100, s25, -3
	v_mov_b64_e32 v[2:3], s[86:87]
	v_mad_u64_u32 v[2:3], s[40:41], v1, s89, v[2:3]
	v_mov_b32_e32 v21, v97
	v_lshl_add_u64 v[2:3], v[2:3], 0, v[20:21]
	v_add_co_u32_e32 v2, vcc, 0xfb00000, v2
	s_nop 1
	v_addc_co_u32_e32 v3, vcc, 0, v3, vcc
	global_load_dwordx4 v[4:7], v[2:3], off offset:1536 nt
.LBB0_348:
	s_or_b64 exec, exec, s[16:17]
	v_mov_b32_e32 v1, 0
	v_mov_b32_e32 v2, 0
	v_mov_b32_e32 v3, 0
	s_and_saveexec_b64 s[16:17], s[0:1]
	s_cbranch_execz .LBB0_350
	v_add3_u32 v2, v100, s25, -2
	v_mov_b64_e32 v[0:1], s[86:87]
	v_mad_u64_u32 v[0:1], s[40:41], v2, s89, v[0:1]
	v_mov_b32_e32 v21, v97
	v_lshl_add_u64 v[0:1], v[0:1], 0, v[20:21]
	v_add_co_u32_e32 v0, vcc, 0xfb00000, v0
	s_nop 1
	v_addc_co_u32_e32 v1, vcc, 0, v1, vcc
	global_load_dwordx4 v[0:3], v[0:1], off offset:1536 nt
.LBB0_350:
	s_or_b64 exec, exec, s[16:17]
	v_mov_b32_e32 v8, 0
	v_mov_b32_e32 v9, 0
	v_mov_b32_e32 v10, 0
	v_mov_b32_e32 v11, 0
	s_and_saveexec_b64 s[16:17], s[0:1]
	s_cbranch_execz .LBB0_352
	v_add3_u32 v10, v100, s25, -1
	v_mov_b64_e32 v[8:9], s[86:87]
	v_mad_u64_u32 v[8:9], s[0:1], v10, s89, v[8:9]
	v_mov_b32_e32 v21, v97
	v_lshl_add_u64 v[8:9], v[8:9], 0, v[20:21]
	v_add_co_u32_e32 v8, vcc, 0xfb00000, v8
	s_nop 1
	v_addc_co_u32_e32 v9, vcc, 0, v9, vcc
	global_load_dwordx4 v[8:11], v[8:9], off offset:1536 nt
.LBB0_352:
	s_or_b64 exec, exec, s[16:17]
	v_lshl_add_u64 v[12:13], s[86:87], 0, v[96:97]
	v_mov_b32_e32 v21, v97
	v_lshl_add_u64 v[16:17], v[12:13], 0, v[20:21]
	v_add_co_u32_e32 v12, vcc, 0xfb00000, v16
	s_waitcnt vmcnt(0) lgkmcnt(0)
	v_lshlrev_b32_e32 v40, 16, v0
	v_addc_co_u32_e32 v13, vcc, 0, v17, vcc
	global_load_dwordx4 v[12:15], v[12:13], off offset:1536 nt
	v_and_b32_e32 v41, 0xffff0000, v0
	v_add_co_u32_e32 v0, vcc, 0xfb02000, v16
	v_lshlrev_b32_e32 v39, 16, v1
	v_and_b32_e32 v38, 0xffff0000, v1
	v_addc_co_u32_e32 v1, vcc, 0, v17, vcc
	v_lshlrev_b32_e32 v37, 16, v2
	v_and_b32_e32 v36, 0xffff0000, v2
	v_add_co_u32_e32 v2, vcc, 0xfb03000, v16
	v_lshlrev_b32_e32 v35, 16, v3
	v_and_b32_e32 v34, 0xffff0000, v3
	v_addc_co_u32_e32 v3, vcc, 0, v17, vcc
	v_lshlrev_b32_e32 v32, 16, v8
	v_lshlrev_b32_e32 v31, 16, v9
	v_and_b32_e32 v30, 0xffff0000, v9
	v_lshlrev_b32_e32 v29, 16, v10
	v_and_b32_e32 v28, 0xffff0000, v10
	v_lshlrev_b32_e32 v27, 16, v11
	v_and_b32_e32 v26, 0xffff0000, v11
	v_and_b32_e32 v33, 0xffff0000, v8
	global_load_dwordx4 v[8:11], v[0:1], off nt
	v_add_co_u32_e32 v0, vcc, 0xfb05000, v16
	v_lshlrev_b32_e32 v48, 16, v4
	s_nop 0
	v_addc_co_u32_e32 v1, vcc, 0, v17, vcc
	v_lshlrev_b32_e32 v47, 16, v5
	v_and_b32_e32 v46, 0xffff0000, v5
	v_lshlrev_b32_e32 v45, 16, v6
	v_and_b32_e32 v44, 0xffff0000, v6
	v_lshlrev_b32_e32 v43, 16, v7
	v_and_b32_e32 v42, 0xffff0000, v7
	v_and_b32_e32 v49, 0xffff0000, v4
	global_load_dwordx4 v[4:7], v[2:3], off offset:2560 nt
	s_nop 0
	global_load_dwordx4 v[0:3], v[0:1], off offset:1024 nt
	v_add_f32_e32 v16, 0, v48
	v_add_f32_e32 v18, 0, v47
	v_add_f32_e32 v16, v16, v40
	v_add_f32_e32 v18, v18, v39
	v_add_f32_e32 v50, v16, v32
	v_add_f32_e32 v53, v18, v31
	v_add_f32_e32 v17, 0, v49
	v_add_f32_e32 v22, 0, v45
	v_add_f32_e32 v17, v17, v41
	v_add_f32_e32 v22, v22, v37
	v_add_f32_e32 v51, v17, v33
	v_add_f32_e32 v22, v22, v29
	v_add_f32_e32 v19, 0, v46
	v_add_f32_e32 v23, 0, v44
	v_add_f32_e32 v19, v19, v38
	v_add_f32_e32 v23, v23, v36
	v_add_f32_e32 v24, 0, v43
	v_add_f32_e32 v54, v19, v30
	v_add_f32_e32 v23, v23, v28
	v_add_f32_e32 v25, 0, v42
	v_add_f32_e32 v24, v24, v35
	v_add_f32_e32 v25, v25, v34
	v_add_f32_e32 v24, v24, v27
	v_add_f32_e32 v25, v25, v26
	v_mov_b32_e32 v93, v97
	s_waitcnt vmcnt(0) lgkmcnt(0)
	v_lshlrev_b32_e32 v16, 16, v12
	v_lshlrev_b32_e32 v18, 16, v13
	v_add_f32_e32 v52, v50, v16
	v_add_f32_e32 v50, v53, v18
	v_min_i32_e32 v53, 3, v101
	v_add_u32_e32 v53, 1, v53
	v_cvt_f32_u32_e32 v58, v53
	v_and_b32_e32 v17, 0xffff0000, v12
	v_lshlrev_b32_e32 v12, 16, v14
	v_add_f32_e32 v56, v22, v12
	v_div_scale_f32 v22, s[0:1], v58, v58, 1.0
	v_rcp_f32_e32 v59, v22
	v_and_b32_e32 v19, 0xffff0000, v13
	v_and_b32_e32 v13, 0xffff0000, v14
	v_add_f32_e32 v55, v23, v13
	v_fma_f32 v23, -v22, v59, 1.0
	v_lshlrev_b32_e32 v14, 16, v15
	v_fmac_f32_e32 v59, v23, v59
	v_div_scale_f32 v23, vcc, 1.0, v58, 1.0
	v_and_b32_e32 v15, 0xffff0000, v15
	v_add_f32_e32 v57, v54, v19
	v_add_f32_e32 v54, v24, v14
	v_mul_f32_e32 v24, v23, v59
	v_add_f32_e32 v53, v25, v15
	v_fma_f32 v25, -v22, v24, v23
	v_fmac_f32_e32 v24, v25, v59
	v_fma_f32 v22, -v22, v24, v23
	v_div_fmas_f32 v22, v22, v59, v24
	v_add_f32_e32 v51, v51, v17
	v_div_fixup_f32 v22, v22, v58, 1.0
	v_fma_f32 v23, v22, v52, -v16
	v_fma_f32 v24, v22, v51, -v17
	v_fma_f32 v25, v22, v50, -v18
	v_fma_f32 v59, v22, v57, -v19
	v_fma_f32 v60, v22, v56, -v12
	v_fma_f32 v61, v22, v55, -v13
	v_fma_f32 v62, v22, v54, -v14
	v_fma_f32 v22, v22, v53, -v15
	v_cvt_pk_bf16_f32 v58, v23, v24
	v_cvt_pk_bf16_f32 v59, v25, v59
	v_cvt_pk_bf16_f32 v60, v60, v61
	v_cvt_pk_bf16_f32 v61, v62, v22
	v_lshl_add_u64 v[22:23], s[86:87], 0, v[92:93]
	v_lshl_add_u64 v[24:25], v[22:23], 0, v[20:21]
	v_add_co_u32_e32 v62, vcc, 0x7900000, v24
	s_movk_i32 s0, 0x3ff0
	s_nop 0
	v_addc_co_u32_e32 v63, vcc, 0, v25, vcc
	v_cmp_lt_u32_e32 vcc, s0, v101
	global_store_dwordx4 v[62:63], v[58:61], off offset:1024
	s_and_saveexec_b64 s[0:1], vcc
	s_cbranch_execz .LBB0_354
	v_add_u32_e32 v21, s7, v101
	v_add_u32_e32 v58, 0xffffc00f, v21
	v_mov_b32_e32 v59, v97
	v_lshlrev_b64 v[58:59], 11, v[58:59]
	v_lshl_add_u64 v[58:59], v[90:91], 0, v[58:59]
	global_store_dwordx4 v[58:59], v[16:19], off
	global_store_dwordx4 v[58:59], v[12:15], off offset:16

; template <int W>
; __device__ __forceinline__ void pool_task_prompt(const Params& p, int l, int b, int c, int g, int rg, int ch, long row0) {
;     ...
;     u32x4 raw[W + 3];
; #pragma unroll
;     for (int i = 0; i < W + 3; ++i) { const int tt = t0 - (W - 1) + i; raw[i] = (u32x4){0u, 0u, 0u, 0u};
;         if (tt >= 0) raw[i] = *(const u32x4*)(P + (size_t)((long)b * SEQ + tt) * INW + 768 + col); }
.LBB0_361:
	v_cmp_lt_u32_e32 vcc, 14, v101
	v_mov_b32_e32 v0, 0
	v_mov_b32_e32 v4, 0
	v_mov_b32_e32 v5, 0
	v_mov_b32_e32 v6, 0
	v_mov_b32_e32 v7, 0
	s_and_saveexec_b64 s[0:1], vcc
	s_cbranch_execz .LBB0_363
	v_add3_u32 v1, v100, s25, -15
	v_mov_b64_e32 v[2:3], s[86:87]
	v_mad_u64_u32 v[2:3], s[12:13], v1, s89, v[2:3]
	v_lshl_add_u64 v[2:3], v[82:83], 1, v[2:3]
	v_add_co_u32_e32 v2, vcc, 0xfb00000, v2
	s_nop 1
	v_addc_co_u32_e32 v3, vcc, 0, v3, vcc
	global_load_dwordx4 v[4:7], v[2:3], off offset:1536 nt
.LBB0_363:
	s_or_b64 exec, exec, s[0:1]
	v_cmp_lt_u32_e32 vcc, 13, v101
	v_mov_b32_e32 v1, 0
	v_mov_b32_e32 v2, 0
	v_mov_b32_e32 v3, 0
	s_and_saveexec_b64 s[0:1], vcc
	s_cbranch_execz .LBB0_365
	v_add3_u32 v2, v100, s25, -14
	v_mov_b64_e32 v[0:1], s[86:87]
	v_mad_u64_u32 v[0:1], s[12:13], v2, s89, v[0:1]
	v_lshl_add_u64 v[0:1], v[82:83], 1, v[0:1]
	v_add_co_u32_e32 v0, vcc, 0xfb00000, v0
	s_nop 1
	v_addc_co_u32_e32 v1, vcc, 0, v1, vcc
	global_load_dwordx4 v[0:3], v[0:1], off offset:1536 nt
.LBB0_365:
	s_or_b64 exec, exec, s[0:1]
	v_cmp_lt_u32_e32 vcc, 12, v101
	v_mov_b32_e32 v8, 0
	v_mov_b32_e32 v12, 0
	v_mov_b32_e32 v13, 0
	v_mov_b32_e32 v14, 0
	v_mov_b32_e32 v15, 0
	s_and_saveexec_b64 s[0:1], vcc
	s_cbranch_execz .LBB0_367
	v_add3_u32 v9, v100, s25, -13
	v_mov_b64_e32 v[10:11], s[86:87]
	v_mad_u64_u32 v[10:11], s[12:13], v9, s89, v[10:11]
	v_lshl_add_u64 v[10:11], v[82:83], 1, v[10:11]
	v_add_co_u32_e32 v10, vcc, 0xfb00000, v10
	s_nop 1
	v_addc_co_u32_e32 v11, vcc, 0, v11, vcc
	global_load_dwordx4 v[12:15], v[10:11], off offset:1536 nt
.LBB0_367:
	s_or_b64 exec, exec, s[0:1]
	v_cmp_lt_u32_e32 vcc, 11, v101
	v_mov_b32_e32 v9, 0
	v_mov_b32_e32 v10, 0
	v_mov_b32_e32 v11, 0
	s_and_saveexec_b64 s[0:1], vcc
	s_cbranch_execz .LBB0_369
	v_add3_u32 v10, v100, s25, -12
	v_mov_b64_e32 v[8:9], s[86:87]
	v_mad_u64_u32 v[8:9], s[12:13], v10, s89, v[8:9]
	v_lshl_add_u64 v[8:9], v[82:83], 1, v[8:9]
	v_add_co_u32_e32 v8, vcc, 0xfb00000, v8
	s_nop 1
	v_addc_co_u32_e32 v9, vcc, 0, v9, vcc
	global_load_dwordx4 v[8:11], v[8:9], off offset:1536 nt
.LBB0_369:
	s_or_b64 exec, exec, s[0:1]
	v_cmp_lt_u32_e32 vcc, 10, v101
	v_mov_b32_e32 v20, 0
	v_mov_b32_e32 v24, 0
	v_mov_b32_e32 v25, 0
	v_mov_b32_e32 v26, 0
	v_mov_b32_e32 v27, 0
	s_and_saveexec_b64 s[0:1], vcc
	s_cbranch_execz .LBB0_371
	v_add3_u32 v18, v100, s25, -11
	v_mov_b64_e32 v[16:17], s[86:87]
	v_mad_u64_u32 v[16:17], s[12:13], v18, s89, v[16:17]
	v_lshl_add_u64 v[16:17], v[82:83], 1, v[16:17]
	v_add_co_u32_e32 v16, vcc, 0xfb00000, v16
	s_nop 1
	v_addc_co_u32_e32 v17, vcc, 0, v17, vcc
	global_load_dwordx4 v[24:27], v[16:17], off offset:1536 nt
.LBB0_371:
	s_or_b64 exec, exec, s[0:1]
	v_cmp_lt_u32_e32 vcc, 9, v101
	v_mov_b32_e32 v21, 0
	v_mov_b32_e32 v22, 0
	v_mov_b32_e32 v23, 0
	s_and_saveexec_b64 s[0:1], vcc
	s_cbranch_execz .LBB0_373
	v_add3_u32 v18, v100, s25, -10
	v_mov_b64_e32 v[16:17], s[86:87]
	v_mad_u64_u32 v[16:17], s[12:13], v18, s89, v[16:17]
	v_lshl_add_u64 v[16:17], v[82:83], 1, v[16:17]
	v_add_co_u32_e32 v16, vcc, 0xfb00000, v16
	s_nop 1
	v_addc_co_u32_e32 v17, vcc, 0, v17, vcc
	global_load_dwordx4 v[20:23], v[16:17], off offset:1536 nt
.LBB0_373:
	s_or_b64 exec, exec, s[0:1]
	v_cmp_lt_u32_e32 vcc, 8, v101
	v_mov_b32_e32 v28, 0
	v_mov_b32_e32 v32, 0
	v_mov_b32_e32 v33, 0
	v_mov_b32_e32 v34, 0
	v_mov_b32_e32 v35, 0
	s_and_saveexec_b64 s[0:1], vcc
	s_cbranch_execz .LBB0_375
	v_add3_u32 v18, v100, s25, -9
	v_mov_b64_e32 v[16:17], s[86:87]
	v_mad_u64_u32 v[16:17], s[12:13], v18, s89, v[16:17]
	v_lshl_add_u64 v[16:17], v[82:83], 1, v[16:17]
	v_add_co_u32_e32 v16, vcc, 0xfb00000, v16
	s_nop 1
	v_addc_co_u32_e32 v17, vcc, 0, v17, vcc
	global_load_dwordx4 v[32:35], v[16:17], off offset:1536 nt
.LBB0_375:
	s_or_b64 exec, exec, s[0:1]
	v_cmp_lt_u32_e32 vcc, 7, v101
	v_mov_b32_e32 v29, 0
	v_mov_b32_e32 v30, 0
	v_mov_b32_e32 v31, 0
	s_and_saveexec_b64 s[0:1], vcc
	s_cbranch_execz .LBB0_377
	v_add3_u32 v18, v100, s25, -8
	v_mov_b64_e32 v[16:17], s[86:87]
	v_mad_u64_u32 v[16:17], s[12:13], v18, s89, v[16:17]
	v_lshl_add_u64 v[16:17], v[82:83], 1, v[16:17]
	v_add_co_u32_e32 v16, vcc, 0xfb00000, v16
	s_nop 1
	v_addc_co_u32_e32 v17, vcc, 0, v17, vcc
	global_load_dwordx4 v[28:31], v[16:17], off offset:1536 nt
.LBB0_377:
	s_or_b64 exec, exec, s[0:1]
	v_cmp_lt_u32_e32 vcc, 6, v101
	v_mov_b32_e32 v40, 0
	v_mov_b32_e32 v44, 0
	v_mov_b32_e32 v45, 0
	v_mov_b32_e32 v46, 0
	v_mov_b32_e32 v47, 0
	s_and_saveexec_b64 s[0:1], vcc
	s_cbranch_execz .LBB0_379
	v_add3_u32 v18, v100, s25, -7
	v_mov_b64_e32 v[16:17], s[86:87]
	v_mad_u64_u32 v[16:17], s[12:13], v18, s89, v[16:17]
	v_lshl_add_u64 v[16:17], v[82:83], 1, v[16:17]
	v_add_co_u32_e32 v16, vcc, 0xfb00000, v16
	s_nop 1
	v_addc_co_u32_e32 v17, vcc, 0, v17, vcc
	global_load_dwordx4 v[44:47], v[16:17], off offset:1536 nt
.LBB0_379:
	s_or_b64 exec, exec, s[0:1]
	v_cmp_lt_u32_e32 vcc, 5, v101
	v_mov_b32_e32 v41, 0
	v_mov_b32_e32 v42, 0
	v_mov_b32_e32 v43, 0
	s_and_saveexec_b64 s[0:1], vcc
	s_cbranch_execz .LBB0_381
	v_add3_u32 v18, v100, s25, -6
	v_mov_b64_e32 v[16:17], s[86:87]
	v_mad_u64_u32 v[16:17], s[12:13], v18, s89, v[16:17]
	v_lshl_add_u64 v[16:17], v[82:83], 1, v[16:17]
	v_add_co_u32_e32 v16, vcc, 0xfb00000, v16
	s_nop 1
	v_addc_co_u32_e32 v17, vcc, 0, v17, vcc
	global_load_dwordx4 v[40:43], v[16:17], off offset:1536 nt
.LBB0_381:
	s_or_b64 exec, exec, s[0:1]
	v_cmp_lt_u32_e32 vcc, 4, v101
	v_mov_b32_e32 v48, 0
	v_mov_b32_e32 v52, 0
	v_mov_b32_e32 v53, 0
	v_mov_b32_e32 v54, 0
	v_mov_b32_e32 v55, 0
	s_and_saveexec_b64 s[0:1], vcc
	s_cbranch_execz .LBB0_383
	v_add3_u32 v18, v100, s25, -5
	v_mov_b64_e32 v[16:17], s[86:87]
	v_mad_u64_u32 v[16:17], s[12:13], v18, s89, v[16:17]
	v_lshl_add_u64 v[16:17], v[82:83], 1, v[16:17]
	v_add_co_u32_e32 v16, vcc, 0xfb00000, v16
	s_nop 1
	v_addc_co_u32_e32 v17, vcc, 0, v17, vcc
	global_load_dwordx4 v[52:55], v[16:17], off offset:1536 nt
; __device__ __forceinline__ void unpack8(const u32x4 w, float* f) { f[0] = bf_lo(w.x); f[1] = bf_hi(w.x); f[2] = bf_lo(w.y); f[3] = bf_hi(w.y); f[4] = bf_lo(w.z); f[5] = bf_hi(w.z); f[6] = bf_lo(w.w); f[7] = bf_hi(w.w); }
; template <int W>
; __device__ __forceinline__ void pool_task_prompt(const Params& p, int l, int b, int c, int g, int rg, int ch, long row0) {
;     ...
;     u32x4 raw[W + 3];
; #pragma unroll
;     for (int i = 0; i < W + 3; ++i) { const int tt = t0 - (W - 1) + i; raw[i] = (u32x4){0u, 0u, 0u, 0u};
;         if (tt >= 0) raw[i] = *(const u32x4*)(P + (size_t)((long)b * SEQ + tt) * INW + 768 + col); }
;     float a[4][8], cur[4][8];
; #pragma unroll
;     for (int k = 0; k < 8; ++k) a[0][k] = 0.f;
; #pragma unroll
;     for (int i = 0; i < W; ++i) { float x[8]; unpack8(raw[i], x);
; #pragma unroll
;         for (int k = 0; k < 8; ++k) { a[0][k] += x[k]; if (i == W - 1) cur[0][k] = x[k]; } }
; #pragma unroll
;     for (int r = 1; r < 4; ++r) { float xin[8], xout[8]; unpack8(raw[W - 1 + r], xin); unpack8(raw[r - 1], xout);
; #pragma unroll
;         for (int k = 0; k < 8; ++k) { a[r][k] = a[r - 1][k] + (xin[k] - xout[k]); cur[r][k] = xin[k]; } }
.LBB0_383:
	s_or_b64 exec, exec, s[0:1]
	v_cmp_ne_u32_e64 s[0:1], 0, v101
	v_mov_b32_e32 v49, 0
	v_mov_b32_e32 v50, 0
	v_mov_b32_e32 v51, 0
	s_and_saveexec_b64 s[12:13], s[0:1]
	s_cbranch_execz .LBB0_385
	v_add3_u32 v18, v100, s25, -4
	v_mov_b64_e32 v[16:17], s[86:87]
	v_mad_u64_u32 v[16:17], s[14:15], v18, s89, v[16:17]
	v_lshl_add_u64 v[16:17], v[82:83], 1, v[16:17]
	v_add_co_u32_e32 v16, vcc, 0xfb00000, v16
	s_nop 1
	v_addc_co_u32_e32 v17, vcc, 0, v17, vcc
	global_load_dwordx4 v[48:51], v[16:17], off offset:1536 nt
.LBB0_385:
	s_or_b64 exec, exec, s[12:13]
	v_mov_b32_e32 v60, 0
	v_mov_b32_e32 v64, 0
	v_mov_b32_e32 v65, 0
	v_mov_b32_e32 v66, 0
	v_mov_b32_e32 v67, 0
	s_and_saveexec_b64 s[12:13], s[0:1]
	s_cbranch_execz .LBB0_387
	v_add3_u32 v18, v100, s25, -3
	v_mov_b64_e32 v[16:17], s[86:87]
	v_mad_u64_u32 v[16:17], s[14:15], v18, s89, v[16:17]
	v_lshl_add_u64 v[16:17], v[82:83], 1, v[16:17]
	v_add_co_u32_e32 v16, vcc, 0xfb00000, v16
	s_nop 1
	v_addc_co_u32_e32 v17, vcc, 0, v17, vcc
	global_load_dwordx4 v[64:67], v[16:17], off offset:1536 nt
.LBB0_387:
	s_or_b64 exec, exec, s[12:13]
	v_mov_b32_e32 v61, 0
	v_mov_b32_e32 v62, 0
	v_mov_b32_e32 v63, 0
	s_and_saveexec_b64 s[12:13], s[0:1]
	s_cbranch_execz .LBB0_389
	v_add3_u32 v18, v100, s25, -2
	v_mov_b64_e32 v[16:17], s[86:87]
	v_mad_u64_u32 v[16:17], s[14:15], v18, s89, v[16:17]
	v_lshl_add_u64 v[16:17], v[82:83], 1, v[16:17]
	v_add_co_u32_e32 v16, vcc, 0xfb00000, v16
	s_nop 1
	v_addc_co_u32_e32 v17, vcc, 0, v17, vcc
	global_load_dwordx4 v[60:63], v[16:17], off offset:1536 nt
.LBB0_389:
	s_or_b64 exec, exec, s[12:13]
	v_mov_b32_e32 v68, 0
	v_mov_b32_e32 v69, 0
	v_mov_b32_e32 v70, 0
	v_mov_b32_e32 v71, 0
	s_and_saveexec_b64 s[12:13], s[0:1]
	s_cbranch_execz .LBB0_391
	v_add3_u32 v18, v100, s25, -1
	v_mov_b64_e32 v[16:17], s[86:87]
	v_mad_u64_u32 v[16:17], s[0:1], v18, s89, v[16:17]
	v_lshl_add_u64 v[16:17], v[82:83], 1, v[16:17]
	v_add_co_u32_e32 v16, vcc, 0xfb00000, v16
	s_nop 1
	v_addc_co_u32_e32 v17, vcc, 0, v17, vcc
	global_load_dwordx4 v[68:71], v[16:17], off offset:1536 nt
.LBB0_391:
	s_or_b64 exec, exec, s[12:13]
	v_lshl_add_u64 v[16:17], s[86:87], 0, v[96:97]
	v_lshlrev_b64 v[94:95], 1, v[82:83]
	v_lshl_add_u64 v[16:17], v[16:17], 0, v[94:95]
	v_add_co_u32_e32 v18, vcc, 0xfb00000, v16
	s_waitcnt vmcnt(0) lgkmcnt(0)
	v_lshlrev_b32_e32 v121, 16, v4
	v_addc_co_u32_e32 v19, vcc, 0, v17, vcc
	v_add_co_u32_e32 v36, vcc, 0xfb02000, v16
	v_and_b32_e32 v122, 0xffff0000, v4
	s_nop 0
	v_addc_co_u32_e32 v37, vcc, 0, v17, vcc
	global_load_dwordx4 v[72:75], v[18:19], off offset:1536 nt
	global_load_dwordx4 v[56:59], v[36:37], off nt
	v_add_co_u32_e32 v18, vcc, 0xfb03000, v16
	v_lshlrev_b32_e32 v120, 16, v5
	s_nop 0
	v_addc_co_u32_e32 v19, vcc, 0, v17, vcc
	v_add_co_u32_e32 v16, vcc, 0xfb05000, v16
	v_and_b32_e32 v119, 0xffff0000, v5
	s_nop 0
	v_addc_co_u32_e32 v17, vcc, 0, v17, vcc
	global_load_dwordx4 v[36:39], v[18:19], off offset:2560 nt
	s_nop 0
	global_load_dwordx4 v[16:19], v[16:17], off offset:1024 nt
	v_and_b32_e32 v117, 0xffff0000, v6
	v_lshlrev_b32_e32 v116, 16, v7
	v_and_b32_e32 v115, 0xffff0000, v7
	v_add_f32_e32 v5, 0, v121
	v_add_f32_e32 v4, 0, v122
	v_lshlrev_b32_e32 v113, 16, v0
	v_and_b32_e32 v114, 0xffff0000, v0
	v_lshlrev_b32_e32 v118, 16, v6
	v_add_f32_e32 v6, 0, v120
	v_add_f32_e32 v7, 0, v119
	v_add_f32_e32 v102, 0, v117
	v_add_f32_e32 v103, 0, v116
	v_add_f32_e32 v104, 0, v115
	v_lshlrev_b32_e32 v112, 16, v1
	v_and_b32_e32 v111, 0xffff0000, v1
	v_and_b32_e32 v109, 0xffff0000, v2
	v_lshlrev_b32_e32 v108, 16, v3
	v_and_b32_e32 v107, 0xffff0000, v3
	v_add_f32_e32 v1, v5, v113
	v_add_f32_e32 v0, v4, v114
	v_lshlrev_b32_e32 v106, 16, v12
	v_and_b32_e32 v12, 0xffff0000, v12
	v_lshlrev_b32_e32 v110, 16, v2
	v_add_f32_e32 v2, v6, v112
	v_add_f32_e32 v3, v7, v111
	v_add_f32_e32 v5, v102, v109
	v_add_f32_e32 v6, v103, v108
	v_add_f32_e32 v7, v104, v107
	v_lshlrev_b32_e32 v105, 16, v13
	v_and_b32_e32 v104, 0xffff0000, v13
	v_lshlrev_b32_e32 v103, 16, v14
	v_and_b32_e32 v102, 0xffff0000, v14
	v_lshlrev_b32_e32 v14, 16, v15
	v_and_b32_e32 v13, 0xffff0000, v15
	v_add_f32_e32 v1, v1, v106
	v_add_f32_e32 v0, v0, v12
	v_lshlrev_b32_e32 v15, 16, v8
	v_and_b32_e32 v8, 0xffff0000, v8
	v_add_f32_e32 v1, v1, v15
	v_add_f32_e32 v0, v0, v8
	v_lshlrev_b32_e32 v8, 16, v24
	v_add_f32_e32 v1, v1, v8
	v_and_b32_e32 v8, 0xffff0000, v24
	v_add_f32_e32 v0, v0, v8
	v_lshlrev_b32_e32 v8, 16, v20
	v_add_f32_e32 v1, v1, v8
	v_and_b32_e32 v8, 0xffff0000, v20
	v_add_f32_e32 v0, v0, v8
	v_lshlrev_b32_e32 v8, 16, v32
	v_add_f32_e32 v1, v1, v8
	v_and_b32_e32 v8, 0xffff0000, v32
	v_add_f32_e32 v0, v0, v8
	v_lshlrev_b32_e32 v8, 16, v28
	v_add_f32_e32 v93, 0, v118
	v_add_f32_e32 v1, v1, v8
	v_and_b32_e32 v8, 0xffff0000, v28
	v_add_f32_e32 v4, v93, v110
	v_add_f32_e32 v0, v0, v8
	v_lshlrev_b32_e32 v8, 16, v44
	v_add_f32_e32 v4, v4, v103
	v_add_f32_e32 v7, v7, v13
	v_lshlrev_b32_e32 v123, 16, v10
	v_lshlrev_b32_e32 v124, 16, v11
	v_and_b32_e32 v11, 0xffff0000, v11
	v_add_f32_e32 v1, v1, v8
	v_and_b32_e32 v8, 0xffff0000, v44
	v_add_f32_e32 v5, v5, v102
	v_and_b32_e32 v10, 0xffff0000, v10
	v_add_f32_e32 v4, v4, v123
	v_add_f32_e32 v7, v7, v11
	v_lshlrev_b32_e32 v11, 16, v26
	v_add_f32_e32 v0, v0, v8
	v_lshlrev_b32_e32 v8, 16, v40
	v_add_f32_e32 v5, v5, v10
	v_and_b32_e32 v15, 0xffff0000, v26
	v_add_f32_e32 v4, v4, v11
	v_lshlrev_b32_e32 v11, 16, v22
	v_add_f32_e32 v1, v1, v8
	v_and_b32_e32 v8, 0xffff0000, v40
	v_add_f32_e32 v5, v5, v15
	v_and_b32_e32 v15, 0xffff0000, v22
	v_add_f32_e32 v4, v4, v11
	v_lshlrev_b32_e32 v11, 16, v34
	v_add_f32_e32 v0, v0, v8
	v_lshlrev_b32_e32 v8, 16, v52
	v_add_f32_e32 v5, v5, v15
; __device__ __forceinline__ void unpack8(const u32x4 w, float* f) { f[0] = bf_lo(w.x); f[1] = bf_hi(w.x); f[2] = bf_lo(w.y); f[3] = bf_hi(w.y); f[4] = bf_lo(w.z); f[5] = bf_hi(w.z); f[6] = bf_lo(w.w); f[7] = bf_hi(w.w); }
; __device__ __forceinline__ u32x4 pack8(const float* f) { u32x4 w; w.x = cvt_pk_bf16(f[0], f[1]); w.y = cvt_pk_bf16(f[2], f[3]); w.z = cvt_pk_bf16(f[4], f[5]); w.w = cvt_pk_bf16(f[6], f[7]); return w; }
; template <int W>
; __device__ __forceinline__ void pool_task_prompt(const Params& p, int l, int b, int c, int g, int rg, int ch, long row0) {
;     ...
;     for (int i = 0; i < W; ++i) { float x[8]; unpack8(raw[i], x);
; #pragma unroll
;         for (int k = 0; k < 8; ++k) { a[0][k] += x[k]; if (i == W - 1) cur[0][k] = x[k]; } }
; #pragma unroll
;     for (int r = 1; r < 4; ++r) { float xin[8], xout[8]; unpack8(raw[W - 1 + r], xin); unpack8(raw[r - 1], xout);
; #pragma unroll
;         for (int k = 0; k < 8; ++k) { a[r][k] = a[r - 1][k] + (xin[k] - xout[k]); cur[r][k] = xin[k]; } }
; #pragma unroll
;     for (int r = 0; r < 4; ++r) {
;         const int t = t0 + r;
;         const float inv = 1.0f / (float)((t + 1) < W ? (t + 1) : W);
;         float d[8];
; #pragma unroll
;         for (int k = 0; k < 8; ++k) d[k] = a[r][k] * inv - cur[r][k];
;         *(u32x4*)(AD + (size_t)(row0 + tl0 + r) * DM + 512 + col) = pack8(d);
;         if (t >= SEQ - 15) { float* pd = p.out + O_PP + (((size_t)l * 2 + b) * 15 + (t - (SEQ - 15))) * 512 + col;
;             *(f32x4*)pd = (f32x4){cur[r][0], cur[r][1], cur[r][2], cur[r][3]}; *(f32x4*)(pd + 4) = (f32x4){cur[r][4], cur[r][5], cur[r][6], cur[r][7]}; }
	v_and_b32_e32 v15, 0xffff0000, v34
	v_add_f32_e32 v4, v4, v11
	v_lshlrev_b32_e32 v11, 16, v30
	v_add_f32_e32 v1, v1, v8
	v_and_b32_e32 v8, 0xffff0000, v52
	v_add_f32_e32 v5, v5, v15
	v_and_b32_e32 v15, 0xffff0000, v30
	v_add_f32_e32 v4, v4, v11
	v_lshlrev_b32_e32 v11, 16, v46
	v_add_f32_e32 v0, v0, v8
	v_lshlrev_b32_e32 v8, 16, v48
	v_add_f32_e32 v2, v2, v105
	v_add_f32_e32 v3, v3, v104
	v_add_f32_e32 v6, v6, v14
	v_lshlrev_b32_e32 v93, 16, v9
	v_and_b32_e32 v9, 0xffff0000, v9
	v_add_f32_e32 v5, v5, v15
	v_and_b32_e32 v15, 0xffff0000, v46
	v_add_f32_e32 v4, v4, v11
	v_lshlrev_b32_e32 v11, 16, v42
	v_add_f32_e32 v1, v1, v8
	v_and_b32_e32 v8, 0xffff0000, v48
	v_add_f32_e32 v2, v2, v93
	v_add_f32_e32 v3, v3, v9
	v_add_f32_e32 v6, v6, v124
	v_lshlrev_b32_e32 v9, 16, v25
	v_and_b32_e32 v10, 0xffff0000, v25
	v_lshlrev_b32_e32 v25, 16, v27
	v_add_f32_e32 v5, v5, v15
	v_and_b32_e32 v15, 0xffff0000, v42
	v_add_f32_e32 v4, v4, v11
	v_lshlrev_b32_e32 v11, 16, v54
	v_add_f32_e32 v0, v0, v8
	v_lshlrev_b32_e32 v8, 16, v64
	v_and_b32_e32 v26, 0xffff0000, v27
	v_add_f32_e32 v2, v2, v9
	v_add_f32_e32 v3, v3, v10
	v_add_f32_e32 v6, v6, v25
	v_lshlrev_b32_e32 v9, 16, v21
	v_and_b32_e32 v10, 0xffff0000, v21
	v_lshlrev_b32_e32 v21, 16, v23
	v_add_f32_e32 v5, v5, v15
	v_and_b32_e32 v15, 0xffff0000, v54
	v_add_f32_e32 v4, v4, v11
	v_lshlrev_b32_e32 v11, 16, v50
	v_add_f32_e32 v1, v1, v8
	v_and_b32_e32 v8, 0xffff0000, v64
	v_add_f32_e32 v7, v7, v26
	v_and_b32_e32 v22, 0xffff0000, v23
	v_add_f32_e32 v2, v2, v9
	v_add_f32_e32 v6, v6, v21
	v_lshlrev_b32_e32 v9, 16, v33
	v_lshlrev_b32_e32 v20, 16, v35
	v_add_f32_e32 v5, v5, v15
	v_and_b32_e32 v15, 0xffff0000, v50
	v_add_f32_e32 v4, v4, v11
	v_lshlrev_b32_e32 v11, 16, v66
	v_add_f32_e32 v0, v0, v8
	v_lshlrev_b32_e32 v8, 16, v60
	v_add_f32_e32 v7, v7, v22
	v_and_b32_e32 v21, 0xffff0000, v35
	v_add_f32_e32 v2, v2, v9
	v_add_f32_e32 v6, v6, v20
	v_lshlrev_b32_e32 v9, 16, v29
	v_lshlrev_b32_e32 v20, 16, v31
	v_add_f32_e32 v5, v5, v15
	v_and_b32_e32 v15, 0xffff0000, v66
	v_add_f32_e32 v4, v4, v11
	v_lshlrev_b32_e32 v11, 16, v62
	v_add_f32_e32 v1, v1, v8
	v_and_b32_e32 v8, 0xffff0000, v60
	v_add_f32_e32 v7, v7, v21
	v_and_b32_e32 v21, 0xffff0000, v31
	v_add_f32_e32 v2, v2, v9
	v_add_f32_e32 v6, v6, v20
	v_lshlrev_b32_e32 v9, 16, v45
	v_lshlrev_b32_e32 v20, 16, v47
	v_add_f32_e32 v5, v5, v15
	v_and_b32_e32 v15, 0xffff0000, v62
	v_add_f32_e32 v0, v0, v8
	v_add_f32_e32 v4, v4, v11
	v_lshlrev_b32_e32 v8, 16, v68
	v_lshlrev_b32_e32 v11, 16, v70
	v_add_f32_e32 v7, v7, v21
	v_and_b32_e32 v21, 0xffff0000, v47
	v_add_f32_e32 v2, v2, v9
	v_add_f32_e32 v6, v6, v20
	v_lshlrev_b32_e32 v9, 16, v41
	v_lshlrev_b32_e32 v20, 16, v43
	v_add_f32_e32 v5, v5, v15
	v_and_b32_e32 v15, 0xffff0000, v70
	v_add_f32_e32 v8, v1, v8
	v_add_f32_e32 v11, v4, v11
	s_waitcnt vmcnt(0) lgkmcnt(0)
	v_lshlrev_b32_e32 v4, 16, v72
	v_add_f32_e32 v7, v7, v21
	v_and_b32_e32 v21, 0xffff0000, v43
	v_add_f32_e32 v2, v2, v9
	v_add_f32_e32 v6, v6, v20
	v_lshlrev_b32_e32 v9, 16, v53
	v_lshlrev_b32_e32 v20, 16, v55
	v_add_f32_e32 v24, v5, v15
	v_add_f32_e32 v15, v8, v4
	v_min_i32_e32 v8, 15, v101
	v_add_f32_e32 v7, v7, v21
	v_and_b32_e32 v21, 0xffff0000, v55
	v_add_f32_e32 v2, v2, v9
	v_add_f32_e32 v6, v6, v20
	v_lshlrev_b32_e32 v9, 16, v49
	v_lshlrev_b32_e32 v20, 16, v51
	v_add_u32_e32 v8, 1, v8
	v_add_f32_e32 v7, v7, v21
	v_and_b32_e32 v21, 0xffff0000, v51
	v_add_f32_e32 v2, v2, v9
	v_add_f32_e32 v6, v6, v20
	v_lshlrev_b32_e32 v9, 16, v65
	v_lshlrev_b32_e32 v20, 16, v67
	v_cvt_f32_u32_e32 v8, v8
	v_add_f32_e32 v3, v3, v10
	v_and_b32_e32 v10, 0xffff0000, v33
	v_add_f32_e32 v7, v7, v21
	v_and_b32_e32 v21, 0xffff0000, v67
	v_add_f32_e32 v2, v2, v9
	v_add_f32_e32 v6, v6, v20
	v_lshlrev_b32_e32 v9, 16, v61
	v_lshlrev_b32_e32 v20, 16, v63
	v_add_f32_e32 v3, v3, v10
	v_and_b32_e32 v10, 0xffff0000, v29
	v_add_f32_e32 v7, v7, v21
	v_and_b32_e32 v21, 0xffff0000, v63
	v_add_f32_e32 v2, v2, v9
	v_add_f32_e32 v6, v6, v20
	v_lshlrev_b32_e32 v9, 16, v69
	v_lshlrev_b32_e32 v20, 16, v71
	v_add_f32_e32 v3, v3, v10
	v_and_b32_e32 v10, 0xffff0000, v45
	v_add_f32_e32 v7, v7, v21
	v_and_b32_e32 v21, 0xffff0000, v71
	v_add_f32_e32 v9, v2, v9
	v_add_f32_e32 v25, v6, v20
	v_lshlrev_b32_e32 v6, 16, v73
	v_add_f32_e32 v3, v3, v10
	v_and_b32_e32 v10, 0xffff0000, v41
	v_add_f32_e32 v26, v7, v21
	v_add_f32_e32 v21, v9, v6
	v_div_scale_f32 v9, s[0:1], v8, v8, 1.0
	v_add_f32_e32 v3, v3, v10
	v_and_b32_e32 v10, 0xffff0000, v53
	v_rcp_f32_e32 v27, v9
	v_add_f32_e32 v3, v3, v10
	v_and_b32_e32 v10, 0xffff0000, v49
	v_add_f32_e32 v3, v3, v10
	v_and_b32_e32 v10, 0xffff0000, v65
	v_and_b32_e32 v1, 0xffff0000, v68
	v_add_f32_e32 v3, v3, v10
	v_and_b32_e32 v10, 0xffff0000, v61
	v_add_f32_e32 v22, v0, v1
	v_lshlrev_b32_e32 v0, 16, v74
	v_lshlrev_b32_e32 v2, 16, v75
	v_add_f32_e32 v3, v3, v10
	v_and_b32_e32 v10, 0xffff0000, v69
	v_add_f32_e32 v23, v11, v0
	v_add_f32_e32 v11, v25, v2
	v_fma_f32 v25, -v9, v27, 1.0
	v_add_f32_e32 v10, v3, v10
	v_and_b32_e32 v5, 0xffff0000, v72
	v_and_b32_e32 v7, 0xffff0000, v73
	v_and_b32_e32 v3, 0xffff0000, v75
	v_fmac_f32_e32 v27, v25, v27
	v_div_scale_f32 v25, vcc, 1.0, v8, 1.0
	v_add_f32_e32 v20, v22, v5
	v_add_f32_e32 v22, v10, v7
	v_add_f32_e32 v10, v26, v3
	v_mul_f32_e32 v26, v25, v27
	v_fma_f32 v28, -v9, v26, v25
	v_fmac_f32_e32 v26, v28, v27
	v_fma_f32 v9, -v9, v26, v25
	v_and_b32_e32 v1, 0xffff0000, v74
	v_div_fmas_f32 v9, v9, v27, v26
	v_add_f32_e32 v24, v24, v1
	v_div_fixup_f32 v8, v9, v8, 1.0
	v_fma_f32 v9, v8, v15, -v4
	v_fma_f32 v25, v8, v20, -v5
	v_fma_f32 v27, v8, v21, -v6
	v_fma_f32 v28, v8, v22, -v7
	v_fma_f32 v29, v8, v23, -v0
	v_fma_f32 v30, v8, v24, -v1
	v_fma_f32 v31, v8, v11, -v2
	v_fma_f32 v8, v8, v10, -v3
	v_mov_b32_e32 v93, v97
	v_cvt_pk_bf16_f32 v26, v9, v25
	v_cvt_pk_bf16_f32 v27, v27, v28
	v_cvt_pk_bf16_f32 v28, v29, v30
	v_cvt_pk_bf16_f32 v29, v31, v8
	v_lshl_add_u64 v[8:9], s[86:87], 0, v[92:93]
	v_lshl_add_u64 v[30:31], v[8:9], 0, v[94:95]
	v_add_co_u32_e32 v30, vcc, 0x7900000, v30
	s_movk_i32 s0, 0x3ff0
	s_nop 0
	v_addc_co_u32_e32 v31, vcc, 0, v31, vcc
	v_cmp_lt_u32_e32 vcc, s0, v101
	global_store_dwordx4 v[30:31], v[26:29], off offset:1024
	s_and_saveexec_b64 s[0:1], vcc
	s_cbranch_execz .LBB0_393
	v_add_u32_e32 v25, s7, v101
	v_add_u32_e32 v26, 0xffffc00f, v25
	v_mov_b32_e32 v27, v97
	v_lshlrev_b64 v[26:27], 11, v[26:27]
	v_lshl_add_u64 v[26:27], v[86:87], 0, v[26:27]
	global_store_dwordx4 v[26:27], v[4:7], off
	global_store_dwordx4 v[26:27], v[0:3], off offset:16

; __device__ __forceinline__ void unpack8(const u32x4 w, float* f) { f[0] = bf_lo(w.x); f[1] = bf_hi(w.x); f[2] = bf_lo(w.y); f[3] = bf_hi(w.y); f[4] = bf_lo(w.z); f[5] = bf_hi(w.z); f[6] = bf_lo(w.w); f[7] = bf_hi(w.w); }
; __device__ __forceinline__ u32x4 pack8(const float* f) { u32x4 w; w.x = cvt_pk_bf16(f[0], f[1]); w.y = cvt_pk_bf16(f[2], f[3]); w.z = cvt_pk_bf16(f[4], f[5]); w.w = cvt_pk_bf16(f[6], f[7]); return w; }
; template <int W>
; __device__ __forceinline__ void pool_task_prompt(const Params& p, int l, int b, int c, int g, int rg, int ch, long row0) {
;     ...
;     u32x4 raw[W + 3];
; #pragma unroll
;     for (int i = 0; i < W + 3; ++i) { const int tt = t0 - (W - 1) + i; raw[i] = (u32x4){0u, 0u, 0u, 0u};
;         if (tt >= 0) raw[i] = *(const u32x4*)(P + (size_t)((long)b * SEQ + tt) * INW + 768 + col); }
;     float a[4][8], cur[4][8];
; #pragma unroll
;     for (int k = 0; k < 8; ++k) a[0][k] = 0.f;
; #pragma unroll
;     for (int i = 0; i < W; ++i) { float x[8]; unpack8(raw[i], x);
; #pragma unroll
;         for (int k = 0; k < 8; ++k) { a[0][k] += x[k]; if (i == W - 1) cur[0][k] = x[k]; } }
; #pragma unroll
;     for (int r = 1; r < 4; ++r) { float xin[8], xout[8]; unpack8(raw[W - 1 + r], xin); unpack8(raw[r - 1], xout);
; #pragma unroll
;         for (int k = 0; k < 8; ++k) { a[r][k] = a[r - 1][k] + (xin[k] - xout[k]); cur[r][k] = xin[k]; } }
; #pragma unroll
;     for (int r = 0; r < 4; ++r) {
;         const int t = t0 + r;
;         const float inv = 1.0f / (float)((t + 1) < W ? (t + 1) : W);
;         float d[8];
; #pragma unroll
;         for (int k = 0; k < 8; ++k) d[k] = a[r][k] * inv - cur[r][k];
;         *(u32x4*)(AD + (size_t)(row0 + tl0 + r) * DM + 512 + col) = pack8(d);
;         if (t >= SEQ - 15) { float* pd = p.out + O_PP + (((size_t)l * 2 + b) * 15 + (t - (SEQ - 15))) * 512 + col;
;             *(f32x4*)pd = (f32x4){cur[r][0], cur[r][1], cur[r][2], cur[r][3]}; *(f32x4*)(pd + 4) = (f32x4){cur[r][4], cur[r][5], cur[r][6], cur[r][7]}; }
.LBB0_402:
	v_mov_b32_e32 v8, 0
	v_cmp_ne_u32_e32 vcc, 0, v101
	v_lshlrev_b32_e32 v28, 1, v76
	v_mov_b32_e32 v9, 0
	v_mov_b32_e32 v10, 0
	v_mov_b32_e32 v11, 0
	s_and_saveexec_b64 s[0:1], vcc
	s_cbranch_execz .LBB0_404
	v_add3_u32 v2, v100, s25, -1
	v_mov_b64_e32 v[0:1], s[86:87]
	v_mad_u64_u32 v[0:1], s[10:11], v2, s89, v[0:1]
	v_mov_b32_e32 v29, v97
	v_lshl_add_u64 v[0:1], v[0:1], 0, v[28:29]
	v_add_co_u32_e32 v0, vcc, 0xfb00000, v0
	s_nop 1
	v_addc_co_u32_e32 v1, vcc, 0, v1, vcc
	global_load_dwordx4 v[8:11], v[0:1], off offset:1536 nt
.LBB0_404:
	s_or_b64 exec, exec, s[0:1]
	v_lshl_add_u64 v[0:1], s[86:87], 0, v[96:97]
	v_mov_b32_e32 v29, v97
	v_lshl_add_u64 v[0:1], v[0:1], 0, v[28:29]
	v_add_co_u32_e32 v2, vcc, 0xfb00000, v0
	s_waitcnt vmcnt(0) lgkmcnt(0)
	v_lshlrev_b32_e32 v36, 16, v8
	v_addc_co_u32_e32 v3, vcc, 0, v1, vcc
	global_load_dwordx4 v[20:23], v[2:3], off offset:1536 nt
	v_add_co_u32_e32 v2, vcc, 0xfb02000, v0
	v_and_b32_e32 v37, 0xffff0000, v8
	s_nop 0
	v_addc_co_u32_e32 v3, vcc, 0, v1, vcc
	v_add_co_u32_e32 v4, vcc, 0xfb03000, v0
	global_load_dwordx4 v[16:19], v[2:3], off nt
	s_nop 0
	v_addc_co_u32_e32 v5, vcc, 0, v1, vcc
	v_add_co_u32_e32 v0, vcc, 0xfb05000, v0
	v_min_i32_e32 v8, 1, v101
	s_nop 0
	v_addc_co_u32_e32 v1, vcc, 0, v1, vcc
	global_load_dwordx4 v[4:7], v[4:5], off offset:2560 nt
	s_nop 0
	global_load_dwordx4 v[0:3], v[0:1], off offset:1024 nt
	v_add_u32_e32 v8, 1, v8
	v_cvt_f32_u32_e32 v8, v8
	v_lshlrev_b32_e32 v35, 16, v9
	v_and_b32_e32 v34, 0xffff0000, v9
	v_lshlrev_b32_e32 v33, 16, v10
	v_div_scale_f32 v9, s[0:1], v8, v8, 1.0
	v_and_b32_e32 v32, 0xffff0000, v10
	v_rcp_f32_e32 v10, v9
	v_lshlrev_b32_e32 v27, 16, v11
	v_and_b32_e32 v26, 0xffff0000, v11
	v_div_scale_f32 v11, vcc, 1.0, v8, 1.0
	v_fma_f32 v12, -v9, v10, 1.0
	v_fmac_f32_e32 v10, v12, v10
	v_mul_f32_e32 v12, v11, v10
	v_fma_f32 v13, -v9, v12, v11
	v_fmac_f32_e32 v12, v13, v10
	v_fma_f32 v9, -v9, v12, v11
	v_div_fmas_f32 v9, v9, v10, v12
	v_add_f32_e32 v24, 0, v36
	v_add_f32_e32 v25, 0, v37
	v_add_f32_e32 v30, 0, v35
	v_add_f32_e32 v31, 0, v34
	v_add_f32_e32 v38, 0, v33
	v_add_f32_e32 v39, 0, v32
	v_add_f32_e32 v46, 0, v27
	v_add_f32_e32 v47, 0, v26
	v_div_fixup_f32 v48, v9, v8, 1.0
	v_mov_b32_e32 v93, v97
	s_movk_i32 s0, 0x3ff0
	s_waitcnt vmcnt(0) lgkmcnt(0)
	v_lshlrev_b32_e32 v12, 16, v20
	v_and_b32_e32 v13, 0xffff0000, v20
	v_lshlrev_b32_e32 v14, 16, v21
	v_and_b32_e32 v15, 0xffff0000, v21
	v_lshlrev_b32_e32 v8, 16, v22
	v_and_b32_e32 v9, 0xffff0000, v22
	v_lshlrev_b32_e32 v10, 16, v23
	v_and_b32_e32 v11, 0xffff0000, v23
	v_add_f32_e32 v45, v24, v12
	v_add_f32_e32 v44, v25, v13
	v_add_f32_e32 v43, v30, v14
	v_add_f32_e32 v42, v31, v15
	v_add_f32_e32 v41, v38, v8
	v_add_f32_e32 v40, v39, v9
	v_add_f32_e32 v39, v46, v10
	v_add_f32_e32 v38, v47, v11
	v_fma_f32 v20, v48, v45, -v12
	v_fma_f32 v21, v48, v44, -v13
	v_fma_f32 v22, v48, v43, -v14
	v_fma_f32 v23, v48, v42, -v15
	v_fma_f32 v30, v48, v39, -v10
	v_fma_f32 v31, v48, v38, -v11
	v_fma_f32 v24, v48, v41, -v8
	v_fma_f32 v25, v48, v40, -v9
	v_cvt_pk_bf16_f32 v20, v20, v21
	v_cvt_pk_bf16_f32 v21, v22, v23
	v_cvt_pk_bf16_f32 v22, v24, v25
	v_cvt_pk_bf16_f32 v23, v30, v31
	v_lshl_add_u64 v[30:31], s[86:87], 0, v[92:93]
	v_lshl_add_u64 v[24:25], v[30:31], 0, v[28:29]
	v_add_co_u32_e32 v46, vcc, 0x7900000, v24
	s_nop 1
	v_addc_co_u32_e32 v47, vcc, 0, v25, vcc
	v_cmp_lt_u32_e32 vcc, s0, v101
	global_store_dwordx4 v[46:47], v[20:23], off offset:1024
	s_and_saveexec_b64 s[0:1], vcc
	s_cbranch_execz .LBB0_406
	v_add_u32_e32 v20, s7, v101
	v_add_u32_e32 v20, 0xffffc00f, v20
	v_mov_b32_e32 v21, v97
	v_lshlrev_b64 v[20:21], 11, v[20:21]
	v_lshl_add_u64 v[20:21], v[84:85], 0, v[20:21]
	global_store_dwordx4 v[20:21], v[12:15], off
	global_store_dwordx4 v[20:21], v[8:11], off offset:16

; template <int W>
; __device__ __forceinline__ void pool_items(const Params& p, int l, bool sample, int b, int c, int g, long row0, int tid) {
;     ...
;     for (int it = tid; it < nitems; it += 512) {
;         const int tl = it >> 4, ch = it & 15, col = g * 128 + ch * 8;
;         const long prow = row0 + tl; const int t = sample ? tl : c * 64 + tl;
;         u32x4 raw[W]; f32x4 h0[W], h1[W];
; #pragma unroll
;         for (int i = 0; i < W; ++i) {
;             const int tt = t - i;
;             raw[i] = (u32x4){0u, 0u, 0u, 0u}; h0[i] = (f32x4){0.f, 0.f, 0.f, 0.f}; h1[i] = h0[i];
;             if (tt >= 0) raw[i] = *(const u32x4*)(P + (size_t)(prow - i) * INW + 768 + col);
;             else if (sample) { const float* sp = p.state_pool + (((size_t)l * 8 + b) * 15 + (15 + tt)) * 512 + col; h0[i] = *(const f32x4*)sp; h1[i] = *(const f32x4*)(sp + 4); }
.LBB0_418:
	v_ashrrev_i32_e32 v68, 4, v101
	v_and_b32_e32 v8, 0x78, v100
	v_or_b32_e32 v1, 0x100, v8
	v_ashrrev_i32_e32 v69, 31, v68
	v_lshl_add_u64 v[72:73], s[40:41], 0, v[68:69]
	v_cmp_lt_i32_e32 vcc, -1, v68
	v_mov_b32_e32 v0, 0
	v_lshlrev_b32_e32 v70, 1, v1
	v_mov_b32_e32 v1, 0
	v_mov_b32_e32 v2, 0
	v_mov_b32_e32 v3, 0
	s_and_saveexec_b64 s[14:15], vcc
	s_cbranch_execz .LBB0_420
	v_mov_b64_e32 v[0:1], s[86:87]
	v_mad_u64_u32 v[0:1], s[16:17], v72, s89, v[0:1]
	v_mad_i32_i24 v1, v73, s89, v1
	v_mov_b32_e32 v71, v97
	v_lshl_add_u64 v[0:1], v[0:1], 0, v[70:71]
	v_add_co_u32_e32 v0, vcc, 0xfb00000, v0
	s_nop 1
	v_addc_co_u32_e32 v1, vcc, 0, v1, vcc
	global_load_dwordx4 v[0:3], v[0:1], off offset:1536 nt
.LBB0_420:
	s_or_b64 exec, exec, s[14:15]
	v_cmp_lt_i32_e64 s[44:45], 0, v68
	s_and_saveexec_b64 s[14:15], s[44:45]
	s_xor_b64 s[14:15], exec, s[14:15]
	s_cbranch_execz .LBB0_422
	v_mov_b64_e32 v[4:5], s[86:87]
	v_mad_u64_u32 v[4:5], s[16:17], v72, s89, v[4:5]
	v_mad_i32_i24 v5, v73, s89, v5
	v_mov_b32_e32 v71, v97
	v_lshl_add_u64 v[4:5], v[4:5], 0, v[70:71]
	v_add_co_u32_e32 v4, vcc, 0xfafe000, v4
	s_nop 1
	v_addc_co_u32_e32 v5, vcc, 0, v5, vcc
	global_load_dwordx4 v[4:7], v[4:5], off offset:3072 nt
.LBB0_422:
	s_or_saveexec_b64 s[14:15], s[14:15]
	v_readlane_b32 s64, v249, 4
	v_lshlrev_b32_e32 v96, 2, v8
	v_readlane_b32 s72, v249, 12
	v_readlane_b32 s73, v249, 13
	v_mov_b32_e32 v8, 0
	v_mov_b32_e32 v9, 0
	v_lshl_add_u64 v[60:61], s[72:73], 0, v[96:97]
	v_mov_b32_e32 v10, 0
	v_mov_b32_e32 v11, 0
	v_mov_b32_e32 v12, 0
	v_mov_b32_e32 v13, 0
	v_mov_b32_e32 v14, 0
	v_mov_b32_e32 v15, 0
	v_readlane_b32 s65, v249, 5
	v_readlane_b32 s66, v249, 6
	v_readlane_b32 s67, v249, 7
	v_readlane_b32 s68, v249, 8
	v_readlane_b32 s69, v249, 9
	v_readlane_b32 s70, v249, 10
	v_readlane_b32 s71, v249, 11
	v_readlane_b32 s74, v249, 14
	v_readlane_b32 s75, v249, 15
	v_readlane_b32 s76, v249, 16
	v_readlane_b32 s77, v249, 17
	v_readlane_b32 s78, v249, 18
	v_readlane_b32 s79, v249, 19
	s_xor_b64 exec, exec, s[14:15]
	s_cbranch_execz .LBB0_424
	s_waitcnt vmcnt(0) lgkmcnt(0)
	v_add_u32_e32 v4, 14, v68
	v_ashrrev_i32_e32 v5, 31, v4
	v_lshl_add_u64 v[4:5], s[2:3], 0, v[4:5]
	v_lshlrev_b64 v[4:5], 11, v[4:5]
	v_lshl_add_u64 v[4:5], v[60:61], 0, v[4:5]
	global_load_dwordx4 v[8:11], v[4:5], off offset:1024 nt
	global_load_dwordx4 v[12:15], v[4:5], off offset:1040 nt
	v_mov_b32_e32 v4, 0
	v_mov_b32_e32 v5, 0
	v_mov_b32_e32 v6, 0
	v_mov_b32_e32 v7, 0
.LBB0_424:
	s_or_b64 exec, exec, s[14:15]
	v_cmp_gt_i32_e32 vcc, 2, v68
	s_and_saveexec_b64 s[14:15], vcc
	s_xor_b64 s[14:15], exec, s[14:15]
	s_cbranch_execz .LBB0_426
	v_add_u32_e32 v16, 13, v68
	v_ashrrev_i32_e32 v17, 31, v16
	v_lshl_add_u64 v[16:17], s[2:3], 0, v[16:17]
	v_lshlrev_b64 v[16:17], 11, v[16:17]
	v_lshl_add_u64 v[20:21], v[60:61], 0, v[16:17]
	global_load_dwordx4 v[16:19], v[20:21], off offset:1040 nt
	s_nop 0
	global_load_dwordx4 v[20:23], v[20:21], off offset:1024 nt
	s_waitcnt vmcnt(0)
	v_mov_b32_e32 v74, v19
	v_mov_b32_e32 v78, v17
	v_mov_b32_e32 v76, v23
	v_mov_b32_e32 v80, v21
.LBB0_426:
	s_or_saveexec_b64 s[14:15], s[14:15]
	v_mov_b32_e32 v24, 0
	v_mov_b32_e32 v25, 0
	v_mov_b32_e32 v26, 0
	v_mov_b32_e32 v27, 0
	s_xor_b64 exec, exec, s[14:15]
	s_cbranch_execz .LBB0_428
	v_mov_b64_e32 v[16:17], s[86:87]
	v_mad_u64_u32 v[16:17], s[16:17], v72, s89, v[16:17]
	v_mad_i32_i24 v17, v73, s89, v17
	v_mov_b32_e32 v71, v97
	v_lshl_add_u64 v[16:17], v[16:17], 0, v[70:71]
	v_add_co_u32_e32 v16, vcc, 0xfafd000, v16
	v_mov_b32_e32 v20, 0
	s_nop 0
	v_addc_co_u32_e32 v17, vcc, 0, v17, vcc
	global_load_dwordx4 v[24:27], v[16:17], off offset:512 nt
	v_mov_b32_e32 v80, 0
	v_mov_b32_e32 v22, v20
	v_mov_b32_e32 v76, v20
	v_mov_b32_e32 v16, v20
	v_mov_b32_e32 v78, v20
	v_mov_b32_e32 v18, v20
	v_mov_b32_e32 v74, v20
.LBB0_428:
	s_or_b64 exec, exec, s[14:15]
	v_cmp_gt_i32_e32 vcc, 3, v68
	s_and_saveexec_b64 s[14:15], vcc
	s_xor_b64 s[14:15], exec, s[14:15]
	s_cbranch_execz .LBB0_430
	v_add_u32_e32 v28, 12, v68
	v_ashrrev_i32_e32 v29, 31, v28
	v_lshl_add_u64 v[28:29], s[2:3], 0, v[28:29]
	v_lshlrev_b64 v[28:29], 11, v[28:29]
	v_lshl_add_u64 v[32:33], v[60:61], 0, v[28:29]
	global_load_dwordx4 v[28:31], v[32:33], off offset:1040 nt
	s_nop 0
	global_load_dwordx4 v[32:35], v[32:33], off offset:1024 nt
	s_waitcnt vmcnt(0)
	v_mov_b32_e32 v75, v31
	v_mov_b32_e32 v19, v30
	v_mov_b32_e32 v79, v29
	v_mov_b32_e32 v17, v28
	v_mov_b32_e32 v77, v35
	v_mov_b32_e32 v23, v34
	v_mov_b32_e32 v81, v33
	v_mov_b32_e32 v21, v32
.LBB0_430:
	s_or_saveexec_b64 s[14:15], s[14:15]
	v_mov_b32_e32 v28, 0
	v_mov_b32_e32 v29, 0
	v_mov_b32_e32 v30, 0
	v_mov_b32_e32 v31, 0
	s_xor_b64 exec, exec, s[14:15]
	s_cbranch_execz .LBB0_432
	v_mov_b64_e32 v[28:29], s[86:87]
	v_mad_u64_u32 v[28:29], s[16:17], v72, s89, v[28:29]
	v_mad_i32_i24 v29, v73, s89, v29
	v_mov_b32_e32 v71, v97
	v_lshl_add_u64 v[28:29], v[28:29], 0, v[70:71]
	v_add_co_u32_e32 v28, vcc, 0xfafb000, v28
	v_mov_b32_e32 v21, 0
	s_nop 0
	v_addc_co_u32_e32 v29, vcc, 0, v29, vcc
	global_load_dwordx4 v[28:31], v[28:29], off offset:2048 nt
	v_mov_b32_e32 v81, v21
	v_mov_b32_e32 v23, v21
	v_mov_b32_e32 v77, v21
	v_mov_b32_e32 v17, v21
	v_mov_b32_e32 v79, v21
	v_mov_b32_e32 v19, v21
	v_mov_b32_e32 v75, v21
; template <int W>
; __device__ __forceinline__ void pool_items(const Params& p, int l, bool sample, int b, int c, int g, long row0, int tid) {
;     ...
; #pragma unroll
;         for (int i = 0; i < W; ++i) {
;             const int tt = t - i;
;             raw[i] = (u32x4){0u, 0u, 0u, 0u}; h0[i] = (f32x4){0.f, 0.f, 0.f, 0.f}; h1[i] = h0[i];
;             if (tt >= 0) raw[i] = *(const u32x4*)(P + (size_t)(prow - i) * INW + 768 + col);
;             else if (sample) { const float* sp = p.state_pool + (((size_t)l * 8 + b) * 15 + (15 + tt)) * 512 + col; h0[i] = *(const f32x4*)sp; h1[i] = *(const f32x4*)(sp + 4); }
.LBB0_432:
	s_or_b64 exec, exec, s[14:15]
	v_cmp_gt_i32_e32 vcc, 4, v68
	s_and_saveexec_b64 s[14:15], vcc
	s_xor_b64 s[14:15], exec, s[14:15]
	s_cbranch_execz .LBB0_434
	v_add_u32_e32 v32, 11, v68
	v_ashrrev_i32_e32 v33, 31, v32
	v_lshl_add_u64 v[32:33], s[2:3], 0, v[32:33]
	v_lshlrev_b64 v[32:33], 11, v[32:33]
	v_lshl_add_u64 v[36:37], v[60:61], 0, v[32:33]
	global_load_dwordx4 v[32:35], v[36:37], off offset:1040 nt
	s_nop 0
	global_load_dwordx4 v[36:39], v[36:37], off offset:1024 nt
	s_waitcnt vmcnt(0)
	v_mov_b32_e32 v82, v35
	v_mov_b32_e32 v86, v33
	v_mov_b32_e32 v84, v39
	v_mov_b32_e32 v88, v37
.LBB0_434:
	s_or_saveexec_b64 s[14:15], s[14:15]
	v_mov_b32_e32 v40, 0
	v_mov_b32_e32 v41, 0
	v_mov_b32_e32 v42, 0
	v_mov_b32_e32 v43, 0
	s_xor_b64 exec, exec, s[14:15]
	s_cbranch_execz .LBB0_436
	v_mov_b64_e32 v[32:33], s[86:87]
	v_mad_u64_u32 v[32:33], s[16:17], v72, s89, v[32:33]
	v_mad_i32_i24 v33, v73, s89, v33
	v_mov_b32_e32 v71, v97
	v_lshl_add_u64 v[32:33], v[32:33], 0, v[70:71]
	v_add_co_u32_e32 v32, vcc, 0xfaf9000, v32
	v_mov_b32_e32 v36, 0
	s_nop 0
	v_addc_co_u32_e32 v33, vcc, 0, v33, vcc
	global_load_dwordx4 v[40:43], v[32:33], off offset:3584 nt
	v_mov_b32_e32 v88, 0
	v_mov_b32_e32 v38, v36
	v_mov_b32_e32 v84, v36
	v_mov_b32_e32 v32, v36
	v_mov_b32_e32 v86, v36
	v_mov_b32_e32 v34, v36
	v_mov_b32_e32 v82, v36
.LBB0_436:
	s_or_b64 exec, exec, s[14:15]
	v_cmp_gt_i32_e32 vcc, 5, v68
	s_and_saveexec_b64 s[14:15], vcc
	s_xor_b64 s[14:15], exec, s[14:15]
	s_cbranch_execz .LBB0_438
	v_add_u32_e32 v44, 10, v68
	v_ashrrev_i32_e32 v45, 31, v44
	v_lshl_add_u64 v[44:45], s[2:3], 0, v[44:45]
	v_lshlrev_b64 v[44:45], 11, v[44:45]
	v_lshl_add_u64 v[48:49], v[60:61], 0, v[44:45]
	global_load_dwordx4 v[44:47], v[48:49], off offset:1040 nt
	s_nop 0
	global_load_dwordx4 v[48:51], v[48:49], off offset:1024 nt
	s_waitcnt vmcnt(0)
	v_mov_b32_e32 v83, v47
	v_mov_b32_e32 v35, v46
	v_mov_b32_e32 v87, v45
	v_mov_b32_e32 v33, v44
	v_mov_b32_e32 v85, v51
	v_mov_b32_e32 v39, v50
	v_mov_b32_e32 v89, v49
	v_mov_b32_e32 v37, v48
.LBB0_438:
	s_or_saveexec_b64 s[14:15], s[14:15]
	v_mov_b32_e32 v44, 0
	v_mov_b32_e32 v45, 0
	v_mov_b32_e32 v46, 0
	v_mov_b32_e32 v47, 0
	s_xor_b64 exec, exec, s[14:15]
	s_cbranch_execz .LBB0_440
	v_mov_b64_e32 v[44:45], s[86:87]
	v_mad_u64_u32 v[44:45], s[16:17], v72, s89, v[44:45]
	v_mad_i32_i24 v45, v73, s89, v45
	v_mov_b32_e32 v71, v97
	v_lshl_add_u64 v[44:45], v[44:45], 0, v[70:71]
	v_add_co_u32_e32 v44, vcc, 0xfaf8000, v44
	v_mov_b32_e32 v37, 0
	s_nop 0
	v_addc_co_u32_e32 v45, vcc, 0, v45, vcc
	global_load_dwordx4 v[44:47], v[44:45], off offset:1024 nt
	v_mov_b32_e32 v89, v37
	v_mov_b32_e32 v39, v37
	v_mov_b32_e32 v85, v37
	v_mov_b32_e32 v33, v37
	v_mov_b32_e32 v87, v37
	v_mov_b32_e32 v35, v37
	v_mov_b32_e32 v83, v37
.LBB0_440:
	s_or_b64 exec, exec, s[14:15]
	v_cmp_gt_i32_e32 vcc, 6, v68
	s_and_saveexec_b64 s[14:15], vcc
	s_xor_b64 s[14:15], exec, s[14:15]
	s_cbranch_execz .LBB0_442
	v_add_u32_e32 v48, 9, v68
	v_ashrrev_i32_e32 v49, 31, v48
	v_lshl_add_u64 v[48:49], s[2:3], 0, v[48:49]
	v_lshlrev_b64 v[48:49], 11, v[48:49]
	v_lshl_add_u64 v[52:53], v[60:61], 0, v[48:49]
	global_load_dwordx4 v[48:51], v[52:53], off offset:1040 nt
	s_nop 0
	global_load_dwordx4 v[52:55], v[52:53], off offset:1024 nt
	s_waitcnt vmcnt(0)
	v_mov_b32_e32 v90, v51
	v_mov_b32_e32 v94, v49
	v_mov_b32_e32 v92, v55
	v_mov_b32_e32 v98, v53
.LBB0_442:
	s_or_saveexec_b64 s[14:15], s[14:15]
	v_mov_b32_e32 v56, 0
	v_mov_b32_e32 v57, 0
	v_mov_b32_e32 v58, 0
	v_mov_b32_e32 v59, 0
	s_xor_b64 exec, exec, s[14:15]
	s_cbranch_execz .LBB0_444
	v_mov_b64_e32 v[48:49], s[86:87]
	v_mad_u64_u32 v[48:49], s[16:17], v72, s89, v[48:49]
	v_mad_i32_i24 v49, v73, s89, v49
	v_mov_b32_e32 v71, v97
	v_lshl_add_u64 v[48:49], v[48:49], 0, v[70:71]
	v_add_co_u32_e32 v48, vcc, 0xfaf6000, v48
	v_mov_b32_e32 v52, 0
	s_nop 0
	v_addc_co_u32_e32 v49, vcc, 0, v49, vcc
	global_load_dwordx4 v[56:59], v[48:49], off offset:2560 nt
	v_mov_b32_e32 v98, 0
	v_mov_b32_e32 v54, v52
	v_mov_b32_e32 v92, v52
	v_mov_b32_e32 v48, v52
	v_mov_b32_e32 v94, v52
	v_mov_b32_e32 v50, v52
	v_mov_b32_e32 v90, v52
.LBB0_444:
	s_or_b64 exec, exec, s[14:15]
	v_cmp_gt_i32_e32 vcc, 7, v68
	s_and_saveexec_b64 s[14:15], vcc
	s_xor_b64 s[14:15], exec, s[14:15]
	s_cbranch_execz .LBB0_446
	v_add_u32_e32 v62, 8, v68
	v_ashrrev_i32_e32 v63, 31, v62
	v_lshl_add_u64 v[62:63], s[2:3], 0, v[62:63]
	v_lshlrev_b64 v[62:63], 11, v[62:63]
	v_lshl_add_u64 v[64:65], v[60:61], 0, v[62:63]
	global_load_dwordx4 v[60:63], v[64:65], off offset:1040 nt
	s_nop 0
	global_load_dwordx4 v[64:67], v[64:65], off offset:1024 nt
	s_waitcnt vmcnt(0)
	v_mov_b32_e32 v91, v63
	v_mov_b32_e32 v51, v62
	v_mov_b32_e32 v95, v61
	v_mov_b32_e32 v49, v60
	v_mov_b32_e32 v93, v67
	v_mov_b32_e32 v55, v66
	v_mov_b32_e32 v99, v65
	v_mov_b32_e32 v53, v64
.LBB0_446:
	s_or_saveexec_b64 s[14:15], s[14:15]
	v_mov_b32_e32 v64, 0
	v_mov_b32_e32 v65, 0
	v_mov_b32_e32 v66, 0
	v_mov_b32_e32 v67, 0
	s_xor_b64 exec, exec, s[14:15]
	s_cbranch_execz .LBB0_448
	v_mov_b64_e32 v[60:61], s[86:87]
	v_mad_u64_u32 v[60:61], s[16:17], v72, s89, v[60:61]
	v_mad_i32_i24 v61, v73, s89, v61
	v_mov_b32_e32 v71, v97
	v_lshl_add_u64 v[60:61], v[60:61], 0, v[70:71]
	v_add_co_u32_e32 v60, vcc, 0xfaf5000, v60
	v_mov_b32_e32 v53, 0
	s_nop 0
	v_addc_co_u32_e32 v61, vcc, 0, v61, vcc
	global_load_dwordx4 v[64:67], v[60:61], off nt
	v_mov_b32_e32 v99, v53
	v_mov_b32_e32 v55, v53
	v_mov_b32_e32 v93, v53
	v_mov_b32_e32 v49, v53
	v_mov_b32_e32 v95, v53
	v_mov_b32_e32 v51, v53
	v_mov_b32_e32 v91, v53

; template <int W>
; __device__ __forceinline__ void pool_items(const Params& p, int l, bool sample, int b, int c, int g, long row0, int tid) {
;     ...
;     for (int it = tid; it < nitems; it += 512) {
;         const int tl = it >> 4, ch = it & 15, col = g * 128 + ch * 8;
;         const long prow = row0 + tl; const int t = sample ? tl : c * 64 + tl;
;         u32x4 raw[W]; f32x4 h0[W], h1[W];
; #pragma unroll
;         for (int i = 0; i < W; ++i) {
;             const int tt = t - i;
;             raw[i] = (u32x4){0u, 0u, 0u, 0u}; h0[i] = (f32x4){0.f, 0.f, 0.f, 0.f}; h1[i] = h0[i];
;             if (tt >= 0) raw[i] = *(const u32x4*)(P + (size_t)(prow - i) * INW + 768 + col);
;             else if (sample) { const float* sp = p.state_pool + (((size_t)l * 8 + b) * 15 + (15 + tt)) * 512 + col; h0[i] = *(const f32x4*)sp; h1[i] = *(const f32x4*)(sp + 4); }
.LBB0_454:
	v_ashrrev_i32_e32 v20, 4, v27
	v_and_b32_e32 v9, 0x78, v26
	v_ashrrev_i32_e32 v21, 31, v20
	v_lshl_add_u64 v[22:23], s[40:41], 0, v[20:21]
	v_cmp_lt_i32_e32 vcc, -1, v20
	v_mov_b32_e32 v0, 0
	v_lshlrev_b32_e32 v96, 1, v9
	v_mov_b32_e32 v1, 0
	v_mov_b32_e32 v2, 0
	v_mov_b32_e32 v3, 0
	s_and_saveexec_b64 s[0:1], vcc
	s_cbranch_execz .LBB0_456
	v_mov_b64_e32 v[0:1], s[86:87]
	v_mad_u64_u32 v[0:1], s[16:17], v22, s89, v[0:1]
	v_mad_i32_i24 v1, v23, s89, v1
	v_lshl_add_u64 v[0:1], v[0:1], 0, v[96:97]
	v_add_co_u32_e32 v0, vcc, 0xfb00000, v0
	s_nop 1
	v_addc_co_u32_e32 v1, vcc, 0, v1, vcc
	global_load_dwordx4 v[0:3], v[0:1], off offset:1536 nt
.LBB0_456:
	s_or_b64 exec, exec, s[0:1]
	v_cmp_lt_i32_e64 s[0:1], 0, v20
	s_and_saveexec_b64 s[16:17], s[0:1]
	s_xor_b64 s[16:17], exec, s[16:17]
	s_cbranch_execz .LBB0_458
	v_mov_b64_e32 v[4:5], s[86:87]
	v_mad_u64_u32 v[4:5], s[44:45], v22, s89, v[4:5]
	v_mad_i32_i24 v5, v23, s89, v5
	v_lshl_add_u64 v[4:5], v[4:5], 0, v[96:97]
	v_add_co_u32_e32 v4, vcc, 0xfafe000, v4
	s_nop 1
	v_addc_co_u32_e32 v5, vcc, 0, v5, vcc
	global_load_dwordx4 v[4:7], v[4:5], off offset:3072 nt
.LBB0_458:
	s_or_saveexec_b64 s[16:17], s[16:17]
	v_mov_b32_e32 v8, 0
	v_lshlrev_b32_e32 v24, 2, v9
	v_mov_b32_e32 v9, 0
	v_mov_b32_e32 v10, 0
	v_mov_b32_e32 v11, 0
	v_mov_b32_e32 v16, 0
	v_mov_b32_e32 v17, 0
	v_mov_b32_e32 v18, 0
	v_mov_b32_e32 v19, 0
	s_xor_b64 exec, exec, s[16:17]
	s_cbranch_execz .LBB0_460
	s_waitcnt vmcnt(0) lgkmcnt(0)
	v_add_u32_e32 v6, 14, v20
	v_readlane_b32 s64, v249, 4
	v_ashrrev_i32_e32 v7, 31, v6
	v_mov_b32_e32 v25, v97
	v_readlane_b32 s72, v249, 12
	v_readlane_b32 s73, v249, 13
	v_lshl_add_u64 v[6:7], s[2:3], 0, v[6:7]
	v_lshlrev_b64 v[6:7], 11, v[6:7]
	v_lshl_add_u64 v[4:5], s[72:73], 0, v[24:25]
	v_lshl_add_u64 v[4:5], v[4:5], 0, v[6:7]
	global_load_dwordx4 v[8:11], v[4:5], off nt
	global_load_dwordx4 v[16:19], v[4:5], off offset:16 nt
	v_mov_b32_e32 v4, 0
	v_mov_b32_e32 v5, 0
	v_mov_b32_e32 v6, 0
	v_mov_b32_e32 v7, 0
	v_readlane_b32 s65, v249, 5
	v_readlane_b32 s66, v249, 6
	v_readlane_b32 s67, v249, 7
	v_readlane_b32 s68, v249, 8
	v_readlane_b32 s69, v249, 9
	v_readlane_b32 s70, v249, 10
	v_readlane_b32 s71, v249, 11
	v_readlane_b32 s74, v249, 14
	v_readlane_b32 s75, v249, 15
	v_readlane_b32 s76, v249, 16
	v_readlane_b32 s77, v249, 17
	v_readlane_b32 s78, v249, 18
	v_readlane_b32 s79, v249, 19

; template <int W>
; __device__ __forceinline__ void pool_items(const Params& p, int l, bool sample, int b, int c, int g, long row0, int tid) {
;     ...
;     for (int it = tid; it < nitems; it += 512) {
;         const int tl = it >> 4, ch = it & 15, col = g * 128 + ch * 8;
;         const long prow = row0 + tl; const int t = sample ? tl : c * 64 + tl;
;         u32x4 raw[W]; f32x4 h0[W], h1[W];
; #pragma unroll
;         for (int i = 0; i < W; ++i) {
;             const int tt = t - i;
;             raw[i] = (u32x4){0u, 0u, 0u, 0u}; h0[i] = (f32x4){0.f, 0.f, 0.f, 0.f}; h1[i] = h0[i];
;             if (tt >= 0) raw[i] = *(const u32x4*)(P + (size_t)(prow - i) * INW + 768 + col);
;             else if (sample) { const float* sp = p.state_pool + (((size_t)l * 8 + b) * 15 + (15 + tt)) * 512 + col; h0[i] = *(const f32x4*)sp; h1[i] = *(const f32x4*)(sp + 4); }
.LBB0_467:
	v_ashrrev_i32_e32 v158, 4, v211
	v_and_b32_e32 v8, 0x78, v210
	v_or_b32_e32 v1, 0x180, v8
	v_ashrrev_i32_e32 v159, 31, v158
	v_lshl_add_u64 v[162:163], s[40:41], 0, v[158:159]
	v_cmp_lt_i32_e32 vcc, -1, v158
	v_mov_b32_e32 v0, 0
	v_lshlrev_b32_e32 v160, 1, v1
	v_mov_b32_e32 v1, 0
	v_mov_b32_e32 v2, 0
	v_mov_b32_e32 v3, 0
	s_and_saveexec_b64 s[12:13], vcc
	s_cbranch_execz .LBB0_469
	v_mov_b64_e32 v[0:1], s[86:87]
	v_mad_u64_u32 v[0:1], s[14:15], v162, s89, v[0:1]
	v_mad_i32_i24 v1, v163, s89, v1
	v_mov_b32_e32 v161, v97
	v_lshl_add_u64 v[0:1], v[0:1], 0, v[160:161]
	v_add_co_u32_e32 v0, vcc, 0xfb00000, v0
	s_nop 1
	v_addc_co_u32_e32 v1, vcc, 0, v1, vcc
	global_load_dwordx4 v[0:3], v[0:1], off offset:1536 nt
.LBB0_469:
	s_or_b64 exec, exec, s[12:13]
	v_cmp_lt_i32_e64 s[44:45], 0, v158
	s_and_saveexec_b64 s[12:13], s[44:45]
	s_xor_b64 s[12:13], exec, s[12:13]
	s_cbranch_execz .LBB0_471
	v_mov_b64_e32 v[4:5], s[86:87]
	v_mad_u64_u32 v[4:5], s[14:15], v162, s89, v[4:5]
	v_mad_i32_i24 v5, v163, s89, v5
	v_mov_b32_e32 v161, v97
	v_lshl_add_u64 v[4:5], v[4:5], 0, v[160:161]
	v_add_co_u32_e32 v4, vcc, 0xfafe000, v4
	s_nop 1
	v_addc_co_u32_e32 v5, vcc, 0, v5, vcc
	global_load_dwordx4 v[4:7], v[4:5], off offset:3072 nt
.LBB0_471:
	s_or_saveexec_b64 s[12:13], s[12:13]
	v_readlane_b32 s64, v249, 4
	v_lshlrev_b32_e32 v96, 2, v8
	v_readlane_b32 s72, v249, 12
	v_readlane_b32 s73, v249, 13
	v_mov_b32_e32 v8, 0
	v_mov_b32_e32 v9, 0
	v_lshl_add_u64 v[150:151], s[72:73], 0, v[96:97]
	v_mov_b32_e32 v10, 0
	v_mov_b32_e32 v11, 0
	v_mov_b32_e32 v12, 0
	v_mov_b32_e32 v13, 0
	v_mov_b32_e32 v14, 0
	v_mov_b32_e32 v15, 0
	v_readlane_b32 s65, v249, 5
	v_readlane_b32 s66, v249, 6
	v_readlane_b32 s67, v249, 7
	v_readlane_b32 s68, v249, 8
	v_readlane_b32 s69, v249, 9
	v_readlane_b32 s70, v249, 10
	v_readlane_b32 s71, v249, 11
	v_readlane_b32 s74, v249, 14
	v_readlane_b32 s75, v249, 15
	v_readlane_b32 s76, v249, 16
	v_readlane_b32 s77, v249, 17
	v_readlane_b32 s78, v249, 18
	v_readlane_b32 s79, v249, 19
	s_xor_b64 exec, exec, s[12:13]
	s_cbranch_execz .LBB0_473
	s_waitcnt vmcnt(0) lgkmcnt(0)
	v_add_u32_e32 v4, 14, v158
	v_ashrrev_i32_e32 v5, 31, v4
	v_lshl_add_u64 v[4:5], s[2:3], 0, v[4:5]
	v_lshlrev_b64 v[4:5], 11, v[4:5]
	v_lshl_add_u64 v[4:5], v[150:151], 0, v[4:5]
	global_load_dwordx4 v[8:11], v[4:5], off offset:1536 nt
	global_load_dwordx4 v[12:15], v[4:5], off offset:1552 nt
	v_mov_b32_e32 v4, 0
	v_mov_b32_e32 v5, v4
	v_mov_b32_e32 v6, v4
	v_mov_b32_e32 v7, v4
.LBB0_473:
	s_or_b64 exec, exec, s[12:13]
	v_cmp_gt_i32_e32 vcc, 2, v158
	s_and_saveexec_b64 s[12:13], vcc
	s_xor_b64 s[12:13], exec, s[12:13]
	s_cbranch_execz .LBB0_475
	v_add_u32_e32 v16, 13, v158
	v_ashrrev_i32_e32 v17, 31, v16
	v_lshl_add_u64 v[16:17], s[2:3], 0, v[16:17]
	v_lshlrev_b64 v[16:17], 11, v[16:17]
	v_lshl_add_u64 v[20:21], v[150:151], 0, v[16:17]
	global_load_dwordx4 v[16:19], v[20:21], off offset:1536 nt
	s_nop 0
	global_load_dwordx4 v[20:23], v[20:21], off offset:1552 nt
.LBB0_475:
	s_or_saveexec_b64 s[12:13], s[12:13]
	v_mov_b32_e32 v24, 0
	v_mov_b32_e32 v25, 0
	v_mov_b32_e32 v26, 0
	v_mov_b32_e32 v27, 0
	s_xor_b64 exec, exec, s[12:13]
	s_cbranch_execz .LBB0_477
	s_waitcnt vmcnt(0)
	v_mov_b64_e32 v[16:17], s[86:87]
	v_mad_u64_u32 v[16:17], s[14:15], v162, s89, v[16:17]
	v_mad_i32_i24 v17, v163, s89, v17
	v_mov_b32_e32 v161, v97
	v_lshl_add_u64 v[16:17], v[16:17], 0, v[160:161]
	v_add_co_u32_e32 v16, vcc, 0xfafd000, v16
	s_nop 1
	v_addc_co_u32_e32 v17, vcc, 0, v17, vcc
	global_load_dwordx4 v[24:27], v[16:17], off offset:512 nt
	v_mov_b32_e32 v16, 0
	v_mov_b32_e32 v17, v16
	v_mov_b32_e32 v18, v16
	v_mov_b32_e32 v19, v16
	v_mov_b32_e32 v20, v16
	v_mov_b32_e32 v21, v16
	v_mov_b32_e32 v22, v16
	v_mov_b32_e32 v23, v16
.LBB0_477:
	s_or_b64 exec, exec, s[12:13]
	v_cmp_gt_i32_e32 vcc, 3, v158
	s_and_saveexec_b64 s[12:13], vcc
	s_xor_b64 s[12:13], exec, s[12:13]
	s_cbranch_execz .LBB0_479
	v_add_u32_e32 v28, 12, v158
	v_ashrrev_i32_e32 v29, 31, v28
	v_lshl_add_u64 v[28:29], s[2:3], 0, v[28:29]
	v_lshlrev_b64 v[28:29], 11, v[28:29]
	v_lshl_add_u64 v[32:33], v[150:151], 0, v[28:29]
	global_load_dwordx4 v[28:31], v[32:33], off offset:1536 nt
	s_nop 0
	global_load_dwordx4 v[32:35], v[32:33], off offset:1552 nt
.LBB0_479:
	s_or_saveexec_b64 s[12:13], s[12:13]
	v_mov_b32_e32 v36, 0
	v_mov_b32_e32 v37, 0
	v_mov_b32_e32 v38, 0
	v_mov_b32_e32 v39, 0
	s_xor_b64 exec, exec, s[12:13]
	s_cbranch_execz .LBB0_481
	s_waitcnt vmcnt(0)
	v_mov_b64_e32 v[28:29], s[86:87]
	v_mad_u64_u32 v[28:29], s[14:15], v162, s89, v[28:29]
	v_mad_i32_i24 v29, v163, s89, v29
	v_mov_b32_e32 v161, v97
	v_lshl_add_u64 v[28:29], v[28:29], 0, v[160:161]
	v_add_co_u32_e32 v28, vcc, 0xfafb000, v28
	s_nop 1
	v_addc_co_u32_e32 v29, vcc, 0, v29, vcc
	global_load_dwordx4 v[36:39], v[28:29], off offset:2048 nt
	v_mov_b32_e32 v28, 0
	v_mov_b32_e32 v29, v28
	v_mov_b32_e32 v30, v28
	v_mov_b32_e32 v31, v28
	v_mov_b32_e32 v32, v28
	v_mov_b32_e32 v33, v28
	v_mov_b32_e32 v34, v28
	v_mov_b32_e32 v35, v28
.LBB0_481:
	s_or_b64 exec, exec, s[12:13]
	v_cmp_gt_i32_e32 vcc, 4, v158
	s_and_saveexec_b64 s[12:13], vcc
	s_xor_b64 s[12:13], exec, s[12:13]
	s_cbranch_execz .LBB0_483
	v_add_u32_e32 v40, 11, v158
	v_ashrrev_i32_e32 v41, 31, v40
	v_lshl_add_u64 v[40:41], s[2:3], 0, v[40:41]
	v_lshlrev_b64 v[40:41], 11, v[40:41]
	v_lshl_add_u64 v[44:45], v[150:151], 0, v[40:41]
	global_load_dwordx4 v[40:43], v[44:45], off offset:1536 nt
	s_nop 0
	global_load_dwordx4 v[44:47], v[44:45], off offset:1552 nt
; template <int W>
; __device__ __forceinline__ void pool_items(const Params& p, int l, bool sample, int b, int c, int g, long row0, int tid) {
;     ...
; #pragma unroll
;         for (int i = 0; i < W; ++i) {
;             const int tt = t - i;
;             raw[i] = (u32x4){0u, 0u, 0u, 0u}; h0[i] = (f32x4){0.f, 0.f, 0.f, 0.f}; h1[i] = h0[i];
;             if (tt >= 0) raw[i] = *(const u32x4*)(P + (size_t)(prow - i) * INW + 768 + col);
;             else if (sample) { const float* sp = p.state_pool + (((size_t)l * 8 + b) * 15 + (15 + tt)) * 512 + col; h0[i] = *(const f32x4*)sp; h1[i] = *(const f32x4*)(sp + 4); }
.LBB0_483:
	s_or_saveexec_b64 s[12:13], s[12:13]
	v_mov_b32_e32 v48, 0
	v_mov_b32_e32 v49, 0
	v_mov_b32_e32 v50, 0
	v_mov_b32_e32 v51, 0
	s_xor_b64 exec, exec, s[12:13]
	s_cbranch_execz .LBB0_485
	s_waitcnt vmcnt(0)
	v_mov_b64_e32 v[40:41], s[86:87]
	v_mad_u64_u32 v[40:41], s[14:15], v162, s89, v[40:41]
	v_mad_i32_i24 v41, v163, s89, v41
	v_mov_b32_e32 v161, v97
	v_lshl_add_u64 v[40:41], v[40:41], 0, v[160:161]
	v_add_co_u32_e32 v40, vcc, 0xfaf9000, v40
	s_nop 1
	v_addc_co_u32_e32 v41, vcc, 0, v41, vcc
	global_load_dwordx4 v[48:51], v[40:41], off offset:3584 nt
	v_mov_b32_e32 v40, 0
	v_mov_b32_e32 v41, v40
	v_mov_b32_e32 v42, v40
	v_mov_b32_e32 v43, v40
	v_mov_b32_e32 v44, v40
	v_mov_b32_e32 v45, v40
	v_mov_b32_e32 v46, v40
	v_mov_b32_e32 v47, v40
.LBB0_485:
	s_or_b64 exec, exec, s[12:13]
	v_cmp_gt_i32_e32 vcc, 5, v158
	s_and_saveexec_b64 s[12:13], vcc
	s_xor_b64 s[12:13], exec, s[12:13]
	s_cbranch_execz .LBB0_487
	v_add_u32_e32 v52, 10, v158
	v_ashrrev_i32_e32 v53, 31, v52
	v_lshl_add_u64 v[52:53], s[2:3], 0, v[52:53]
	v_lshlrev_b64 v[52:53], 11, v[52:53]
	v_lshl_add_u64 v[56:57], v[150:151], 0, v[52:53]
	global_load_dwordx4 v[52:55], v[56:57], off offset:1536 nt
	s_nop 0
	global_load_dwordx4 v[56:59], v[56:57], off offset:1552 nt
.LBB0_487:
	s_or_saveexec_b64 s[12:13], s[12:13]
	v_mov_b32_e32 v60, 0
	v_mov_b32_e32 v61, 0
	v_mov_b32_e32 v62, 0
	v_mov_b32_e32 v63, 0
	s_xor_b64 exec, exec, s[12:13]
	s_cbranch_execz .LBB0_489
	s_waitcnt vmcnt(0)
	v_mov_b64_e32 v[52:53], s[86:87]
	v_mad_u64_u32 v[52:53], s[14:15], v162, s89, v[52:53]
	v_mad_i32_i24 v53, v163, s89, v53
	v_mov_b32_e32 v161, v97
	v_lshl_add_u64 v[52:53], v[52:53], 0, v[160:161]
	v_add_co_u32_e32 v52, vcc, 0xfaf8000, v52
	s_nop 1
	v_addc_co_u32_e32 v53, vcc, 0, v53, vcc
	global_load_dwordx4 v[60:63], v[52:53], off offset:1024 nt
	v_mov_b32_e32 v52, 0
	v_mov_b32_e32 v53, v52
	v_mov_b32_e32 v54, v52
	v_mov_b32_e32 v55, v52
	v_mov_b32_e32 v56, v52
	v_mov_b32_e32 v57, v52
	v_mov_b32_e32 v58, v52
	v_mov_b32_e32 v59, v52
.LBB0_489:
	s_or_b64 exec, exec, s[12:13]
	v_cmp_gt_i32_e32 vcc, 6, v158
	s_and_saveexec_b64 s[12:13], vcc
	s_xor_b64 s[12:13], exec, s[12:13]
	s_cbranch_execz .LBB0_491
	v_add_u32_e32 v64, 9, v158
	v_ashrrev_i32_e32 v65, 31, v64
	v_lshl_add_u64 v[64:65], s[2:3], 0, v[64:65]
	v_lshlrev_b64 v[64:65], 11, v[64:65]
	v_lshl_add_u64 v[68:69], v[150:151], 0, v[64:65]
	global_load_dwordx4 v[64:67], v[68:69], off offset:1536 nt
	s_nop 0
	global_load_dwordx4 v[68:71], v[68:69], off offset:1552 nt
.LBB0_491:
	s_or_saveexec_b64 s[12:13], s[12:13]
	v_mov_b32_e32 v72, 0
	v_mov_b32_e32 v73, 0
	v_mov_b32_e32 v74, 0
	v_mov_b32_e32 v75, 0
	s_xor_b64 exec, exec, s[12:13]
	s_cbranch_execz .LBB0_493
	s_waitcnt vmcnt(0)
	v_mov_b64_e32 v[64:65], s[86:87]
	v_mad_u64_u32 v[64:65], s[14:15], v162, s89, v[64:65]
	v_mad_i32_i24 v65, v163, s89, v65
	v_mov_b32_e32 v161, v97
	v_lshl_add_u64 v[64:65], v[64:65], 0, v[160:161]
	v_add_co_u32_e32 v64, vcc, 0xfaf6000, v64
	s_nop 1
	v_addc_co_u32_e32 v65, vcc, 0, v65, vcc
	global_load_dwordx4 v[72:75], v[64:65], off offset:2560 nt
	v_mov_b32_e32 v64, 0
	v_mov_b32_e32 v65, v64
	v_mov_b32_e32 v66, v64
	v_mov_b32_e32 v67, v64
	v_mov_b32_e32 v68, v64
	v_mov_b32_e32 v69, v64
	v_mov_b32_e32 v70, v64
	v_mov_b32_e32 v71, v64
.LBB0_493:
	s_or_b64 exec, exec, s[12:13]
	v_cmp_gt_i32_e32 vcc, 7, v158
	s_and_saveexec_b64 s[12:13], vcc
	s_xor_b64 s[12:13], exec, s[12:13]
	s_cbranch_execz .LBB0_495
	v_add_u32_e32 v76, 8, v158
	v_ashrrev_i32_e32 v77, 31, v76
	v_lshl_add_u64 v[76:77], s[2:3], 0, v[76:77]
	v_lshlrev_b64 v[76:77], 11, v[76:77]
	v_lshl_add_u64 v[80:81], v[150:151], 0, v[76:77]
	global_load_dwordx4 v[76:79], v[80:81], off offset:1536 nt
	s_nop 0
	global_load_dwordx4 v[80:83], v[80:81], off offset:1552 nt
.LBB0_495:
	s_or_saveexec_b64 s[12:13], s[12:13]
	v_mov_b32_e32 v84, 0
	v_mov_b32_e32 v85, 0
	v_mov_b32_e32 v86, 0
	v_mov_b32_e32 v87, 0
	s_xor_b64 exec, exec, s[12:13]
	s_cbranch_execz .LBB0_497
	s_waitcnt vmcnt(0)
	v_mov_b64_e32 v[76:77], s[86:87]
	v_mad_u64_u32 v[76:77], s[14:15], v162, s89, v[76:77]
	v_mad_i32_i24 v77, v163, s89, v77
	v_mov_b32_e32 v161, v97
	v_lshl_add_u64 v[76:77], v[76:77], 0, v[160:161]
	v_add_co_u32_e32 v76, vcc, 0xfaf5000, v76
	s_nop 1
	v_addc_co_u32_e32 v77, vcc, 0, v77, vcc
	global_load_dwordx4 v[84:87], v[76:77], off nt
	v_mov_b32_e32 v76, 0
	v_mov_b32_e32 v77, v76
	v_mov_b32_e32 v78, v76
	v_mov_b32_e32 v79, v76
	v_mov_b32_e32 v80, v76
	v_mov_b32_e32 v81, v76
	v_mov_b32_e32 v82, v76
	v_mov_b32_e32 v83, v76
.LBB0_497:
	s_or_b64 exec, exec, s[12:13]
	v_cmp_gt_i32_e32 vcc, 8, v158
	s_and_saveexec_b64 s[12:13], vcc
	s_xor_b64 s[12:13], exec, s[12:13]
	s_cbranch_execz .LBB0_499
	v_add_u32_e32 v88, 7, v158
	v_ashrrev_i32_e32 v89, 31, v88
	v_lshl_add_u64 v[88:89], s[2:3], 0, v[88:89]
	v_lshlrev_b64 v[88:89], 11, v[88:89]
	v_lshl_add_u64 v[92:93], v[150:151], 0, v[88:89]
	global_load_dwordx4 v[88:91], v[92:93], off offset:1552 nt
	s_nop 0
	global_load_dwordx4 v[92:95], v[92:93], off offset:1536 nt
	s_waitcnt vmcnt(0)
	v_mov_b32_e32 v164, v91
	v_mov_b32_e32 v168, v89
	v_mov_b32_e32 v166, v95
	v_mov_b32_e32 v170, v93
.LBB0_499:
	s_or_saveexec_b64 s[12:13], s[12:13]
	v_mov_b32_e32 v98, 0
	v_mov_b32_e32 v99, 0
	v_mov_b32_e32 v100, 0
	v_mov_b32_e32 v101, 0
	s_xor_b64 exec, exec, s[12:13]
	s_cbranch_execz .LBB0_501
	v_mov_b64_e32 v[88:89], s[86:87]
	v_mad_u64_u32 v[88:89], s[14:15], v162, s89, v[88:89]
	v_mad_i32_i24 v89, v163, s89, v89
	v_mov_b32_e32 v161, v97
	v_lshl_add_u64 v[88:89], v[88:89], 0, v[160:161]
	v_add_co_u32_e32 v88, vcc, 0xfaf3000, v88
	v_mov_b32_e32 v92, 0
	s_nop 0
	v_addc_co_u32_e32 v89, vcc, 0, v89, vcc
	global_load_dwordx4 v[98:101], v[88:89], off offset:1536 nt
	v_mov_b32_e32 v170, 0
	v_mov_b32_e32 v94, v92
	v_mov_b32_e32 v166, v92
	v_mov_b32_e32 v88, v92
	v_mov_b32_e32 v168, v92
	v_mov_b32_e32 v90, v92
	v_mov_b32_e32 v164, v92
; template <int W>
; __device__ __forceinline__ void pool_items(const Params& p, int l, bool sample, int b, int c, int g, long row0, int tid) {
;     ...
; #pragma unroll
;         for (int i = 0; i < W; ++i) {
;             const int tt = t - i;
;             raw[i] = (u32x4){0u, 0u, 0u, 0u}; h0[i] = (f32x4){0.f, 0.f, 0.f, 0.f}; h1[i] = h0[i];
;             if (tt >= 0) raw[i] = *(const u32x4*)(P + (size_t)(prow - i) * INW + 768 + col);
;             else if (sample) { const float* sp = p.state_pool + (((size_t)l * 8 + b) * 15 + (15 + tt)) * 512 + col; h0[i] = *(const f32x4*)sp; h1[i] = *(const f32x4*)(sp + 4); }
.LBB0_501:
	s_or_b64 exec, exec, s[12:13]
	v_cmp_gt_i32_e32 vcc, 9, v158
	s_and_saveexec_b64 s[12:13], vcc
	s_xor_b64 s[12:13], exec, s[12:13]
	s_cbranch_execz .LBB0_503
	v_add_u32_e32 v102, 6, v158
	v_ashrrev_i32_e32 v103, 31, v102
	v_lshl_add_u64 v[102:103], s[2:3], 0, v[102:103]
	v_lshlrev_b64 v[102:103], 11, v[102:103]
	v_lshl_add_u64 v[106:107], v[150:151], 0, v[102:103]
	global_load_dwordx4 v[102:105], v[106:107], off offset:1552 nt
	s_nop 0
	global_load_dwordx4 v[106:109], v[106:107], off offset:1536 nt
	s_waitcnt vmcnt(0)
	v_mov_b32_e32 v165, v105
	v_mov_b32_e32 v91, v104
	v_mov_b32_e32 v169, v103
	v_mov_b32_e32 v89, v102
	v_mov_b32_e32 v167, v109
	v_mov_b32_e32 v95, v108
	v_mov_b32_e32 v171, v107
	v_mov_b32_e32 v93, v106
.LBB0_503:
	s_or_saveexec_b64 s[12:13], s[12:13]
	v_mov_b32_e32 v102, 0
	v_mov_b32_e32 v103, 0
	v_mov_b32_e32 v104, 0
	v_mov_b32_e32 v105, 0
	s_xor_b64 exec, exec, s[12:13]
	s_cbranch_execz .LBB0_505
	v_mov_b64_e32 v[102:103], s[86:87]
	v_mad_u64_u32 v[102:103], s[14:15], v162, s89, v[102:103]
	v_mad_i32_i24 v103, v163, s89, v103
	v_mov_b32_e32 v161, v97
	v_lshl_add_u64 v[102:103], v[102:103], 0, v[160:161]
	v_add_co_u32_e32 v102, vcc, 0xfaf1000, v102
	v_mov_b32_e32 v93, 0
	s_nop 0
	v_addc_co_u32_e32 v103, vcc, 0, v103, vcc
	global_load_dwordx4 v[102:105], v[102:103], off offset:3072 nt
	v_mov_b32_e32 v171, v93
	v_mov_b32_e32 v95, v93
	v_mov_b32_e32 v167, v93
	v_mov_b32_e32 v89, v93
	v_mov_b32_e32 v169, v93
	v_mov_b32_e32 v91, v93
	v_mov_b32_e32 v165, v93
.LBB0_505:
	s_or_b64 exec, exec, s[12:13]
	v_cmp_gt_i32_e32 vcc, 10, v158
	s_and_saveexec_b64 s[12:13], vcc
	s_xor_b64 s[12:13], exec, s[12:13]
	s_cbranch_execz .LBB0_507
	v_add_u32_e32 v106, 5, v158
	v_ashrrev_i32_e32 v107, 31, v106
	v_lshl_add_u64 v[106:107], s[2:3], 0, v[106:107]
	v_lshlrev_b64 v[106:107], 11, v[106:107]
	v_lshl_add_u64 v[110:111], v[150:151], 0, v[106:107]
	global_load_dwordx4 v[106:109], v[110:111], off offset:1552 nt
	s_nop 0
	global_load_dwordx4 v[110:113], v[110:111], off offset:1536 nt
	s_waitcnt vmcnt(0)
	v_mov_b32_e32 v172, v109
	v_mov_b32_e32 v176, v107
	v_mov_b32_e32 v174, v113
	v_mov_b32_e32 v178, v111
.LBB0_507:
	s_or_saveexec_b64 s[12:13], s[12:13]
	v_mov_b32_e32 v114, 0
	v_mov_b32_e32 v115, 0
	v_mov_b32_e32 v116, 0
	v_mov_b32_e32 v117, 0
	s_xor_b64 exec, exec, s[12:13]
	s_cbranch_execz .LBB0_509
	v_mov_b64_e32 v[106:107], s[86:87]
	v_mad_u64_u32 v[106:107], s[14:15], v162, s89, v[106:107]
	v_mad_i32_i24 v107, v163, s89, v107
	v_mov_b32_e32 v161, v97
	v_lshl_add_u64 v[106:107], v[106:107], 0, v[160:161]
	v_add_co_u32_e32 v106, vcc, 0xfaf0000, v106
	v_mov_b32_e32 v110, 0
	s_nop 0
	v_addc_co_u32_e32 v107, vcc, 0, v107, vcc
	global_load_dwordx4 v[114:117], v[106:107], off offset:512 nt
	v_mov_b32_e32 v178, 0
	v_mov_b32_e32 v112, v110
	v_mov_b32_e32 v174, v110
	v_mov_b32_e32 v106, v110
	v_mov_b32_e32 v176, v110
	v_mov_b32_e32 v108, v110
	v_mov_b32_e32 v172, v110
.LBB0_509:
	s_or_b64 exec, exec, s[12:13]
	v_cmp_gt_i32_e32 vcc, 11, v158
	s_and_saveexec_b64 s[12:13], vcc
	s_xor_b64 s[12:13], exec, s[12:13]
	s_cbranch_execz .LBB0_511
	v_add_u32_e32 v118, 4, v158
	v_ashrrev_i32_e32 v119, 31, v118
	v_lshl_add_u64 v[118:119], s[2:3], 0, v[118:119]
	v_lshlrev_b64 v[118:119], 11, v[118:119]
	v_lshl_add_u64 v[122:123], v[150:151], 0, v[118:119]
	global_load_dwordx4 v[118:121], v[122:123], off offset:1552 nt
	s_nop 0
	global_load_dwordx4 v[122:125], v[122:123], off offset:1536 nt
	s_waitcnt vmcnt(0)
	v_mov_b32_e32 v173, v121
	v_mov_b32_e32 v109, v120
	v_mov_b32_e32 v177, v119
	v_mov_b32_e32 v107, v118
	v_mov_b32_e32 v175, v125
	v_mov_b32_e32 v113, v124
	v_mov_b32_e32 v179, v123
	v_mov_b32_e32 v111, v122
.LBB0_511:
	s_or_saveexec_b64 s[12:13], s[12:13]
	v_mov_b32_e32 v118, 0
	v_mov_b32_e32 v119, 0
	v_mov_b32_e32 v120, 0
	v_mov_b32_e32 v121, 0
	s_xor_b64 exec, exec, s[12:13]
	s_cbranch_execz .LBB0_513
	v_mov_b64_e32 v[118:119], s[86:87]
	v_mad_u64_u32 v[118:119], s[14:15], v162, s89, v[118:119]
	v_mad_i32_i24 v119, v163, s89, v119
	v_mov_b32_e32 v161, v97
	v_lshl_add_u64 v[118:119], v[118:119], 0, v[160:161]
	v_add_co_u32_e32 v118, vcc, 0xfaee000, v118
	v_mov_b32_e32 v111, 0
	s_nop 0
	v_addc_co_u32_e32 v119, vcc, 0, v119, vcc
	global_load_dwordx4 v[118:121], v[118:119], off offset:2048 nt
	v_mov_b32_e32 v179, v111
	v_mov_b32_e32 v113, v111
	v_mov_b32_e32 v175, v111
	v_mov_b32_e32 v107, v111
	v_mov_b32_e32 v177, v111
	v_mov_b32_e32 v109, v111
	v_mov_b32_e32 v173, v111
.LBB0_513:
	s_or_b64 exec, exec, s[12:13]
	v_cmp_gt_i32_e32 vcc, 12, v158
	s_and_saveexec_b64 s[12:13], vcc
	s_xor_b64 s[12:13], exec, s[12:13]
	s_cbranch_execz .LBB0_515
	v_add_u32_e32 v122, 3, v158
	v_ashrrev_i32_e32 v123, 31, v122
	v_lshl_add_u64 v[122:123], s[2:3], 0, v[122:123]
	v_lshlrev_b64 v[122:123], 11, v[122:123]
	v_lshl_add_u64 v[126:127], v[150:151], 0, v[122:123]
	global_load_dwordx4 v[122:125], v[126:127], off offset:1552 nt
	s_nop 0
	global_load_dwordx4 v[126:129], v[126:127], off offset:1536 nt
	s_waitcnt vmcnt(0)
	v_mov_b32_e32 v180, v125
	v_mov_b32_e32 v184, v123
	v_mov_b32_e32 v182, v129
	v_mov_b32_e32 v186, v127
; template <int W>
; __device__ __forceinline__ void pool_items(const Params& p, int l, bool sample, int b, int c, int g, long row0, int tid) {
;     ...
; #pragma unroll
;         for (int i = 0; i < W; ++i) {
;             const int tt = t - i;
;             raw[i] = (u32x4){0u, 0u, 0u, 0u}; h0[i] = (f32x4){0.f, 0.f, 0.f, 0.f}; h1[i] = h0[i];
;             if (tt >= 0) raw[i] = *(const u32x4*)(P + (size_t)(prow - i) * INW + 768 + col);
;             else if (sample) { const float* sp = p.state_pool + (((size_t)l * 8 + b) * 15 + (15 + tt)) * 512 + col; h0[i] = *(const f32x4*)sp; h1[i] = *(const f32x4*)(sp + 4); }
.LBB0_515:
	s_or_saveexec_b64 s[12:13], s[12:13]
	v_mov_b32_e32 v130, 0
	v_mov_b32_e32 v131, 0
	v_mov_b32_e32 v132, 0
	v_mov_b32_e32 v133, 0
	s_xor_b64 exec, exec, s[12:13]
	s_cbranch_execz .LBB0_517
	v_mov_b64_e32 v[122:123], s[86:87]
	v_mad_u64_u32 v[122:123], s[14:15], v162, s89, v[122:123]
	v_mad_i32_i24 v123, v163, s89, v123
	v_mov_b32_e32 v161, v97
	v_lshl_add_u64 v[122:123], v[122:123], 0, v[160:161]
	v_add_co_u32_e32 v122, vcc, 0xfaec000, v122
	v_mov_b32_e32 v126, 0
	s_nop 0
	v_addc_co_u32_e32 v123, vcc, 0, v123, vcc
	global_load_dwordx4 v[130:133], v[122:123], off offset:3584 nt
	v_mov_b32_e32 v186, 0
	v_mov_b32_e32 v128, v126
	v_mov_b32_e32 v182, v126
	v_mov_b32_e32 v122, v126
	v_mov_b32_e32 v184, v126
	v_mov_b32_e32 v124, v126
	v_mov_b32_e32 v180, v126
.LBB0_517:
	s_or_b64 exec, exec, s[12:13]
	v_cmp_gt_i32_e32 vcc, 13, v158
	s_and_saveexec_b64 s[12:13], vcc
	s_xor_b64 s[12:13], exec, s[12:13]
	s_cbranch_execz .LBB0_519
	v_add_u32_e32 v134, 2, v158
	v_ashrrev_i32_e32 v135, 31, v134
	v_lshl_add_u64 v[134:135], s[2:3], 0, v[134:135]
	v_lshlrev_b64 v[134:135], 11, v[134:135]
	v_lshl_add_u64 v[138:139], v[150:151], 0, v[134:135]
	global_load_dwordx4 v[134:137], v[138:139], off offset:1552 nt
	s_nop 0
	global_load_dwordx4 v[138:141], v[138:139], off offset:1536 nt
	s_waitcnt vmcnt(0)
	v_mov_b32_e32 v181, v137
	v_mov_b32_e32 v125, v136
	v_mov_b32_e32 v185, v135
	v_mov_b32_e32 v123, v134
	v_mov_b32_e32 v183, v141
	v_mov_b32_e32 v129, v140
	v_mov_b32_e32 v187, v139
	v_mov_b32_e32 v127, v138
.LBB0_519:
	s_or_saveexec_b64 s[12:13], s[12:13]
	v_mov_b32_e32 v134, 0
	v_mov_b32_e32 v135, 0
	v_mov_b32_e32 v136, 0
	v_mov_b32_e32 v137, 0
	s_xor_b64 exec, exec, s[12:13]
	s_cbranch_execz .LBB0_521
	v_mov_b64_e32 v[134:135], s[86:87]
	v_mad_u64_u32 v[134:135], s[14:15], v162, s89, v[134:135]
	v_mad_i32_i24 v135, v163, s89, v135
	v_mov_b32_e32 v161, v97
	v_lshl_add_u64 v[134:135], v[134:135], 0, v[160:161]
	v_add_co_u32_e32 v134, vcc, 0xfaeb000, v134
	v_mov_b32_e32 v127, 0
	s_nop 0
	v_addc_co_u32_e32 v135, vcc, 0, v135, vcc
	global_load_dwordx4 v[134:137], v[134:135], off offset:1024 nt
	v_mov_b32_e32 v187, v127
	v_mov_b32_e32 v129, v127
	v_mov_b32_e32 v183, v127
	v_mov_b32_e32 v123, v127
	v_mov_b32_e32 v185, v127
	v_mov_b32_e32 v125, v127
	v_mov_b32_e32 v181, v127
.LBB0_521:
	s_or_b64 exec, exec, s[12:13]
	v_cmp_gt_i32_e32 vcc, 14, v158
	s_and_saveexec_b64 s[12:13], vcc
	s_xor_b64 s[12:13], exec, s[12:13]
	s_cbranch_execz .LBB0_523
	v_add_u32_e32 v138, 1, v158
	v_ashrrev_i32_e32 v139, 31, v138
	v_lshl_add_u64 v[138:139], s[2:3], 0, v[138:139]
	v_lshlrev_b64 v[138:139], 11, v[138:139]
	v_lshl_add_u64 v[142:143], v[150:151], 0, v[138:139]
	global_load_dwordx4 v[138:141], v[142:143], off offset:1552 nt
	s_nop 0
	global_load_dwordx4 v[142:145], v[142:143], off offset:1536 nt
	s_waitcnt vmcnt(0)
	v_mov_b32_e32 v188, v141
	v_mov_b32_e32 v192, v139
	v_mov_b32_e32 v190, v145
	v_mov_b32_e32 v206, v143
.LBB0_523:
	s_or_saveexec_b64 s[12:13], s[12:13]
	v_mov_b32_e32 v146, 0
	v_mov_b32_e32 v147, 0
	v_mov_b32_e32 v148, 0
	v_mov_b32_e32 v149, 0
	s_xor_b64 exec, exec, s[12:13]
	s_cbranch_execz .LBB0_525
	v_mov_b64_e32 v[138:139], s[86:87]
	v_mad_u64_u32 v[138:139], s[14:15], v162, s89, v[138:139]
	v_mad_i32_i24 v139, v163, s89, v139
	v_mov_b32_e32 v161, v97
	v_lshl_add_u64 v[138:139], v[138:139], 0, v[160:161]
	v_add_co_u32_e32 v138, vcc, 0xfae9000, v138
	v_mov_b32_e32 v142, 0
	s_nop 0
	v_addc_co_u32_e32 v139, vcc, 0, v139, vcc
	global_load_dwordx4 v[146:149], v[138:139], off offset:2560 nt
	v_mov_b32_e32 v206, 0
	v_mov_b32_e32 v144, v142
	v_mov_b32_e32 v190, v142
	v_mov_b32_e32 v138, v142
	v_mov_b32_e32 v192, v142
	v_mov_b32_e32 v140, v142
	v_mov_b32_e32 v188, v142
.LBB0_525:
	s_or_b64 exec, exec, s[12:13]
	v_cmp_gt_i32_e32 vcc, 15, v158
	s_and_saveexec_b64 s[12:13], vcc
	s_xor_b64 s[12:13], exec, s[12:13]
	s_cbranch_execz .LBB0_527
	v_lshl_add_u64 v[152:153], s[2:3], 0, v[158:159]
	v_lshlrev_b64 v[152:153], 11, v[152:153]
	v_lshl_add_u64 v[154:155], v[150:151], 0, v[152:153]
	global_load_dwordx4 v[150:153], v[154:155], off offset:1552 nt
	s_nop 0
	global_load_dwordx4 v[154:157], v[154:155], off offset:1536 nt
	s_waitcnt vmcnt(0)
	v_mov_b32_e32 v189, v153
	v_mov_b32_e32 v141, v152
	v_mov_b32_e32 v193, v151
	v_mov_b32_e32 v139, v150
	v_mov_b32_e32 v191, v157
	v_mov_b32_e32 v145, v156
	v_mov_b32_e32 v207, v155
	v_mov_b32_e32 v143, v154
.LBB0_527:
	s_or_saveexec_b64 s[12:13], s[12:13]
	v_mov_b32_e32 v154, 0
	v_mov_b32_e32 v155, 0
	v_mov_b32_e32 v156, 0
	v_mov_b32_e32 v157, 0
	s_xor_b64 exec, exec, s[12:13]
	s_cbranch_execz .LBB0_529
	v_mov_b64_e32 v[150:151], s[86:87]
	v_mad_u64_u32 v[150:151], s[14:15], v162, s89, v[150:151]
	v_mad_i32_i24 v151, v163, s89, v151
	v_mov_b32_e32 v161, v97
	v_lshl_add_u64 v[150:151], v[150:151], 0, v[160:161]
	v_add_co_u32_e32 v150, vcc, 0xfae8000, v150
	v_mov_b32_e32 v143, 0
	s_nop 0
	v_addc_co_u32_e32 v151, vcc, 0, v151, vcc
	global_load_dwordx4 v[154:157], v[150:151], off nt
	v_mov_b32_e32 v207, v143
	v_mov_b32_e32 v145, v143
	v_mov_b32_e32 v191, v143
	v_mov_b32_e32 v139, v143
	v_mov_b32_e32 v193, v143
	v_mov_b32_e32 v141, v143
	v_mov_b32_e32 v189, v143

; template <int W>
; __device__ __forceinline__ void pool_items(const Params& p, int l, bool sample, int b, int c, int g, long row0, int tid) {
;     ...
;     for (int it = tid; it < nitems; it += 512) {
;         const int tl = it >> 4, ch = it & 15, col = g * 128 + ch * 8;
;         const long prow = row0 + tl; const int t = sample ? tl : c * 64 + tl;
;         u32x4 raw[W]; f32x4 h0[W], h1[W];
; #pragma unroll
;         for (int i = 0; i < W; ++i) {
;             const int tt = t - i;
;             raw[i] = (u32x4){0u, 0u, 0u, 0u}; h0[i] = (f32x4){0.f, 0.f, 0.f, 0.f}; h1[i] = h0[i];
;             if (tt >= 0) raw[i] = *(const u32x4*)(P + (size_t)(prow - i) * INW + 768 + col);
;             else if (sample) { const float* sp = p.state_pool + (((size_t)l * 8 + b) * 15 + (15 + tt)) * 512 + col; h0[i] = *(const f32x4*)sp; h1[i] = *(const f32x4*)(sp + 4); }
.LBB0_537:
	v_ashrrev_i32_e32 v36, 4, v51
	v_and_b32_e32 v8, 0x78, v50
	v_or_b32_e32 v1, 0x80, v8
	v_ashrrev_i32_e32 v37, 31, v36
	v_lshl_add_u64 v[40:41], s[40:41], 0, v[36:37]
	v_cmp_lt_i32_e32 vcc, -1, v36
	v_mov_b32_e32 v0, 0
	v_lshlrev_b32_e32 v38, 1, v1
	v_mov_b32_e32 v1, 0
	v_mov_b32_e32 v2, 0
	v_mov_b32_e32 v3, 0
	s_and_saveexec_b64 s[0:1], vcc
	s_cbranch_execz .LBB0_539
	v_mov_b64_e32 v[0:1], s[86:87]
	v_mad_u64_u32 v[0:1], s[14:15], v40, s89, v[0:1]
	v_mad_i32_i24 v1, v41, s89, v1
	v_mov_b32_e32 v39, v97
	v_lshl_add_u64 v[0:1], v[0:1], 0, v[38:39]
	v_add_co_u32_e32 v0, vcc, 0xfb00000, v0
	s_nop 1
	v_addc_co_u32_e32 v1, vcc, 0, v1, vcc
	global_load_dwordx4 v[0:3], v[0:1], off offset:1536 nt
.LBB0_539:
	s_or_b64 exec, exec, s[0:1]
	v_cmp_lt_i32_e64 s[0:1], 0, v36
	s_and_saveexec_b64 s[14:15], s[0:1]
	s_xor_b64 s[14:15], exec, s[14:15]
	s_cbranch_execz .LBB0_541
	v_mov_b64_e32 v[4:5], s[86:87]
	v_mad_u64_u32 v[4:5], s[16:17], v40, s89, v[4:5]
	v_mad_i32_i24 v5, v41, s89, v5
	v_mov_b32_e32 v39, v97
	v_lshl_add_u64 v[4:5], v[4:5], 0, v[38:39]
	v_add_co_u32_e32 v4, vcc, 0xfafe000, v4
	s_nop 1
	v_addc_co_u32_e32 v5, vcc, 0, v5, vcc
	global_load_dwordx4 v[4:7], v[4:5], off offset:3072 nt
.LBB0_541:
	s_or_saveexec_b64 s[14:15], s[14:15]
	v_readlane_b32 s64, v249, 4
	v_lshlrev_b32_e32 v96, 2, v8
	v_readlane_b32 s72, v249, 12
	v_readlane_b32 s73, v249, 13
	v_mov_b32_e32 v8, 0
	v_mov_b32_e32 v9, 0
	v_lshl_add_u64 v[28:29], s[72:73], 0, v[96:97]
	v_mov_b32_e32 v10, 0
	v_mov_b32_e32 v11, 0
	v_mov_b32_e32 v12, 0
	v_mov_b32_e32 v13, 0
	v_mov_b32_e32 v14, 0
	v_mov_b32_e32 v15, 0
	v_readlane_b32 s65, v249, 5
	v_readlane_b32 s66, v249, 6
	v_readlane_b32 s67, v249, 7
	v_readlane_b32 s68, v249, 8
	v_readlane_b32 s69, v249, 9
	v_readlane_b32 s70, v249, 10
	v_readlane_b32 s71, v249, 11
	v_readlane_b32 s74, v249, 14
	v_readlane_b32 s75, v249, 15
	v_readlane_b32 s76, v249, 16
	v_readlane_b32 s77, v249, 17
	v_readlane_b32 s78, v249, 18
	v_readlane_b32 s79, v249, 19
	s_xor_b64 exec, exec, s[14:15]
	s_cbranch_execz .LBB0_543
	s_waitcnt vmcnt(0) lgkmcnt(0)
	v_add_u32_e32 v4, 14, v36
	v_ashrrev_i32_e32 v5, 31, v4
	v_lshl_add_u64 v[4:5], s[2:3], 0, v[4:5]
	v_lshlrev_b64 v[4:5], 11, v[4:5]
	v_lshl_add_u64 v[4:5], v[28:29], 0, v[4:5]
	global_load_dwordx4 v[8:11], v[4:5], off offset:512 nt
	global_load_dwordx4 v[12:15], v[4:5], off offset:528 nt
	v_mov_b32_e32 v4, 0
	v_mov_b32_e32 v5, v4
	v_mov_b32_e32 v6, v4
	v_mov_b32_e32 v7, v4
.LBB0_543:
	s_or_b64 exec, exec, s[14:15]
	v_cmp_gt_i32_e32 vcc, 2, v36
	s_and_saveexec_b64 s[14:15], vcc
	s_xor_b64 s[14:15], exec, s[14:15]
	s_cbranch_execz .LBB0_545
	v_add_u32_e32 v16, 13, v36
	v_ashrrev_i32_e32 v17, 31, v16
	v_lshl_add_u64 v[16:17], s[2:3], 0, v[16:17]
	v_lshlrev_b64 v[16:17], 11, v[16:17]
	v_lshl_add_u64 v[20:21], v[28:29], 0, v[16:17]
	global_load_dwordx4 v[16:19], v[20:21], off offset:528 nt
	s_nop 0
	global_load_dwordx4 v[20:23], v[20:21], off offset:512 nt
	s_waitcnt vmcnt(0)
	v_mov_b32_e32 v42, v19
	v_mov_b32_e32 v46, v17
	v_mov_b32_e32 v44, v23
	v_mov_b32_e32 v48, v21
.LBB0_545:
	s_or_saveexec_b64 s[14:15], s[14:15]
	v_mov_b32_e32 v24, 0
	v_mov_b32_e32 v25, 0
	v_mov_b32_e32 v26, 0
	v_mov_b32_e32 v27, 0
	s_xor_b64 exec, exec, s[14:15]
	s_cbranch_execz .LBB0_547
	v_mov_b64_e32 v[16:17], s[86:87]
	v_mad_u64_u32 v[16:17], s[16:17], v40, s89, v[16:17]
	v_mad_i32_i24 v17, v41, s89, v17
	v_mov_b32_e32 v39, v97
	v_lshl_add_u64 v[16:17], v[16:17], 0, v[38:39]
	v_add_co_u32_e32 v16, vcc, 0xfafd000, v16
	v_mov_b32_e32 v20, 0
	s_nop 0
	v_addc_co_u32_e32 v17, vcc, 0, v17, vcc
	global_load_dwordx4 v[24:27], v[16:17], off offset:512 nt
	v_mov_b32_e32 v48, 0
	v_mov_b32_e32 v22, v20
	v_mov_b32_e32 v44, v20
	v_mov_b32_e32 v16, v20
	v_mov_b32_e32 v46, v20
	v_mov_b32_e32 v18, v20
	v_mov_b32_e32 v42, v20
.LBB0_547:
	s_or_b64 exec, exec, s[14:15]
	v_cmp_gt_i32_e32 vcc, 3, v36
	s_and_saveexec_b64 s[14:15], vcc
	s_xor_b64 s[14:15], exec, s[14:15]
	s_cbranch_execz .LBB0_549
	v_add_u32_e32 v30, 12, v36
	v_ashrrev_i32_e32 v31, 31, v30
	v_lshl_add_u64 v[30:31], s[2:3], 0, v[30:31]
	v_lshlrev_b64 v[30:31], 11, v[30:31]
	v_lshl_add_u64 v[32:33], v[28:29], 0, v[30:31]
	global_load_dwordx4 v[28:31], v[32:33], off offset:528 nt
	s_nop 0
	global_load_dwordx4 v[32:35], v[32:33], off offset:512 nt
	s_waitcnt vmcnt(0)
	v_mov_b32_e32 v43, v31
	v_mov_b32_e32 v19, v30
	v_mov_b32_e32 v47, v29
	v_mov_b32_e32 v17, v28
	v_mov_b32_e32 v45, v35
	v_mov_b32_e32 v23, v34
	v_mov_b32_e32 v49, v33
	v_mov_b32_e32 v21, v32
.LBB0_549:
	s_or_saveexec_b64 s[14:15], s[14:15]
	v_mov_b32_e32 v32, 0
	v_mov_b32_e32 v33, 0
	v_mov_b32_e32 v34, 0
	v_mov_b32_e32 v35, 0
	s_xor_b64 exec, exec, s[14:15]
	s_cbranch_execz .LBB0_551
	v_mov_b64_e32 v[28:29], s[86:87]
	v_mad_u64_u32 v[28:29], s[16:17], v40, s89, v[28:29]
	v_mad_i32_i24 v29, v41, s89, v29
	v_mov_b32_e32 v39, v97
	v_lshl_add_u64 v[28:29], v[28:29], 0, v[38:39]
	v_add_co_u32_e32 v28, vcc, 0xfafb000, v28
	v_mov_b32_e32 v21, 0
	s_nop 0
	v_addc_co_u32_e32 v29, vcc, 0, v29, vcc
	global_load_dwordx4 v[32:35], v[28:29], off offset:2048 nt
	v_mov_b32_e32 v49, v21
	v_mov_b32_e32 v23, v21
	v_mov_b32_e32 v45, v21
	v_mov_b32_e32 v17, v21
	v_mov_b32_e32 v47, v21
	v_mov_b32_e32 v19, v21
	v_mov_b32_e32 v43, v21

; __device__ __forceinline__ void attn_unit(const Params& p, int l, LAS unsigned char* lds, bool sample, int b, int c, int kvh) {
;     ...
;     const int gq = wid >> 1, half = wid & 1, h = kvh * 4 + gq;
;     const bool active = !sample || half == 0;
;     const int tq = half * 32 + q32;
;     const long qrow = sample ? row0 + (q32 & 15) : row0 + tq;
;     u32x4 qraw[4];
; #pragma unroll
;     for (int d0 = 0; d0 < 4; ++d0) qraw[d0] = *(const u32x4*)(P + (size_t)qrow * INW + h * 64 + d0 * 16 + hi * 8);
;     u32x4 kraw[3], vraw[3]; f32x4 kc0[3], kc1[3], vc0[3], vc1[3];
; #pragma unroll
;     for (int it = 0; it < 3; ++it) {
;         const int idx = it * 512 + tid, j = idx >> 3, ch = idx & 7;
;         kraw[it] = (u32x4){0u, 0u, 0u, 0u}; vraw[it] = kraw[it];
;         kc0[it] = (f32x4){0.f, 0.f, 0.f, 0.f}; kc1[it] = kc0[it]; vc0[it] = kc0[it]; vc1[it] = kc0[it];
;         if (!sample) { const int tk = c * 64 - 128 + j;
;             if (tk >= 0) { const size_t o = (size_t)((long)b * SEQ + tk) * INW + kvh * 64 + ch * 8; kraw[it] = *(const u32x4*)(P + o + 512); vraw[it] = *(const u32x4*)(P + o + 640); } }
;         else if (j < 128) { const size_t ci = ((((size_t)l * 8 + b) * 128 + j) * 2 + kvh) * 64 + ch * 8;
;             kc0[it] = *(const f32x4*)(p.cache_k + ci); kc1[it] = *(const f32x4*)(p.cache_k + ci + 4); vc0[it] = *(const f32x4*)(p.cache_v + ci); vc1[it] = *(const f32x4*)(p.cache_v + ci + 4); }
;         else if (j < 144) { const size_t o = (size_t)((long)MP + b * 16 + (j - 128)) * INW + kvh * 64 + ch * 8; kraw[it] = *(const u32x4*)(P + o + 512); vraw[it] = *(const u32x4*)(P + o + 640); }
.LBB0_554:
	s_and_b32 s12, s23, 1
	v_ashrrev_i32_e32 v110, 5, v208
	s_ashr_i32 s7, s25, 7
	s_lshl_b32 s0, s12, 2
	s_add_i32 s7, s7, s0
	v_and_or_b32 v2, v208, 15, s40
	v_mov_b64_e32 v[0:1], s[84:85]
	v_mad_u64_u32 v[0:1], s[0:1], v2, s89, v[0:1]
	s_lshl_b32 s2, s7, 6
	v_mad_i32_i24 v1, s41, v227, v1
	s_ashr_i32 s3, s2, 31
	v_lshlrev_b32_e32 v88, 3, v110
	v_lshl_add_u64 v[0:1], s[2:3], 1, v[0:1]
	v_ashrrev_i32_e32 v89, 31, v88
	v_lshl_add_u64 v[0:1], v[88:89], 1, v[0:1]
	global_load_dwordx4 v[12:15], v[0:1], off nt
	global_load_dwordx4 v[8:11], v[0:1], off offset:32 nt
	global_load_dwordx4 v[4:7], v[0:1], off offset:64 nt
	s_nop 0
	global_load_dwordx4 v[0:3], v[0:1], off offset:96 nt
	v_lshlrev_b32_e32 v16, 3, v209
	s_lshl_b32 s0, s12, 7
	v_and_b32_e32 v98, 56, v16
	s_add_u32 s0, s84, s0
	s_addc_u32 s1, s85, 0
	v_lshlrev_b32_e32 v96, 1, v98
	v_lshl_add_u64 v[16:17], s[0:1], 0, v[96:97]
	v_ashrrev_i32_e32 v94, 3, v209
	s_movk_i32 s0, 0x7f
	v_cmp_lt_i32_e32 vcc, s0, v94
	s_and_saveexec_b64 s[0:1], vcc
	s_xor_b64 s[0:1], exec, s[0:1]
	s_cbranch_execz .LBB0_558
	v_cmp_gt_u32_e32 vcc, s83, v94
	v_mov_b32_e32 v87, 0
	v_mov_b32_e32 v86, 0
	v_mov_b32_e32 v85, 0
	v_mov_b32_e32 v84, 0
	v_mov_b32_e32 v83, 0
	v_mov_b32_e32 v82, 0
	v_mov_b32_e32 v81, 0
	v_mov_b32_e32 v80, 0
	s_and_saveexec_b64 s[10:11], vcc
	s_cbranch_execz .LBB0_557
	v_add_u32_e32 v96, 0xffffff80, v94
	v_lshl_add_u64 v[18:19], s[40:41], 0, v[96:97]
	v_mad_u64_u32 v[20:21], s[14:15], v18, s89, v[16:17]
	v_mad_i32_i24 v21, v19, s89, v21
	global_load_dwordx4 v[84:87], v[20:21], off offset:1024 nt
	global_load_dwordx4 v[80:83], v[20:21], off offset:1280 nt

; __device__ __forceinline__ void attn_unit(const Params& p, int l, LAS unsigned char* lds, bool sample, int b, int c, int kvh) {
;     ...
;     for (int it = 0; it < 3; ++it) {
;         const int idx = it * 512 + tid, j = idx >> 3, ch = idx & 7;
;         kraw[it] = (u32x4){0u, 0u, 0u, 0u}; vraw[it] = kraw[it];
;         kc0[it] = (f32x4){0.f, 0.f, 0.f, 0.f}; kc1[it] = kc0[it]; vc0[it] = kc0[it]; vc1[it] = kc0[it];
;         if (!sample) { const int tk = c * 64 - 128 + j;
;             if (tk >= 0) { const size_t o = (size_t)((long)b * SEQ + tk) * INW + kvh * 64 + ch * 8; kraw[it] = *(const u32x4*)(P + o + 512); vraw[it] = *(const u32x4*)(P + o + 640); } }
;         else if (j < 128) { const size_t ci = ((((size_t)l * 8 + b) * 128 + j) * 2 + kvh) * 64 + ch * 8;
;             kc0[it] = *(const f32x4*)(p.cache_k + ci); kc1[it] = *(const f32x4*)(p.cache_k + ci + 4); vc0[it] = *(const f32x4*)(p.cache_v + ci); vc1[it] = *(const f32x4*)(p.cache_v + ci + 4); }
;         else if (j < 144) { const size_t o = (size_t)((long)MP + b * 16 + (j - 128)) * INW + kvh * 64 + ch * 8; kraw[it] = *(const u32x4*)(P + o + 512); vraw[it] = *(const u32x4*)(P + o + 640); }
.LBB0_558:
	s_or_saveexec_b64 s[0:1], s[0:1]
	s_lshl_b32 s96, s12, 6
	v_mov_b32_e32 v60, 0
	v_mov_b32_e32 v61, 0
	v_mov_b32_e32 v62, 0
	v_mov_b32_e32 v63, 0
	v_mov_b32_e32 v68, 0
	v_mov_b32_e32 v69, 0
	v_mov_b32_e32 v70, 0
	v_mov_b32_e32 v71, 0
	v_mov_b32_e32 v56, 0
	v_mov_b32_e32 v57, 0
	v_mov_b32_e32 v58, 0
	v_mov_b32_e32 v59, 0
	v_mov_b32_e32 v64, 0
	v_mov_b32_e32 v65, 0
	v_mov_b32_e32 v66, 0
	v_mov_b32_e32 v67, 0
	s_xor_b64 exec, exec, s[0:1]
	s_cbranch_execz .LBB0_560
	v_ashrrev_i32_e32 v95, 31, v94
	s_lshl_b64 s[10:11], s[8:9], 14
	v_lshlrev_b64 v[18:19], 7, v[94:95]
	s_or_b64 s[10:11], s[10:11], s[96:97]
	v_lshl_add_u64 v[18:19], s[10:11], 0, v[18:19]
	v_or_b32_e32 v18, v18, v98
	v_readlane_b32 s64, v249, 4
	v_lshlrev_b64 v[18:19], 2, v[18:19]
	v_readlane_b32 s68, v249, 8
	v_readlane_b32 s69, v249, 9
	v_readlane_b32 s70, v249, 10
	v_readlane_b32 s71, v249, 11
	v_lshl_add_u64 v[20:21], s[68:69], 0, v[18:19]
	global_load_dwordx4 v[56:59], v[20:21], off offset:16 nt
	global_load_dwordx4 v[64:67], v[20:21], off nt
	v_lshl_add_u64 v[18:19], s[70:71], 0, v[18:19]
	global_load_dwordx4 v[60:63], v[18:19], off offset:16 nt
	global_load_dwordx4 v[68:71], v[18:19], off nt
	s_waitcnt vmcnt(0) lgkmcnt(0)
	v_mov_b32_e32 v80, 0
	v_mov_b32_e32 v81, 0
	v_mov_b32_e32 v82, 0
	v_mov_b32_e32 v83, 0
	v_mov_b32_e32 v84, 0
	v_mov_b32_e32 v85, 0
	v_mov_b32_e32 v86, 0
	v_mov_b32_e32 v87, 0
	v_readlane_b32 s65, v249, 5
	v_readlane_b32 s66, v249, 6
	v_readlane_b32 s67, v249, 7
	v_readlane_b32 s72, v249, 12
	v_readlane_b32 s73, v249, 13
	v_readlane_b32 s74, v249, 14
	v_readlane_b32 s75, v249, 15
	v_readlane_b32 s76, v249, 16
	v_readlane_b32 s77, v249, 17
	v_readlane_b32 s78, v249, 18
	v_readlane_b32 s79, v249, 19
.LBB0_560:
	s_or_b64 exec, exec, s[0:1]
	v_add_u32_e32 v18, 0x200, v209
	v_ashrrev_i32_e32 v92, 3, v18
	s_movk_i32 s0, 0x7f
	v_cmp_lt_i32_e32 vcc, s0, v92
	s_and_saveexec_b64 s[0:1], vcc
	s_xor_b64 s[0:1], exec, s[0:1]
	s_cbranch_execz .LBB0_564
	v_cmp_gt_u32_e32 vcc, s83, v92
	v_mov_b32_e32 v79, 0
	v_mov_b32_e32 v78, 0
	v_mov_b32_e32 v77, 0
	v_mov_b32_e32 v76, 0
	v_mov_b32_e32 v75, 0
	v_mov_b32_e32 v74, 0
	v_mov_b32_e32 v73, 0
	v_mov_b32_e32 v72, 0
	s_and_saveexec_b64 s[10:11], vcc
	s_cbranch_execz .LBB0_563
	v_add_u32_e32 v96, 0xffffff80, v92
	v_lshl_add_u64 v[18:19], s[40:41], 0, v[96:97]
	v_mad_u64_u32 v[20:21], s[14:15], v18, s89, v[16:17]
	v_mad_i32_i24 v21, v19, s89, v21
	global_load_dwordx4 v[76:79], v[20:21], off offset:1024 nt
	global_load_dwordx4 v[72:75], v[20:21], off offset:1280 nt

; __device__ __forceinline__ void attn_unit(const Params& p, int l, LAS unsigned char* lds, bool sample, int b, int c, int kvh) {
;     ...
;     for (int it = 0; it < 3; ++it) {
;         const int idx = it * 512 + tid, j = idx >> 3, ch = idx & 7;
;         kraw[it] = (u32x4){0u, 0u, 0u, 0u}; vraw[it] = kraw[it];
;         kc0[it] = (f32x4){0.f, 0.f, 0.f, 0.f}; kc1[it] = kc0[it]; vc0[it] = kc0[it]; vc1[it] = kc0[it];
;         if (!sample) { const int tk = c * 64 - 128 + j;
;             if (tk >= 0) { const size_t o = (size_t)((long)b * SEQ + tk) * INW + kvh * 64 + ch * 8; kraw[it] = *(const u32x4*)(P + o + 512); vraw[it] = *(const u32x4*)(P + o + 640); } }
;         else if (j < 128) { const size_t ci = ((((size_t)l * 8 + b) * 128 + j) * 2 + kvh) * 64 + ch * 8;
;             kc0[it] = *(const f32x4*)(p.cache_k + ci); kc1[it] = *(const f32x4*)(p.cache_k + ci + 4); vc0[it] = *(const f32x4*)(p.cache_v + ci); vc1[it] = *(const f32x4*)(p.cache_v + ci + 4); }
;         else if (j < 144) { const size_t o = (size_t)((long)MP + b * 16 + (j - 128)) * INW + kvh * 64 + ch * 8; kraw[it] = *(const u32x4*)(P + o + 512); vraw[it] = *(const u32x4*)(P + o + 640); }
.LBB0_564:
	s_or_saveexec_b64 s[0:1], s[0:1]
	v_mov_b32_e32 v40, 0
	v_mov_b32_e32 v41, 0
	v_mov_b32_e32 v42, 0
	v_mov_b32_e32 v43, 0
	v_mov_b32_e32 v44, 0
	v_mov_b32_e32 v45, 0
	v_mov_b32_e32 v46, 0
	v_mov_b32_e32 v47, 0
	v_mov_b32_e32 v32, 0
	v_mov_b32_e32 v33, 0
	v_mov_b32_e32 v34, 0
	v_mov_b32_e32 v35, 0
	v_mov_b32_e32 v36, 0
	v_mov_b32_e32 v37, 0
	v_mov_b32_e32 v38, 0
	v_mov_b32_e32 v39, 0
	s_xor_b64 exec, exec, s[0:1]
	s_cbranch_execz .LBB0_566
	v_ashrrev_i32_e32 v93, 31, v92
	s_lshl_b64 s[10:11], s[8:9], 14
	v_mov_b32_e32 v20, s96
	v_lshlrev_b64 v[18:19], 7, v[92:93]
	v_or3_b32 v21, s11, 0, 0
	v_or3_b32 v20, s10, v20, v98
	v_lshl_add_u64 v[18:19], v[20:21], 0, v[18:19]
	v_readlane_b32 s64, v249, 4
	v_lshlrev_b64 v[18:19], 2, v[18:19]
	v_readlane_b32 s68, v249, 8
	v_readlane_b32 s69, v249, 9
	v_readlane_b32 s70, v249, 10
	v_readlane_b32 s71, v249, 11
	v_lshl_add_u64 v[20:21], s[68:69], 0, v[18:19]
	global_load_dwordx4 v[32:35], v[20:21], off offset:16 nt
	global_load_dwordx4 v[36:39], v[20:21], off nt
	v_lshl_add_u64 v[18:19], s[70:71], 0, v[18:19]
	global_load_dwordx4 v[40:43], v[18:19], off offset:16 nt
	global_load_dwordx4 v[44:47], v[18:19], off nt
	s_waitcnt vmcnt(0) lgkmcnt(0)
	v_mov_b32_e32 v72, 0
	v_mov_b32_e32 v73, v72
	v_mov_b32_e32 v74, v72
	v_mov_b32_e32 v75, v72
	v_mov_b32_e32 v76, v72
	v_mov_b32_e32 v77, v72
	v_mov_b32_e32 v78, v72
	v_mov_b32_e32 v79, v72
	v_readlane_b32 s65, v249, 5
	v_readlane_b32 s66, v249, 6
	v_readlane_b32 s67, v249, 7
	v_readlane_b32 s72, v249, 12
	v_readlane_b32 s73, v249, 13
	v_readlane_b32 s74, v249, 14
	v_readlane_b32 s75, v249, 15
	v_readlane_b32 s76, v249, 16
	v_readlane_b32 s77, v249, 17
	v_readlane_b32 s78, v249, 18
	v_readlane_b32 s79, v249, 19
.LBB0_566:
	s_or_b64 exec, exec, s[0:1]
	v_add_u32_e32 v18, 0x400, v209
	v_ashrrev_i32_e32 v90, 3, v18
	s_movk_i32 s0, 0x7f
	v_cmp_lt_i32_e32 vcc, s0, v90
	s_and_saveexec_b64 s[0:1], vcc
	s_xor_b64 s[0:1], exec, s[0:1]
	s_cbranch_execz .LBB0_570
	v_cmp_gt_u32_e32 vcc, s83, v90
	v_mov_b32_e32 v55, 0
	v_mov_b32_e32 v54, 0
	v_mov_b32_e32 v53, 0
	v_mov_b32_e32 v52, 0
	v_mov_b32_e32 v51, 0
	v_mov_b32_e32 v50, 0
	v_mov_b32_e32 v49, 0
	v_mov_b32_e32 v48, 0
	s_and_saveexec_b64 s[10:11], vcc
	s_cbranch_execz .LBB0_569
	v_add_u32_e32 v96, 0xffffff80, v90
	v_lshl_add_u64 v[18:19], s[40:41], 0, v[96:97]
	v_mad_u64_u32 v[16:17], s[14:15], v18, s89, v[16:17]
	v_mad_i32_i24 v17, v19, s89, v17
	global_load_dwordx4 v[52:55], v[16:17], off offset:1024 nt
	global_load_dwordx4 v[48:51], v[16:17], off offset:1280 nt

; __device__ __forceinline__ void attn_unit(const Params& p, int l, LAS unsigned char* lds, bool sample, int b, int c, int kvh) {
;     ...
;     for (int it = 0; it < 3; ++it) {
;         const int idx = it * 512 + tid, j = idx >> 3, ch = idx & 7;
;         kraw[it] = (u32x4){0u, 0u, 0u, 0u}; vraw[it] = kraw[it];
;         kc0[it] = (f32x4){0.f, 0.f, 0.f, 0.f}; kc1[it] = kc0[it]; vc0[it] = kc0[it]; vc1[it] = kc0[it];
;         if (!sample) { const int tk = c * 64 - 128 + j;
;             if (tk >= 0) { const size_t o = (size_t)((long)b * SEQ + tk) * INW + kvh * 64 + ch * 8; kraw[it] = *(const u32x4*)(P + o + 512); vraw[it] = *(const u32x4*)(P + o + 640); } }
;         else if (j < 128) { const size_t ci = ((((size_t)l * 8 + b) * 128 + j) * 2 + kvh) * 64 + ch * 8;
;             kc0[it] = *(const f32x4*)(p.cache_k + ci); kc1[it] = *(const f32x4*)(p.cache_k + ci + 4); vc0[it] = *(const f32x4*)(p.cache_v + ci); vc1[it] = *(const f32x4*)(p.cache_v + ci + 4); }
;         else if (j < 144) { const size_t o = (size_t)((long)MP + b * 16 + (j - 128)) * INW + kvh * 64 + ch * 8; kraw[it] = *(const u32x4*)(P + o + 512); vraw[it] = *(const u32x4*)(P + o + 640); }
.LBB0_570:
	s_or_saveexec_b64 s[0:1], s[0:1]
	v_mov_b32_e32 v24, 0
	v_mov_b32_e32 v25, 0
	v_mov_b32_e32 v26, 0
	v_mov_b32_e32 v27, 0
	v_mov_b32_e32 v28, 0
	v_mov_b32_e32 v29, 0
	v_mov_b32_e32 v30, 0
	v_mov_b32_e32 v31, 0
	v_mov_b32_e32 v16, 0
	v_mov_b32_e32 v17, 0
	v_mov_b32_e32 v18, 0
	v_mov_b32_e32 v19, 0
	v_mov_b32_e32 v20, 0
	v_mov_b32_e32 v21, 0
	v_mov_b32_e32 v22, 0
	v_mov_b32_e32 v23, 0
	s_xor_b64 exec, exec, s[0:1]
	s_cbranch_execz .LBB0_572
	v_ashrrev_i32_e32 v91, 31, v90
	s_lshl_b64 s[10:11], s[8:9], 14
	v_mov_b32_e32 v18, s96
	v_lshlrev_b64 v[16:17], 7, v[90:91]
	v_or3_b32 v19, s11, 0, 0
	v_or3_b32 v18, s10, v18, v98
	v_lshl_add_u64 v[16:17], v[18:19], 0, v[16:17]
	v_readlane_b32 s64, v249, 4
	v_lshlrev_b64 v[24:25], 2, v[16:17]
	v_readlane_b32 s68, v249, 8
	v_readlane_b32 s69, v249, 9
	v_readlane_b32 s70, v249, 10
	v_readlane_b32 s71, v249, 11
	v_lshl_add_u64 v[20:21], s[68:69], 0, v[24:25]
	global_load_dwordx4 v[16:19], v[20:21], off offset:16 nt
	s_nop 0
	global_load_dwordx4 v[20:23], v[20:21], off nt
	v_lshl_add_u64 v[28:29], s[70:71], 0, v[24:25]
	global_load_dwordx4 v[24:27], v[28:29], off offset:16 nt
	s_nop 0
	global_load_dwordx4 v[28:31], v[28:29], off nt
	s_waitcnt vmcnt(0) lgkmcnt(0)
	v_mov_b32_e32 v48, 0
	v_mov_b32_e32 v49, v48
	v_mov_b32_e32 v50, v48
	v_mov_b32_e32 v51, v48
	v_mov_b32_e32 v52, v48
	v_mov_b32_e32 v53, v48
	v_mov_b32_e32 v54, v48
	v_mov_b32_e32 v55, v48
	v_readlane_b32 s65, v249, 5
	v_readlane_b32 s66, v249, 6
	v_readlane_b32 s67, v249, 7
	v_readlane_b32 s72, v249, 12
	v_readlane_b32 s73, v249, 13
	v_readlane_b32 s74, v249, 14
	v_readlane_b32 s75, v249, 15
	v_readlane_b32 s76, v249, 16
	v_readlane_b32 s77, v249, 17
	v_readlane_b32 s78, v249, 18
	v_readlane_b32 s79, v249, 19

; __device__ __forceinline__ void unpack8(const u32x4 w, float* f) { f[0] = bf_lo(w.x); f[1] = bf_hi(w.x); f[2] = bf_lo(w.y); f[3] = bf_hi(w.y); f[4] = bf_lo(w.z); f[5] = bf_hi(w.z); f[6] = bf_lo(w.w); f[7] = bf_hi(w.w); }
; __device__ __forceinline__ void attn_unit(const Params& p, int l, LAS unsigned char* lds, bool sample, int b, int c, int kvh) {
;     ...
;     for (int it = 0; it < 3; ++it) {
;         const int idx = it * 512 + tid, j = idx >> 3, ch = idx & 7;
;         float kf[8], vf[8];
;         const bool fromproj = !sample || j >= 128;
;         if (fromproj) { unpack8(kraw[it], kf); unpack8(vraw[it], vf); }
;         else {
; #pragma unroll
;             for (int i = 0; i < 4; ++i) { kf[i] = kc0[it][i]; kf[4 + i] = kc1[it][i]; vf[i] = vc0[it][i]; vf[4 + i] = vc1[it][i]; } }
;         float ss = 0.f;
; #pragma unroll
;         for (int i = 0; i < 8; ++i) ss += kf[i] * kf[i];
;         ss += __shfl_xor(ss, 1); ss += __shfl_xor(ss, 2); ss += __shfl_xor(ss, 4);
;         if (fromproj) { const float sc = __builtin_amdgcn_rsqf(ss * (1.0f / 64.0f) + EPS);
; #pragma unroll
;             for (int i = 0; i < 8; ++i) kf[i] = kf[i] * sc * knorm[ch * 8 + i]; }
.LBB0_576:
	s_or_b64 exec, exec, s[0:1]
	s_waitcnt vmcnt(0) lgkmcnt(0)
	v_and_b32_e32 v81, 64, v225
	v_xor_b32_e32 v80, 1, v225
	v_add_u32_e32 v85, 64, v81
	v_cmp_lt_i32_e64 s[0:1], v80, v85
	v_xor_b32_e32 v82, 2, v225
	v_or_b32_e32 v96, 2, v98
	v_cndmask_b32_e64 v80, v225, v80, s[0:1]
	v_lshlrev_b32_e32 v91, 2, v80
	v_mul_f32_e32 v80, v65, v65
	v_fmac_f32_e32 v80, v64, v64
	v_fmac_f32_e32 v80, v66, v66
	v_fmac_f32_e32 v80, v67, v67
	v_fmac_f32_e32 v80, v56, v56
	v_fmac_f32_e32 v80, v57, v57
	v_fmac_f32_e32 v80, v58, v58
	v_fmac_f32_e32 v80, v59, v59
	ds_bpermute_b32 v81, v91, v80
	v_cmp_lt_i32_e64 s[0:1], v82, v85
	s_waitcnt lgkmcnt(0)
	v_add_f32_e32 v80, v80, v81
	v_cndmask_b32_e64 v82, v225, v82, s[0:1]
	v_lshlrev_b32_e32 v93, 2, v82
	ds_bpermute_b32 v81, v93, v80
	v_xor_b32_e32 v82, 4, v225
	v_cmp_lt_i32_e64 s[0:1], v82, v85
	s_waitcnt lgkmcnt(0)
	v_add_f32_e32 v81, v80, v81
	v_cndmask_b32_e64 v82, v225, v82, s[0:1]
	v_lshlrev_b32_e32 v99, 2, v82
	ds_bpermute_b32 v83, v99, v81
	v_or_b32_e32 v82, 4, v98
	v_or_b32_e32 v80, 6, v98
	s_and_saveexec_b64 s[0:1], vcc
	s_xor_b64 s[0:1], exec, s[0:1]
	v_or_b32_e32 v96, 2, v98
	v_or_b32_e32 v82, 4, v98
	v_or_b32_e32 v80, 6, v98
	s_or_saveexec_b64 s[0:1], s[0:1]
	v_lshlrev_b32_e32 v104, 2, v98
	s_xor_b64 exec, exec, s[0:1]
	s_cbranch_execz .LBB0_580
	global_load_dwordx4 v[100:103], v104, s[50:51] offset:16 nt
	global_load_dwordx4 v[106:109], v104, s[50:51] nt
	s_waitcnt lgkmcnt(0)
	v_add_f32_e32 v81, v81, v83
	v_fmamk_f32 v81, v81, 0x3c800000, v223
	v_rsq_f32_e32 v84, v81
	s_nop 0
	v_pk_mul_f32 v[64:65], v[64:65], v[84:85] op_sel_hi:[1,0]
	v_pk_mul_f32 v[66:67], v[66:67], v[84:85] op_sel_hi:[1,0]
	v_pk_mul_f32 v[56:57], v[56:57], v[84:85] op_sel_hi:[1,0]
	v_pk_mul_f32 v[58:59], v[58:59], v[84:85] op_sel_hi:[1,0]
	s_waitcnt vmcnt(1)
	v_pk_mul_f32 v[56:57], v[56:57], v[100:101]
	s_waitcnt vmcnt(0)
	v_pk_mul_f32 v[64:65], v[64:65], v[106:107]
	v_pk_mul_f32 v[66:67], v[66:67], v[108:109]
	v_pk_mul_f32 v[58:59], v[58:59], v[102:103]

; __device__ __forceinline__ void unpack8(const u32x4 w, float* f) { f[0] = bf_lo(w.x); f[1] = bf_hi(w.x); f[2] = bf_lo(w.y); f[3] = bf_hi(w.y); f[4] = bf_lo(w.z); f[5] = bf_hi(w.z); f[6] = bf_lo(w.w); f[7] = bf_hi(w.w); }
; __device__ __forceinline__ u32x4 pack8(const float* f) { u32x4 w; w.x = cvt_pk_bf16(f[0], f[1]); w.y = cvt_pk_bf16(f[2], f[3]); w.z = cvt_pk_bf16(f[4], f[5]); w.w = cvt_pk_bf16(f[6], f[7]); return w; }
; __device__ __forceinline__ void attn_unit(const Params& p, int l, LAS unsigned char* lds, bool sample, int b, int c, int kvh) {
;     ...
;     bf16x8 qf[4];
;     {
;         float qv[4][8]; float ss = 0.f;
; #pragma unroll
;         for (int d0 = 0; d0 < 4; ++d0) { unpack8(qraw[d0], qv[d0]);
; #pragma unroll
;             for (int i = 0; i < 8; ++i) ss += qv[d0][i] * qv[d0][i]; }
;         ss += __shfl_xor(ss, 32);
;         const float sc = __builtin_amdgcn_rsqf(ss * (1.0f / 64.0f) + EPS) * (0.125f * LOG2E);
;         const float* qn = p.q_norm + l * 64;
; #pragma unroll
;         for (int d0 = 0; d0 < 4; ++d0) { float t8[8];
; #pragma unroll
;             for (int i = 0; i < 8; ++i) t8[i] = qv[d0][i] * sc * qn[d0 * 16 + hi * 8 + i];
;             qf[d0] = __builtin_bit_cast(bf16x8, pack8(t8)); }
;     }
;     __syncthreads();
.LBB0_604:
	s_or_b64 exec, exec, s[0:1]
	v_and_b32_e32 v41, 0xffff0000, v12
	v_lshlrev_b32_e32 v42, 16, v12
	v_lshlrev_b32_e32 v37, 16, v14
	v_and_b32_e32 v36, 0xffff0000, v14
	v_mul_f32_e32 v14, v41, v41
	v_lshlrev_b32_e32 v40, 16, v13
	v_fmac_f32_e32 v14, v42, v42
	v_and_b32_e32 v39, 0xffff0000, v13
	v_fmac_f32_e32 v14, v40, v40
	v_fmac_f32_e32 v14, v39, v39
	v_fmac_f32_e32 v14, v37, v37
	v_lshlrev_b32_e32 v35, 16, v15
	v_fmac_f32_e32 v14, v36, v36
	v_and_b32_e32 v34, 0xffff0000, v15
	v_fmac_f32_e32 v14, v35, v35
	v_fmac_f32_e32 v14, v34, v34
	v_lshlrev_b32_e32 v38, 16, v8
	v_and_b32_e32 v33, 0xffff0000, v8
	v_fmac_f32_e32 v14, v38, v38
	v_lshlrev_b32_e32 v32, 16, v9
	v_fmac_f32_e32 v14, v33, v33
	v_and_b32_e32 v31, 0xffff0000, v9
	v_fmac_f32_e32 v14, v32, v32
	v_lshlrev_b32_e32 v30, 16, v10
	v_fmac_f32_e32 v14, v31, v31
	v_and_b32_e32 v29, 0xffff0000, v10
	v_fmac_f32_e32 v14, v30, v30
	v_lshlrev_b32_e32 v28, 16, v11
	v_fmac_f32_e32 v14, v29, v29
	v_and_b32_e32 v27, 0xffff0000, v11
	v_fmac_f32_e32 v14, v28, v28
	v_fmac_f32_e32 v14, v27, v27
	v_lshlrev_b32_e32 v26, 16, v4
	v_and_b32_e32 v25, 0xffff0000, v4
	v_fmac_f32_e32 v14, v26, v26
	v_lshlrev_b32_e32 v24, 16, v5
	v_fmac_f32_e32 v14, v25, v25
	v_and_b32_e32 v23, 0xffff0000, v5
	v_fmac_f32_e32 v14, v24, v24
	v_lshlrev_b32_e32 v22, 16, v6
	v_fmac_f32_e32 v14, v23, v23
	v_and_b32_e32 v21, 0xffff0000, v6
	v_fmac_f32_e32 v14, v22, v22
	v_lshlrev_b32_e32 v20, 16, v7
	v_fmac_f32_e32 v14, v21, v21
	v_and_b32_e32 v19, 0xffff0000, v7
	v_fmac_f32_e32 v14, v20, v20
	v_fmac_f32_e32 v14, v19, v19
	v_lshlrev_b32_e32 v18, 16, v0
	v_and_b32_e32 v17, 0xffff0000, v0
	v_fmac_f32_e32 v14, v18, v18
	v_lshlrev_b32_e32 v16, 16, v1
	v_fmac_f32_e32 v14, v17, v17
	v_and_b32_e32 v15, 0xffff0000, v1
	v_fmac_f32_e32 v14, v16, v16
	v_lshlrev_b32_e32 v13, 16, v2
	v_fmac_f32_e32 v14, v15, v15
	v_and_b32_e32 v12, 0xffff0000, v2
	v_fmac_f32_e32 v14, v13, v13
	v_xor_b32_e32 v0, 32, v225
	v_lshlrev_b32_e32 v11, 16, v3
	v_fmac_f32_e32 v14, v12, v12
	v_cmp_lt_i32_e32 vcc, v0, v85
	v_and_b32_e32 v10, 0xffff0000, v3
	v_fmac_f32_e32 v14, v11, v11
	v_cndmask_b32_e32 v0, v225, v0, vcc
	v_fmac_f32_e32 v14, v10, v10
	v_lshlrev_b32_e32 v96, 2, v0
	ds_bpermute_b32 v0, v96, v14
	v_lshl_add_u64 v[8:9], v[88:89], 2, s[58:59]
	s_bitcmp1_b32 s25, 6
	s_waitcnt lgkmcnt(0)
	v_add_f32_e32 v0, v14, v0
	v_fmamk_f32 v0, v0, 0x3c800000, v223
	v_rsq_f32_e32 v0, v0
	s_nop 0
	v_mul_f32_e32 v14, 0x3e38aa3b, v0
	global_load_dwordx4 v[0:3], v[8:9], off offset:16 nt
	global_load_dwordx4 v[4:7], v[8:9], off nt
	v_mul_f32_e32 v37, v14, v37
	v_mul_f32_e32 v42, v14, v42
	v_mul_f32_e32 v41, v14, v41
	v_mul_f32_e32 v40, v14, v40
	v_mul_f32_e32 v39, v14, v39
	v_mul_f32_e32 v30, v14, v30
	v_mul_f32_e32 v29, v14, v29
	v_mul_f32_e32 v28, v14, v28
	v_mul_f32_e32 v27, v14, v27
	v_mul_f32_e32 v38, v14, v38
	v_mul_f32_e32 v33, v14, v33
	v_mul_f32_e32 v32, v14, v32
	v_mul_f32_e32 v31, v14, v31
	v_mul_f32_e32 v22, v14, v22
	v_mul_f32_e32 v21, v14, v21
	v_mul_f32_e32 v20, v14, v20
	v_mul_f32_e32 v19, v14, v19
	v_mul_f32_e32 v25, v14, v25
	v_mul_f32_e32 v24, v14, v24
	v_mul_f32_e32 v23, v14, v23
	v_mul_f32_e32 v16, v14, v16
	v_mul_f32_e32 v15, v14, v15
	v_mul_f32_e32 v13, v14, v13
	v_mul_f32_e32 v12, v14, v12
	v_mul_f32_e32 v11, v14, v11
	v_mul_f32_e32 v10, v14, v10
	s_waitcnt vmcnt(0)
	v_mul_f32_e32 v37, v0, v37
	v_mul_f32_e32 v0, v14, v36
	v_mul_f32_e32 v36, v1, v0
	v_mul_f32_e32 v0, v14, v35
	v_mul_f32_e32 v35, v0, v2
	v_mul_f32_e32 v0, v14, v34
	v_mul_f32_e32 v4, v4, v42
	v_mul_f32_e32 v5, v5, v41
	v_mul_f32_e32 v6, v6, v40
	v_mul_f32_e32 v7, v7, v39
	v_mul_f32_e32 v3, v0, v3
	v_cvt_pk_bf16_f32 v0, v4, v5
	v_cvt_pk_bf16_f32 v1, v6, v7
	v_cvt_pk_bf16_f32 v2, v37, v36
	v_cvt_pk_bf16_f32 v3, v35, v3
	global_load_dwordx4 v[4:7], v[8:9], off offset:80 nt
	global_load_dwordx4 v[34:37], v[8:9], off offset:64 nt
	s_waitcnt vmcnt(1)
	v_mul_f32_e32 v4, v30, v4
	v_mul_f32_e32 v5, v29, v5
	v_mul_f32_e32 v6, v28, v6
	v_mul_f32_e32 v7, v27, v7
	s_waitcnt vmcnt(0)
	v_mul_f32_e32 v34, v38, v34
	v_mul_f32_e32 v33, v33, v35
	v_mul_f32_e32 v32, v32, v36
	v_mul_f32_e32 v31, v31, v37
	v_cvt_pk_bf16_f32 v98, v34, v33
	v_cvt_pk_bf16_f32 v99, v32, v31
	v_cvt_pk_bf16_f32 v100, v4, v5
	v_cvt_pk_bf16_f32 v101, v6, v7
	v_mul_f32_e32 v30, v14, v26
	global_load_dwordx4 v[4:7], v[8:9], off offset:144 nt
	global_load_dwordx4 v[26:29], v[8:9], off offset:128 nt
	s_waitcnt vmcnt(1)
	v_mul_f32_e32 v4, v22, v4
	v_mul_f32_e32 v5, v21, v5
	v_mul_f32_e32 v6, v20, v6
	v_mul_f32_e32 v7, v19, v7
	s_waitcnt vmcnt(0)
	v_mul_f32_e32 v26, v30, v26
	v_mul_f32_e32 v25, v25, v27
	v_mul_f32_e32 v24, v24, v28
	v_mul_f32_e32 v23, v23, v29
	v_cvt_pk_bf16_f32 v102, v26, v25
	v_cvt_pk_bf16_f32 v103, v24, v23
	v_cvt_pk_bf16_f32 v104, v4, v5
	v_cvt_pk_bf16_f32 v105, v6, v7
	v_mul_f32_e32 v22, v14, v18
	global_load_dwordx4 v[4:7], v[8:9], off offset:208 nt
	global_load_dwordx4 v[18:21], v[8:9], off offset:192 nt
	v_mul_f32_e32 v9, v14, v17
	s_waitcnt vmcnt(1)
	v_mul_f32_e32 v4, v13, v4
	s_waitcnt vmcnt(0)
	v_mul_f32_e32 v8, v22, v18
	v_mul_f32_e32 v9, v9, v19
	v_mul_f32_e32 v16, v16, v20
	v_mul_f32_e32 v15, v15, v21
	v_mul_f32_e32 v5, v12, v5
	v_mul_f32_e32 v6, v11, v6
	v_mul_f32_e32 v7, v10, v7
	v_cvt_pk_bf16_f32 v106, v8, v9
	v_cvt_pk_bf16_f32 v107, v16, v15
	v_cvt_pk_bf16_f32 v108, v4, v5
	v_cvt_pk_bf16_f32 v109, v6, v7
	s_barrier
	s_cbranch_scc1 .LBB0_285
; #define LAS __attribute__((address_space(3)))
; __device__ __forceinline__ int crow(int r, int hi) { return (r & 3) + 8 * (r >> 2) + 4 * hi; }
; __device__ __forceinline__ void attn_unit(const Params& p, int l, LAS unsigned char* lds, bool sample, int b, int c, int kvh) {
;     ...
;     if (active) {
;         f32x16 s[6];
; #pragma unroll
;         for (int kt = 0; kt < 6; ++kt) {
;             s[kt] = (f32x16){};
; #pragma unroll
;             for (int d0 = 0; d0 < 4; ++d0) {
;                 const bf16x8 kfr = *(const LAS bf16x8*)(Ks + (kt * 32 + q32) * KS_LD + d0 * 16 + hi * 8);
;                 s[kt] = __builtin_amdgcn_mfma_f32_32x32x16_bf16(kfr, qf[d0], s[kt], 0, 0, 0);
;             }
;         }
;         const float slope2 = __builtin_amdgcn_exp2f(-(float)(h + 1)) * LOG2E;
;         const int jmin = sample ? 0 : (c >= 2 ? 0 : 128 - 64 * c), jmax = sample ? 144 : 192;
;         float mx = -3.0e38f;
;         const float relb = (float)(128 + tq - 4 * hi);
;         const bool need_mask = sample || c < 2;
; #pragma unroll
;         for (int kt = 0; kt < 6; ++kt)
; #pragma unroll
;             for (int r = 0; r < 16; ++r) {
;                 float v = __builtin_fmaf(-slope2, __builtin_fabsf(relb - (float)(32 * kt + (r & 3) + 8 * (r >> 2))), s[kt][r]);
;                 if (need_mask) { const int j = 32 * kt + crow(r, hi); if (j < jmin || j >= jmax) v = -1.0e30f; }
;                 s[kt][r] = v; mx = __builtin_fmaxf(mx, v);
	v_and_b32_e32 v111, 31, v208
	v_lshlrev_b32_e32 v4, 4, v110
	v_mul_u32_u24_e32 v5, 0x90, v111
	v_add3_u32 v116, 0, v4, v5
	ds_read_b128 v[4:7], v116
	ds_read_b128 v[8:11], v116 offset:32
	s_ashr_i32 s9, s25, 6
	s_lshl_b32 s0, s9, 7
	s_waitcnt lgkmcnt(1)
	v_mfma_f32_32x32x16_bf16 v[80:95], v[4:7], v[0:3], 0
	ds_read_b128 v[4:7], v116 offset:64
	ds_read_b128 v[112:115], v116 offset:23072
	s_add_i32 s8, s0, 0
	s_add_i32 s0, s7, 1
	v_or_b32_e32 v117, 0x80, v111
	s_movk_i32 s1, 0x8f
	v_readlane_b32 s64, v249, 20
	s_waitcnt lgkmcnt(2)
	v_mfma_f32_32x32x16_bf16 v[80:95], v[8:11], v[98:101], v[80:95]
	v_readlane_b32 s68, v249, 24
	v_readlane_b32 s69, v249, 25
	v_readlane_b32 s65, v249, 21
	v_readlane_b32 s66, v249, 22
	v_readlane_b32 s67, v249, 23
	v_readlane_b32 s70, v249, 26
	v_readlane_b32 s71, v249, 27
	s_waitcnt lgkmcnt(1)
	v_mfma_f32_32x32x16_bf16 v[80:95], v[4:7], v[102:105], v[80:95]
	ds_read_b128 v[4:7], v116 offset:96
	v_readlane_b32 s72, v249, 28
	v_readlane_b32 s73, v249, 29
	v_readlane_b32 s74, v249, 30
	v_readlane_b32 s75, v249, 31
	v_readlane_b32 s76, v249, 32
	v_readlane_b32 s77, v249, 33
	s_waitcnt lgkmcnt(0)
	v_mfma_f32_32x32x16_bf16 v[80:95], v[4:7], v[106:109], v[80:95]
	ds_read_b128 v[4:7], v116 offset:4608
	v_readlane_b32 s78, v249, 34
	v_readlane_b32 s79, v249, 35
	s_waitcnt lgkmcnt(0)
	v_mfma_f32_32x32x16_bf16 v[64:79], v[4:7], v[0:3], 0
	ds_read_b128 v[4:7], v116 offset:4640
	s_waitcnt lgkmcnt(0)
	v_mfma_f32_32x32x16_bf16 v[64:79], v[4:7], v[98:101], v[64:79]
	ds_read_b128 v[4:7], v116 offset:4672
	s_waitcnt lgkmcnt(0)
	v_mfma_f32_32x32x16_bf16 v[64:79], v[4:7], v[102:105], v[64:79]
	ds_read_b128 v[4:7], v116 offset:4704
	s_waitcnt lgkmcnt(0)
	v_mfma_f32_32x32x16_bf16 v[64:79], v[4:7], v[106:109], v[64:79]
	ds_read_b128 v[4:7], v116 offset:9216
	s_waitcnt lgkmcnt(0)
	v_mfma_f32_32x32x16_bf16 v[48:63], v[4:7], v[0:3], 0
	ds_read_b128 v[4:7], v116 offset:9248
	s_waitcnt lgkmcnt(0)
	v_mfma_f32_32x32x16_bf16 v[48:63], v[4:7], v[98:101], v[48:63]
	ds_read_b128 v[4:7], v116 offset:9280
	s_waitcnt lgkmcnt(0)
	v_mfma_f32_32x32x16_bf16 v[48:63], v[4:7], v[102:105], v[48:63]
	ds_read_b128 v[4:7], v116 offset:9312
	s_waitcnt lgkmcnt(0)
	v_mfma_f32_32x32x16_bf16 v[48:63], v[4:7], v[106:109], v[48:63]
	ds_read_b128 v[4:7], v116 offset:13824
	s_waitcnt lgkmcnt(0)
	v_mfma_f32_32x32x16_bf16 v[32:47], v[4:7], v[0:3], 0
	ds_read_b128 v[4:7], v116 offset:13856
	s_waitcnt lgkmcnt(0)
	v_mfma_f32_32x32x16_bf16 v[32:47], v[4:7], v[98:101], v[32:47]
	ds_read_b128 v[4:7], v116 offset:13888
	s_waitcnt lgkmcnt(0)
	v_mfma_f32_32x32x16_bf16 v[32:47], v[4:7], v[102:105], v[32:47]
	ds_read_b128 v[4:7], v116 offset:13920
	s_waitcnt lgkmcnt(0)
	v_mfma_f32_32x32x16_bf16 v[32:47], v[4:7], v[106:109], v[32:47]
	ds_read_b128 v[4:7], v116 offset:18432
	s_waitcnt lgkmcnt(0)
	v_mfma_f32_32x32x16_bf16 v[16:31], v[4:7], v[0:3], 0
	ds_read_b128 v[4:7], v116 offset:18464
	s_waitcnt lgkmcnt(0)
	v_mfma_f32_32x32x16_bf16 v[16:31], v[4:7], v[98:101], v[16:31]
	ds_read_b128 v[4:7], v116 offset:18496
	s_waitcnt lgkmcnt(0)
	v_mfma_f32_32x32x16_bf16 v[16:31], v[4:7], v[102:105], v[16:31]
	ds_read_b128 v[4:7], v116 offset:18528
	s_waitcnt lgkmcnt(0)
	v_mfma_f32_32x32x16_bf16 v[16:31], v[4:7], v[106:109], v[16:31]
	ds_read_b128 v[4:7], v116 offset:23040
	s_waitcnt lgkmcnt(0)
	v_mfma_f32_32x32x16_bf16 v[0:15], v[4:7], v[0:3], 0
	v_mfma_f32_32x32x16_bf16 v[0:15], v[112:115], v[98:101], v[0:15]
	ds_read_b128 v[98:101], v116 offset:23104
	s_waitcnt lgkmcnt(0)
	v_mfma_f32_32x32x16_bf16 v[0:15], v[98:101], v[102:105], v[0:15]
	ds_read_b128 v[98:101], v116 offset:23136
	s_waitcnt lgkmcnt(0)
	v_mfma_f32_32x32x16_bf16 v[0:15], v[98:101], v[106:109], v[0:15]
	v_cvt_f32_i32_e32 v98, s0
	s_mov_b32 s0, 0xff61b1e6
	v_exp_f32_e64 v99, -v98
	v_lshlrev_b32_e32 v98, 2, v110
	v_sub_u32_e32 v100, v117, v98
	v_cvt_f32_i32_e32 v136, v100
	v_mul_f32_e32 v137, 0xbfb8aa3b, v99
	v_cmp_lt_u32_e32 vcc, s1, v98
	v_fma_f32 v80, v137, |v136|, v80
	s_nop 0
	v_cndmask_b32_e32 v135, v80, v226, vcc
	v_add_f32_e32 v80, -1.0, v136
	v_fma_f32 v80, v137, |v80|, v81
	v_add_f32_e32 v81, -2.0, v136
	v_fma_f32 v81, v137, |v81|, v82
	v_cndmask_b32_e32 v134, v81, v226, vcc
	v_add_f32_e32 v81, 0xc0400000, v136
	v_fma_f32 v81, v137, |v81|, v83
	v_cndmask_b32_e32 v132, v81, v226, vcc
	v_add_f32_e32 v81, 0xc1000000, v136
	v_add_u32_e32 v83, 8, v98
	v_cndmask_b32_e32 v133, v80, v226, vcc
	v_fma_f32 v81, v137, |v81|, v84
	v_cmp_lt_u32_e32 vcc, s1, v83
	v_max3_f32 v80, v135, s0, v133
	v_max3_f32 v80, v80, v134, v132
	v_cndmask_b32_e32 v131, v81, v226, vcc
	v_add_f32_e32 v81, 0xc1100000, v136
	v_fma_f32 v81, v137, |v81|, v85
	v_cndmask_b32_e32 v130, v81, v226, vcc
	v_add_f32_e32 v81, 0xc1200000, v136
	v_fma_f32 v81, v137, |v81|, v86
	v_cndmask_b32_e32 v129, v81, v226, vcc
	v_add_f32_e32 v81, 0xc1300000, v136
	v_fma_f32 v81, v137, |v81|, v87
	v_cndmask_b32_e32 v128, v81, v226, vcc
	v_add_f32_e32 v81, 0xc1800000, v136
	v_fma_f32 v82, v137, |v81|, v88
	v_add_u32_e32 v81, 16, v98
	v_cmp_lt_u32_e32 vcc, s1, v81
	v_max3_f32 v80, v80, v131, v130
	v_max3_f32 v80, v80, v129, v128
	v_cndmask_b32_e32 v126, v82, v226, vcc
	v_add_f32_e32 v82, 0xc1880000, v136
	v_fma_f32 v82, v137, |v82|, v89
	v_cndmask_b32_e32 v127, v82, v226, vcc
	v_add_f32_e32 v82, 0xc1900000, v136
	v_fma_f32 v82, v137, |v82|, v90
	v_cndmask_b32_e32 v124, v82, v226, vcc
	v_add_f32_e32 v82, 0xc1980000, v136
	v_fma_f32 v82, v137, |v82|, v91
	v_cndmask_b32_e32 v125, v82, v226, vcc
	v_add_f32_e32 v82, 0xc1c00000, v136
	v_fma_f32 v84, v137, |v82|, v92
	v_add_u32_e32 v82, 24, v98
	v_cmp_lt_u32_e32 vcc, s1, v82
	v_max3_f32 v80, v80, v126, v127
	v_max3_f32 v80, v80, v124, v125
; __device__ __forceinline__ int crow(int r, int hi) { return (r & 3) + 8 * (r >> 2) + 4 * hi; }
; __device__ __forceinline__ void attn_unit(const Params& p, int l, LAS unsigned char* lds, bool sample, int b, int c, int kvh) {
;     ...
; #pragma unroll
;         for (int kt = 0; kt < 6; ++kt)
; #pragma unroll
;             for (int r = 0; r < 16; ++r) {
;                 float v = __builtin_fmaf(-slope2, __builtin_fabsf(relb - (float)(32 * kt + (r & 3) + 8 * (r >> 2))), s[kt][r]);
;                 if (need_mask) { const int j = 32 * kt + crow(r, hi); if (j < jmin || j >= jmax) v = -1.0e30f; }
;                 s[kt][r] = v; mx = __builtin_fmaxf(mx, v);
;             }
	v_cndmask_b32_e32 v123, v84, v226, vcc
	v_add_f32_e32 v84, 0xc1c80000, v136
	v_fma_f32 v84, v137, |v84|, v93
	v_cndmask_b32_e32 v121, v84, v226, vcc
	v_add_f32_e32 v84, 0xc1d00000, v136
	v_fma_f32 v84, v137, |v84|, v94
	v_cndmask_b32_e32 v122, v84, v226, vcc
	v_add_f32_e32 v84, 0xc1d80000, v136
	v_fma_f32 v84, v137, |v84|, v95
	v_max3_f32 v80, v80, v123, v121
	v_cndmask_b32_e32 v120, v84, v226, vcc
	v_max3_f32 v84, v80, v122, v120
	v_add_u32_e32 v80, 32, v98
	v_add_f32_e32 v85, 0xc2000000, v136
	v_fma_f32 v64, v137, |v85|, v64
	v_cmp_lt_u32_e32 vcc, s1, v80
	s_movk_i32 s0, 0xff70
	s_nop 0
	v_cndmask_b32_e32 v119, v64, v226, vcc
	v_add_f32_e32 v64, 0xc2040000, v136
	v_fma_f32 v64, v137, |v64|, v65
	v_add_f32_e32 v65, 0xc2080000, v136
	v_fma_f32 v65, v137, |v65|, v66
	v_cndmask_b32_e32 v118, v65, v226, vcc
	v_add_f32_e32 v65, 0xc20c0000, v136
	v_fma_f32 v65, v137, |v65|, v67
	v_cndmask_b32_e32 v116, v65, v226, vcc
	v_add_f32_e32 v65, 0xc2200000, v136
	v_add_u32_e32 v67, 40, v98
	v_cndmask_b32_e32 v117, v64, v226, vcc
	v_fma_f32 v65, v137, |v65|, v68
	v_cmp_lt_u32_e32 vcc, s1, v67
	v_max3_f32 v64, v84, v119, v117
	v_max3_f32 v64, v64, v118, v116
	v_cndmask_b32_e32 v115, v65, v226, vcc
	v_add_f32_e32 v65, 0xc2240000, v136
	v_fma_f32 v65, v137, |v65|, v69
	v_cndmask_b32_e32 v114, v65, v226, vcc
	v_add_f32_e32 v65, 0xc2280000, v136
	v_fma_f32 v65, v137, |v65|, v70
	v_cndmask_b32_e32 v113, v65, v226, vcc
	v_add_f32_e32 v65, 0xc22c0000, v136
	v_fma_f32 v65, v137, |v65|, v71
	v_cndmask_b32_e32 v112, v65, v226, vcc
	v_add_f32_e32 v65, 0xc2400000, v136
	v_fma_f32 v66, v137, |v65|, v72
	v_add_u32_e32 v65, 48, v98
	v_cmp_lt_u32_e32 vcc, s1, v65
	v_max3_f32 v64, v64, v115, v114
	v_max3_f32 v64, v64, v113, v112
	v_cndmask_b32_e32 v108, v66, v226, vcc
	v_add_f32_e32 v66, 0xc2440000, v136
	v_fma_f32 v66, v137, |v66|, v73
	v_cndmask_b32_e32 v109, v66, v226, vcc
	v_add_f32_e32 v66, 0xc2480000, v136
	v_fma_f32 v66, v137, |v66|, v74
	v_cndmask_b32_e32 v106, v66, v226, vcc
	v_add_f32_e32 v66, 0xc24c0000, v136
	v_fma_f32 v66, v137, |v66|, v75
	v_cndmask_b32_e32 v107, v66, v226, vcc
	v_add_f32_e32 v66, 0xc2600000, v136
	v_fma_f32 v68, v137, |v66|, v76
	v_add_u32_e32 v66, 56, v98
	v_cmp_lt_u32_e32 vcc, s1, v66
	v_max3_f32 v64, v64, v108, v109
	v_max3_f32 v64, v64, v106, v107
	v_cndmask_b32_e32 v105, v68, v226, vcc
	v_add_f32_e32 v68, 0xc2640000, v136
	v_fma_f32 v68, v137, |v68|, v77
	v_cndmask_b32_e32 v103, v68, v226, vcc
	v_add_f32_e32 v68, 0xc2680000, v136
	v_fma_f32 v68, v137, |v68|, v78
	v_cndmask_b32_e32 v104, v68, v226, vcc
	v_add_f32_e32 v68, 0xc26c0000, v136
	v_fma_f32 v68, v137, |v68|, v79
	v_max3_f32 v64, v64, v105, v103
	v_cndmask_b32_e32 v102, v68, v226, vcc
	v_max3_f32 v68, v64, v104, v102
	v_add_u32_e32 v64, 64, v98
	v_add_f32_e32 v69, 0xc2800000, v136
	v_fma_f32 v48, v137, |v69|, v48
	v_cmp_lt_u32_e32 vcc, s1, v64
	s_nop 1
	v_cndmask_b32_e32 v101, v48, v226, vcc
	v_add_f32_e32 v48, 0xc2820000, v136
	v_fma_f32 v48, v137, |v48|, v49
	v_add_f32_e32 v49, 0xc2840000, v136
	v_fma_f32 v49, v137, |v49|, v50
	v_cndmask_b32_e32 v99, v49, v226, vcc
	v_add_f32_e32 v49, 0xc2860000, v136
	v_fma_f32 v49, v137, |v49|, v51
	v_cndmask_b32_e32 v95, v49, v226, vcc
	v_add_f32_e32 v49, 0xc2900000, v136
	v_fma_f32 v49, v137, |v49|, v52
	v_add_u32_e32 v52, 0x48, v98
	v_cndmask_b32_e32 v100, v48, v226, vcc
	v_cmp_lt_u32_e32 vcc, s1, v52
	v_add_u32_e32 v50, 0x50, v98
	v_add_u32_e32 v51, 0x58, v98
	v_cndmask_b32_e32 v94, v49, v226, vcc
	v_add_f32_e32 v49, 0xc2920000, v136
	v_fma_f32 v49, v137, |v49|, v53
	v_cndmask_b32_e32 v93, v49, v226, vcc
	v_add_f32_e32 v49, 0xc2940000, v136
	v_fma_f32 v49, v137, |v49|, v54
	v_cndmask_b32_e32 v92, v49, v226, vcc
	v_add_f32_e32 v49, 0xc2960000, v136
	v_fma_f32 v49, v137, |v49|, v55
	v_cndmask_b32_e32 v91, v49, v226, vcc
	v_add_f32_e32 v49, 0xc2a00000, v136
	v_fma_f32 v49, v137, |v49|, v56
	v_cmp_lt_u32_e32 vcc, s1, v50
	v_max3_f32 v48, v68, v101, v100
	v_max3_f32 v48, v48, v99, v95
	v_cndmask_b32_e32 v90, v49, v226, vcc
	v_add_f32_e32 v49, 0xc2a20000, v136
	v_fma_f32 v49, v137, |v49|, v57
	v_cndmask_b32_e32 v89, v49, v226, vcc
	v_add_f32_e32 v49, 0xc2a40000, v136
	v_fma_f32 v49, v137, |v49|, v58
	v_cndmask_b32_e32 v88, v49, v226, vcc
	v_add_f32_e32 v49, 0xc2a60000, v136
	v_fma_f32 v49, v137, |v49|, v59
	v_cndmask_b32_e32 v87, v49, v226, vcc
	v_add_f32_e32 v49, 0xc2b00000, v136
	v_fma_f32 v49, v137, |v49|, v60
	v_cmp_lt_u32_e32 vcc, s1, v51
	v_max3_f32 v48, v48, v94, v93
	v_max3_f32 v48, v48, v92, v91
	v_cndmask_b32_e32 v86, v49, v226, vcc
	v_add_f32_e32 v49, 0xc2b20000, v136
	v_fma_f32 v49, v137, |v49|, v61
	v_cndmask_b32_e32 v85, v49, v226, vcc
	v_add_f32_e32 v49, 0xc2b40000, v136
	v_fma_f32 v49, v137, |v49|, v62
	v_max3_f32 v48, v48, v90, v89
	v_cndmask_b32_e32 v84, v49, v226, vcc
	v_add_f32_e32 v49, 0xc2b60000, v136
	v_max3_f32 v48, v48, v88, v87
	v_fma_f32 v49, v137, |v49|, v63
	v_max3_f32 v48, v48, v86, v85
	v_cndmask_b32_e32 v79, v49, v226, vcc
	v_max3_f32 v49, v48, v84, v79
	v_add_u32_e32 v48, 0x60, v98
	v_add_f32_e32 v53, 0xc2c00000, v136
	v_fma_f32 v32, v137, |v53|, v32
	v_cmp_lt_u32_e32 vcc, s1, v48
	s_nop 1
	v_cndmask_b32_e32 v78, v32, v226, vcc
	v_add_f32_e32 v32, 0xc2c20000, v136
	v_fma_f32 v32, v137, |v32|, v33
	v_add_f32_e32 v33, 0xc2c40000, v136
	v_fma_f32 v33, v137, |v33|, v34
	v_cndmask_b32_e32 v76, v33, v226, vcc
	v_add_f32_e32 v33, 0xc2c60000, v136
	v_cndmask_b32_e32 v77, v32, v226, vcc
	v_fma_f32 v33, v137, |v33|, v35
	v_max3_f32 v32, v49, v78, v77
	v_cndmask_b32_e32 v75, v33, v226, vcc
	v_add_f32_e32 v33, 0xc2d00000, v136
	v_add_u32_e32 v49, 0x68, v98
	v_fma_f32 v33, v137, |v33|, v36
	v_cmp_lt_u32_e32 vcc, s1, v49
; __device__ __forceinline__ int crow(int r, int hi) { return (r & 3) + 8 * (r >> 2) + 4 * hi; }
; __device__ __forceinline__ void attn_unit(const Params& p, int l, LAS unsigned char* lds, bool sample, int b, int c, int kvh) {
;     ...
; #pragma unroll
;         for (int kt = 0; kt < 6; ++kt)
; #pragma unroll
;             for (int r = 0; r < 16; ++r) {
;                 float v = __builtin_fmaf(-slope2, __builtin_fabsf(relb - (float)(32 * kt + (r & 3) + 8 * (r >> 2))), s[kt][r]);
;                 if (need_mask) { const int j = 32 * kt + crow(r, hi); if (j < jmin || j >= jmax) v = -1.0e30f; }
;                 s[kt][r] = v; mx = __builtin_fmaxf(mx, v);
;             }
;         mx = __builtin_fmaxf(mx, __shfl_xor(mx, 32));
;         const float sink2 = p.sinks[l * 8 + h] * LOG2E;
	v_max3_f32 v32, v32, v76, v75
	v_add_u32_e32 v34, 0xa0, v98
	v_cndmask_b32_e32 v74, v33, v226, vcc
	v_add_f32_e32 v33, 0xc2d20000, v136
	v_fma_f32 v33, v137, |v33|, v37
	v_cndmask_b32_e32 v73, v33, v226, vcc
	v_add_f32_e32 v33, 0xc2d40000, v136
	v_fma_f32 v33, v137, |v33|, v38
	v_cndmask_b32_e32 v72, v33, v226, vcc
	v_add_f32_e32 v33, 0xc2d60000, v136
	v_fma_f32 v33, v137, |v33|, v39
	v_cndmask_b32_e32 v71, v33, v226, vcc
	v_add_f32_e32 v33, 0xc2e00000, v136
	v_fma_f32 v33, v137, |v33|, v40
	v_add_u32_e32 v40, 0x70, v98
	v_cmp_lt_u32_e32 vcc, s1, v40
	v_add_u32_e32 v38, 0x80, v98
	v_add_u32_e32 v39, 0x88, v98
	v_cndmask_b32_e32 v70, v33, v226, vcc
	v_add_f32_e32 v33, 0xc2e20000, v136
	v_fma_f32 v33, v137, |v33|, v41
	v_cndmask_b32_e32 v69, v33, v226, vcc
	v_add_f32_e32 v33, 0xc2e40000, v136
	v_fma_f32 v33, v137, |v33|, v42
	v_cndmask_b32_e32 v68, v33, v226, vcc
	v_add_f32_e32 v33, 0xc2e60000, v136
	v_fma_f32 v33, v137, |v33|, v43
	v_cndmask_b32_e32 v63, v33, v226, vcc
	v_add_f32_e32 v33, 0xc2f00000, v136
	v_add_u32_e32 v41, 0x78, v98
	v_fma_f32 v33, v137, |v33|, v44
	v_cmp_lt_u32_e32 vcc, s1, v41
	v_add_u32_e32 v37, 0x98, v98
	v_max3_f32 v32, v32, v74, v73
	v_cndmask_b32_e32 v62, v33, v226, vcc
	v_add_f32_e32 v33, 0xc2f20000, v136
	v_fma_f32 v33, v137, |v33|, v45
	v_cndmask_b32_e32 v61, v33, v226, vcc
	v_add_f32_e32 v33, 0xc2f40000, v136
	v_fma_f32 v33, v137, |v33|, v46
	v_cndmask_b32_e32 v60, v33, v226, vcc
	v_add_f32_e32 v33, 0xc2f60000, v136
	v_fma_f32 v33, v137, |v33|, v47
	v_cndmask_b32_e32 v59, v33, v226, vcc
	v_add_f32_e32 v33, 0xc3000000, v136
	v_fma_f32 v16, v137, |v33|, v16
	v_cmp_lt_u32_e32 vcc, s1, v38
	v_max3_f32 v32, v32, v72, v71
	v_max3_f32 v32, v32, v70, v69
	v_cndmask_b32_e32 v58, v16, v226, vcc
	v_add_f32_e32 v16, 0xc3010000, v136
	v_fma_f32 v16, v137, |v16|, v17
	v_add_f32_e32 v17, 0xc3020000, v136
	v_fma_f32 v17, v137, |v17|, v18
	v_cndmask_b32_e32 v56, v17, v226, vcc
	v_add_f32_e32 v17, 0xc3030000, v136
	v_fma_f32 v17, v137, |v17|, v19
	v_cndmask_b32_e32 v55, v17, v226, vcc
	v_add_f32_e32 v17, 0xc3080000, v136
	v_cndmask_b32_e32 v57, v16, v226, vcc
	v_fma_f32 v17, v137, |v17|, v20
	v_cmp_lt_u32_e32 vcc, s1, v39
	v_max3_f32 v32, v32, v68, v63
	v_max3_f32 v32, v32, v62, v61
	v_cndmask_b32_e32 v54, v17, v226, vcc
	v_add_f32_e32 v17, 0xc3090000, v136
	v_fma_f32 v17, v137, |v17|, v21
	v_cndmask_b32_e32 v53, v17, v226, vcc
	v_add_f32_e32 v17, 0xc30a0000, v136
	v_fma_f32 v17, v137, |v17|, v22
	v_cndmask_b32_e32 v47, v17, v226, vcc
	v_add_f32_e32 v17, 0xc30b0000, v136
	v_fma_f32 v17, v137, |v17|, v23
	v_cndmask_b32_e32 v46, v17, v226, vcc
	v_add_f32_e32 v17, 0xc3100000, v136
	v_fma_f32 v17, v137, |v17|, v24
	v_subrev_co_u32_e32 v36, vcc, s0, v98
	v_max3_f32 v32, v32, v60, v59
	s_nop 0
	v_cndmask_b32_e32 v45, v17, v226, vcc
	v_add_f32_e32 v17, 0xc3110000, v136
	v_fma_f32 v17, v137, |v17|, v25
	v_cndmask_b32_e32 v44, v17, v226, vcc
	v_add_f32_e32 v17, 0xc3120000, v136
	v_fma_f32 v17, v137, |v17|, v26
	v_cndmask_b32_e32 v43, v17, v226, vcc
	v_add_f32_e32 v17, 0xc3130000, v136
	v_fma_f32 v17, v137, |v17|, v27
	v_cndmask_b32_e32 v42, v17, v226, vcc
	v_add_f32_e32 v17, 0xc3180000, v136
	v_fma_f32 v17, v137, |v17|, v28
	v_cmp_lt_u32_e32 vcc, s1, v37
	v_max3_f32 v16, v32, v58, v57
	v_add_u32_e32 v35, 0xa8, v98
	v_cndmask_b32_e32 v27, v17, v226, vcc
	v_add_f32_e32 v17, 0xc3190000, v136
	v_fma_f32 v17, v137, |v17|, v29
	v_cndmask_b32_e32 v26, v17, v226, vcc
	v_add_f32_e32 v17, 0xc31a0000, v136
	v_fma_f32 v17, v137, |v17|, v30
	v_cndmask_b32_e32 v25, v17, v226, vcc
	v_add_f32_e32 v17, 0xc31b0000, v136
	v_fma_f32 v17, v137, |v17|, v31
	v_cndmask_b32_e32 v24, v17, v226, vcc
	v_add_f32_e32 v17, 0xc3200000, v136
	v_fma_f32 v0, v137, |v17|, v0
	v_cmp_lt_u32_e32 vcc, s1, v34
	v_max3_f32 v16, v16, v56, v55
	v_max3_f32 v16, v16, v54, v53
	v_cndmask_b32_e32 v23, v0, v226, vcc
	v_add_f32_e32 v0, 0xc3210000, v136
	v_fma_f32 v0, v137, |v0|, v1
	v_add_f32_e32 v1, 0xc3220000, v136
	v_fma_f32 v1, v137, |v1|, v2
	v_cndmask_b32_e32 v21, v1, v226, vcc
	v_add_f32_e32 v1, 0xc3230000, v136
	v_fma_f32 v1, v137, |v1|, v3
	v_cndmask_b32_e32 v20, v1, v226, vcc
	v_add_f32_e32 v1, 0xc3280000, v136
	v_cndmask_b32_e32 v22, v0, v226, vcc
	v_fma_f32 v1, v137, |v1|, v4
	v_cmp_lt_u32_e32 vcc, s1, v35
	v_max3_f32 v16, v16, v47, v46
	v_max3_f32 v16, v16, v45, v44
	v_cndmask_b32_e32 v19, v1, v226, vcc
	v_add_f32_e32 v1, 0xc3290000, v136
	v_fma_f32 v1, v137, |v1|, v5
	v_cndmask_b32_e32 v18, v1, v226, vcc
	v_add_f32_e32 v1, 0xc32a0000, v136
	v_max3_f32 v16, v16, v43, v42
	v_fma_f32 v1, v137, |v1|, v6
	v_max3_f32 v16, v16, v27, v26
	v_cndmask_b32_e32 v17, v1, v226, vcc
	v_add_f32_e32 v1, 0xc32b0000, v136
	v_max3_f32 v16, v16, v25, v24
	v_fma_f32 v1, v137, |v1|, v7
	v_max3_f32 v0, v16, v23, v22
	v_cndmask_b32_e32 v16, v1, v226, vcc
	v_add_f32_e32 v1, 0xc3300000, v136
	v_add_u32_e32 v32, 0xb0, v98
	v_fma_f32 v1, v137, |v1|, v8
	v_cmp_lt_u32_e32 vcc, s1, v32
	v_add_u32_e32 v33, 0xb8, v98
	s_add_i32 s0, s7, s19
	v_cndmask_b32_e32 v7, v1, v226, vcc
	v_add_f32_e32 v1, 0xc3310000, v136
	v_fma_f32 v1, v137, |v1|, v9
	v_cndmask_b32_e32 v6, v1, v226, vcc
	v_add_f32_e32 v1, 0xc3320000, v136
	v_fma_f32 v1, v137, |v1|, v10
	v_cndmask_b32_e32 v5, v1, v226, vcc
	v_add_f32_e32 v1, 0xc3330000, v136
	v_fma_f32 v1, v137, |v1|, v11
	v_cndmask_b32_e32 v4, v1, v226, vcc
	v_cmp_lt_u32_e32 vcc, s1, v33
	s_ashr_i32 s1, s0, 31
	s_lshl_b64 s[0:1], s[0:1], 2
	s_add_u32 s0, s68, s0
	s_addc_u32 s1, s69, s1
	global_load_dword v10, v97, s[0:1]
	v_max3_f32 v0, v0, v21, v20
	v_add_f32_e32 v1, 0xc3380000, v136
	v_max3_f32 v0, v0, v19, v18
	v_fma_f32 v1, v137, |v1|, v12
	v_max3_f32 v0, v0, v17, v16
	v_cndmask_b32_e32 v3, v1, v226, vcc
	v_add_f32_e32 v1, 0xc3390000, v136
	v_max3_f32 v0, v0, v7, v6
	v_fma_f32 v1, v137, |v1|, v13
	v_max3_f32 v0, v0, v5, v4
	v_cndmask_b32_e32 v2, v1, v226, vcc
	v_max3_f32 v8, v0, v3, v2
	v_add_f32_e32 v0, 0xc33a0000, v136
	v_fma_f32 v0, v137, |v0|, v14
	v_cndmask_b32_e32 v1, v0, v226, vcc
	v_add_f32_e32 v0, 0xc33b0000, v136
	v_fma_f32 v0, v137, |v0|, v15
	v_cndmask_b32_e32 v0, v0, v226, vcc
	v_max3_f32 v8, v8, v1, v0
	ds_bpermute_b32 v9, v96, v8
	v_cmp_gt_u32_e32 vcc, 32, v208
	s_waitcnt vmcnt(0)
; __device__ __forceinline__ void attn_unit(const Params& p, int l, LAS unsigned char* lds, bool sample, int b, int c, int kvh) {
;     ...
;         mx = __builtin_fmaxf(mx, __shfl_xor(mx, 32));
;         const float sink2 = p.sinks[l * 8 + h] * LOG2E;
;         const float mm = __builtin_fmaxf(mx, sink2);
;         float sum = 0.f;
; #pragma unroll
;         for (int kt = 0; kt < 6; ++kt)
; #pragma unroll
;             for (int r = 0; r < 16; ++r) { const float e = __builtin_amdgcn_exp2f(s[kt][r] - mm); s[kt][r] = e; sum += e; }
	v_mul_f32_e32 v12, 0x3fb8aa3b, v10
	s_waitcnt lgkmcnt(0)
	v_max3_f32 v13, v8, v9, v12
	v_sub_f32_e32 v8, v135, v13
	v_exp_f32_e32 v8, v8
	v_sub_f32_e32 v9, v133, v13
	v_exp_f32_e32 v9, v9
	v_sub_f32_e32 v31, v126, v13
	v_add_f32_e32 v10, 0, v8
	v_exp_f32_e32 v126, v31
	v_add_f32_e32 v11, v9, v10
	v_sub_f32_e32 v10, v134, v13
	v_exp_f32_e32 v10, v10
	v_sub_f32_e32 v31, v127, v13
	v_exp_f32_e32 v127, v31
	v_sub_f32_e32 v31, v124, v13
	v_add_f32_e32 v14, v10, v11
	v_sub_f32_e32 v11, v132, v13
	v_exp_f32_e32 v11, v11
	v_exp_f32_e32 v124, v31
	v_sub_f32_e32 v31, v125, v13
	v_exp_f32_e32 v125, v31
	v_add_f32_e32 v15, v11, v14
	v_sub_f32_e32 v14, v131, v13
	v_exp_f32_e32 v14, v14
	v_sub_f32_e32 v31, v123, v13
	v_exp_f32_e32 v123, v31
	v_sub_f32_e32 v31, v121, v13
	v_add_f32_e32 v28, v14, v15
	v_sub_f32_e32 v15, v130, v13
	v_exp_f32_e32 v15, v15
	v_exp_f32_e32 v121, v31
	v_sub_f32_e32 v31, v122, v13
	v_exp_f32_e32 v122, v31
	v_add_f32_e32 v29, v15, v28
	v_sub_f32_e32 v28, v129, v13
	v_exp_f32_e32 v28, v28
	v_sub_f32_e32 v31, v120, v13
	v_exp_f32_e32 v120, v31
	v_sub_f32_e32 v31, v119, v13
	v_add_f32_e32 v30, v28, v29
	v_sub_f32_e32 v29, v128, v13
	v_exp_f32_e32 v29, v29
	v_exp_f32_e32 v119, v31
	v_sub_f32_e32 v31, v117, v13
	v_exp_f32_e32 v117, v31
	v_add_f32_e32 v30, v29, v30
	v_add_f32_e32 v30, v126, v30
	v_add_f32_e32 v30, v127, v30
	v_add_f32_e32 v30, v124, v30
	v_add_f32_e32 v30, v125, v30
	v_add_f32_e32 v30, v123, v30
	v_add_f32_e32 v30, v121, v30
	v_sub_f32_e32 v31, v118, v13
	v_add_f32_e32 v30, v122, v30
	v_exp_f32_e32 v118, v31
	v_sub_f32_e32 v31, v116, v13
	v_add_f32_e32 v30, v120, v30
	v_exp_f32_e32 v116, v31
	v_sub_f32_e32 v31, v115, v13
	v_add_f32_e32 v30, v119, v30
	v_exp_f32_e32 v115, v31
	v_sub_f32_e32 v31, v114, v13
	v_add_f32_e32 v30, v117, v30
	v_exp_f32_e32 v114, v31
	v_sub_f32_e32 v31, v113, v13
	v_add_f32_e32 v30, v118, v30
	v_exp_f32_e32 v113, v31
	v_sub_f32_e32 v31, v112, v13
	v_add_f32_e32 v30, v116, v30
	v_exp_f32_e32 v112, v31
	v_sub_f32_e32 v31, v108, v13
	v_add_f32_e32 v30, v115, v30
	v_exp_f32_e32 v108, v31
	v_sub_f32_e32 v31, v109, v13
	v_add_f32_e32 v30, v114, v30
	v_exp_f32_e32 v109, v31
	v_sub_f32_e32 v31, v106, v13
	v_add_f32_e32 v30, v113, v30
	v_exp_f32_e32 v106, v31
	v_sub_f32_e32 v31, v107, v13
	v_add_f32_e32 v30, v112, v30
	v_exp_f32_e32 v107, v31
	v_sub_f32_e32 v31, v105, v13
	v_add_f32_e32 v30, v108, v30
	v_exp_f32_e32 v105, v31
	v_sub_f32_e32 v31, v103, v13
	v_add_f32_e32 v30, v109, v30
	v_exp_f32_e32 v103, v31
	v_sub_f32_e32 v31, v104, v13
	v_add_f32_e32 v30, v106, v30
	v_exp_f32_e32 v104, v31
	v_sub_f32_e32 v31, v102, v13
	v_add_f32_e32 v30, v107, v30
	v_exp_f32_e32 v102, v31
	v_sub_f32_e32 v31, v101, v13
	v_add_f32_e32 v30, v105, v30
	v_exp_f32_e32 v101, v31
	v_sub_f32_e32 v31, v100, v13
	v_add_f32_e32 v30, v103, v30
	v_exp_f32_e32 v100, v31
	v_sub_f32_e32 v31, v99, v13
	v_add_f32_e32 v30, v104, v30
	v_exp_f32_e32 v99, v31
	v_sub_f32_e32 v31, v95, v13
	v_add_f32_e32 v30, v102, v30
	v_exp_f32_e32 v95, v31
	v_sub_f32_e32 v31, v94, v13
	v_add_f32_e32 v30, v101, v30
	v_exp_f32_e32 v94, v31
	v_sub_f32_e32 v31, v93, v13
	v_add_f32_e32 v30, v100, v30
	v_exp_f32_e32 v93, v31
	v_sub_f32_e32 v31, v92, v13
	v_add_f32_e32 v30, v99, v30
	v_exp_f32_e32 v92, v31
	v_sub_f32_e32 v31, v91, v13
	v_add_f32_e32 v30, v95, v30
	v_exp_f32_e32 v91, v31
	v_sub_f32_e32 v31, v90, v13
	v_add_f32_e32 v30, v94, v30
	v_exp_f32_e32 v90, v31
	v_sub_f32_e32 v31, v89, v13
	v_add_f32_e32 v30, v93, v30
	v_exp_f32_e32 v89, v31
	v_sub_f32_e32 v31, v88, v13
	v_add_f32_e32 v30, v92, v30
	v_exp_f32_e32 v88, v31
	v_sub_f32_e32 v31, v87, v13
	v_add_f32_e32 v30, v91, v30
	v_exp_f32_e32 v87, v31
	v_sub_f32_e32 v31, v86, v13
	v_add_f32_e32 v30, v90, v30
	v_exp_f32_e32 v86, v31
	v_sub_f32_e32 v31, v85, v13
	v_add_f32_e32 v30, v89, v30
	v_exp_f32_e32 v85, v31
	v_sub_f32_e32 v31, v84, v13
	v_add_f32_e32 v30, v88, v30
	v_exp_f32_e32 v84, v31
	v_sub_f32_e32 v31, v79, v13
	v_add_f32_e32 v30, v87, v30
	v_exp_f32_e32 v79, v31
	v_sub_f32_e32 v31, v78, v13
	v_add_f32_e32 v30, v86, v30
	v_exp_f32_e32 v78, v31
	v_sub_f32_e32 v31, v77, v13
	v_add_f32_e32 v30, v85, v30
	v_exp_f32_e32 v77, v31
	v_sub_f32_e32 v31, v76, v13
	v_add_f32_e32 v30, v84, v30
	v_exp_f32_e32 v76, v31
	v_sub_f32_e32 v31, v75, v13
	v_add_f32_e32 v30, v79, v30
	v_exp_f32_e32 v75, v31
; __device__ __forceinline__ void attn_unit(const Params& p, int l, LAS unsigned char* lds, bool sample, int b, int c, int kvh) {
;     ...
;         float sum = 0.f;
; #pragma unroll
;         for (int kt = 0; kt < 6; ++kt)
; #pragma unroll
;             for (int r = 0; r < 16; ++r) { const float e = __builtin_amdgcn_exp2f(s[kt][r] - mm); s[kt][r] = e; sum += e; }
;         sum += __shfl_xor(sum, 32);
;         const float denom = sum + __builtin_amdgcn_exp2f(sink2 - mm);
;         if (hi == 0) wsc[q32] = 1.0f / denom;
	v_sub_f32_e32 v31, v74, v13
	v_add_f32_e32 v30, v78, v30
	v_exp_f32_e32 v74, v31
	v_sub_f32_e32 v31, v73, v13
	v_add_f32_e32 v30, v77, v30
	v_exp_f32_e32 v73, v31
	v_sub_f32_e32 v31, v72, v13
	v_add_f32_e32 v30, v76, v30
	v_exp_f32_e32 v72, v31
	v_sub_f32_e32 v31, v71, v13
	v_add_f32_e32 v30, v75, v30
	v_exp_f32_e32 v71, v31
	v_sub_f32_e32 v31, v70, v13
	v_add_f32_e32 v30, v74, v30
	v_exp_f32_e32 v70, v31
	v_sub_f32_e32 v31, v69, v13
	v_add_f32_e32 v30, v73, v30
	v_exp_f32_e32 v69, v31
	v_sub_f32_e32 v31, v68, v13
	v_add_f32_e32 v30, v72, v30
	v_exp_f32_e32 v68, v31
	v_sub_f32_e32 v31, v63, v13
	v_add_f32_e32 v30, v71, v30
	v_exp_f32_e32 v63, v31
	v_sub_f32_e32 v31, v62, v13
	v_add_f32_e32 v30, v70, v30
	v_exp_f32_e32 v62, v31
	v_sub_f32_e32 v31, v61, v13
	v_add_f32_e32 v30, v69, v30
	v_exp_f32_e32 v61, v31
	v_sub_f32_e32 v31, v60, v13
	v_add_f32_e32 v30, v68, v30
	v_exp_f32_e32 v60, v31
	v_sub_f32_e32 v31, v59, v13
	v_add_f32_e32 v30, v63, v30
	v_exp_f32_e32 v59, v31
	v_sub_f32_e32 v31, v58, v13
	v_add_f32_e32 v30, v62, v30
	v_exp_f32_e32 v58, v31
	v_sub_f32_e32 v31, v57, v13
	v_add_f32_e32 v30, v61, v30
	v_exp_f32_e32 v57, v31
	v_sub_f32_e32 v31, v56, v13
	v_add_f32_e32 v30, v60, v30
	v_exp_f32_e32 v56, v31
	v_sub_f32_e32 v31, v55, v13
	v_add_f32_e32 v30, v59, v30
	v_exp_f32_e32 v55, v31
	v_sub_f32_e32 v31, v54, v13
	v_add_f32_e32 v30, v58, v30
	v_exp_f32_e32 v54, v31
	v_sub_f32_e32 v31, v53, v13
	v_add_f32_e32 v30, v57, v30
	v_exp_f32_e32 v53, v31
	v_sub_f32_e32 v31, v47, v13
	v_add_f32_e32 v30, v56, v30
	v_exp_f32_e32 v130, v31
	v_sub_f32_e32 v31, v46, v13
	v_add_f32_e32 v30, v55, v30
	v_exp_f32_e32 v134, v31
	v_sub_f32_e32 v31, v45, v13
	v_add_f32_e32 v30, v54, v30
	v_exp_f32_e32 v45, v31
	v_sub_f32_e32 v31, v44, v13
	v_add_f32_e32 v30, v53, v30
	v_exp_f32_e32 v44, v31
	v_sub_f32_e32 v31, v43, v13
	v_add_f32_e32 v30, v130, v30
	v_exp_f32_e32 v43, v31
	v_sub_f32_e32 v31, v42, v13
	v_add_f32_e32 v30, v134, v30
	v_exp_f32_e32 v46, v31
	v_sub_f32_e32 v27, v27, v13
	v_add_f32_e32 v30, v45, v30
	v_exp_f32_e32 v131, v27
	v_sub_f32_e32 v26, v26, v13
	v_add_f32_e32 v30, v44, v30
	v_exp_f32_e32 v135, v26
	v_sub_f32_e32 v25, v25, v13
	v_add_f32_e32 v30, v43, v30
	v_exp_f32_e32 v137, v25
	v_sub_f32_e32 v24, v24, v13
	v_add_f32_e32 v30, v46, v30
	v_exp_f32_e32 v140, v24
	v_sub_f32_e32 v23, v23, v13
	v_add_f32_e32 v27, v131, v30
	v_exp_f32_e32 v42, v23
	v_sub_f32_e32 v22, v22, v13
	v_add_f32_e32 v26, v135, v27
	v_exp_f32_e32 v47, v22
	v_sub_f32_e32 v21, v21, v13
	v_add_f32_e32 v25, v137, v26
	v_exp_f32_e32 v128, v21
	v_sub_f32_e32 v20, v20, v13
	v_add_f32_e32 v24, v140, v25
	v_exp_f32_e32 v132, v20
	v_sub_f32_e32 v19, v19, v13
	v_add_f32_e32 v23, v42, v24
	v_exp_f32_e32 v138, v19
	v_sub_f32_e32 v18, v18, v13
	v_add_f32_e32 v22, v47, v23
	v_exp_f32_e32 v141, v18
	v_sub_f32_e32 v17, v17, v13
	v_add_f32_e32 v21, v128, v22
	v_exp_f32_e32 v142, v17
	v_sub_f32_e32 v16, v16, v13
	v_add_f32_e32 v20, v132, v21
	v_exp_f32_e32 v144, v16
	v_sub_f32_e32 v7, v7, v13
	v_add_f32_e32 v19, v138, v20
	v_exp_f32_e32 v129, v7
	v_sub_f32_e32 v6, v6, v13
	v_add_f32_e32 v18, v141, v19
	v_exp_f32_e32 v133, v6
	v_sub_f32_e32 v5, v5, v13
	v_add_f32_e32 v17, v142, v18
	v_exp_f32_e32 v136, v5
	v_sub_f32_e32 v4, v4, v13
	v_add_f32_e32 v16, v144, v17
	v_exp_f32_e32 v139, v4
	v_sub_f32_e32 v3, v3, v13
	v_add_f32_e32 v7, v129, v16
	v_exp_f32_e32 v143, v3
	v_sub_f32_e32 v2, v2, v13
	v_add_f32_e32 v6, v133, v7
	v_exp_f32_e32 v145, v2
	v_sub_f32_e32 v1, v1, v13
	v_add_f32_e32 v5, v136, v6
	v_exp_f32_e32 v146, v1
	v_sub_f32_e32 v0, v0, v13
	v_add_f32_e32 v4, v139, v5
	v_exp_f32_e32 v147, v0
	v_add_f32_e32 v3, v143, v4
	v_add_f32_e32 v2, v145, v3
	v_add_f32_e32 v1, v146, v2
	v_add_f32_e32 v0, v147, v1
	ds_bpermute_b32 v1, v96, v0
	s_and_saveexec_b64 s[0:1], vcc
	s_cbranch_execz .LBB0_607
	v_sub_f32_e32 v2, v12, v13
	v_exp_f32_e32 v2, v2
	s_waitcnt lgkmcnt(0)
	v_add_f32_e32 v0, v0, v1
	v_add_f32_e32 v0, v2, v0
	v_div_scale_f32 v1, s[10:11], v0, v0, 1.0
	v_rcp_f32_e32 v2, v1
	v_div_scale_f32 v3, vcc, 1.0, v0, 1.0
	v_fma_f32 v4, -v1, v2, 1.0
	v_fmac_f32_e32 v2, v4, v2
	v_mul_f32_e32 v4, v3, v2
	v_fma_f32 v5, -v1, v4, v3
	v_fmac_f32_e32 v4, v5, v2
	v_fma_f32 v1, -v1, v4, v3
	v_div_fmas_f32 v1, v1, v2, v4
	v_div_fixup_f32 v0, v1, v0, 1.0
	v_lshl_add_u32 v1, v111, 2, s8
	ds_write_b32 v1, v0 offset:53248

; #define LAS __attribute__((address_space(3)))
; __device__ __forceinline__ void transpose_item(const float* W, int N, const float* ks, bf16_t* WT, int ldo, int orow0, int k0, int n0, LAS float* scr, int lane) {
;     f32x4 v[8];
; #pragma unroll
;     for (int i = 0; i < 8; ++i) v[i] = *(const f32x4*)(W + (size_t)(k0 + i * 4 + (lane >> 4)) * N + n0 + 4 * (lane & 15));
; #pragma unroll
;     for (int i = 0; i < 8; ++i) { const int kk = i * 4 + (lane >> 4); const float sc = ks ? ks[k0 + kk] : 1.0f; LAS float* d = scr + kk * 65 + 4 * (lane & 15);
;         d[0] = v[i][0] * sc; d[1] = v[i][1] * sc; d[2] = v[i][2] * sc; d[3] = v[i][3] * sc; }
; __device__ __forceinline__ void convert_weights(const Params& p, LAS unsigned char* lds, int first, int last, int worker, int nworkers) {
;     ...
;         const int l = it / WI_L; int r = it % WI_L;
;         unsigned char* wb = p.ws + WS_W + (size_t)l * W_LAYER;
;         if (r < WI_IN) { const int kb = r / 52, nb = r % 52; transpose_item(p.w_in + (size_t)l * DM * INW, INW, p.norm_mix + l * DM, (bf16_t*)(wb + WO_IN), DM, nb * 64, kb * 32, nb * 64, scr, lane); continue; } r -= WI_IN;
;         if (r < WI_BA) { const int kb = r / 16, nb = r % 16; transpose_item(p.w_br_attn + (size_t)l * 512 * DM, DM, nullptr, (bf16_t*)(wb + WO_MIX), 512, nb * 64, kb * 32, nb * 64, scr, lane); continue; } r -= WI_BA;
;         if (r < WI_OUT) { const int kb = r / 16, nb = r % 16; transpose_item(p.w_out + (size_t)l * DM * DM, DM, nullptr, (bf16_t*)(wb + WO_OUT), DM, nb * 64, kb * 32, nb * 64, scr, lane); continue; } r -= WI_OUT;
;         if (r < WI_UP) { const int kb = r / 88, nb = r % 88; const int n0 = nb * 64; const int nn = n0 < FF ? n0 : n0 - FF; const int orow = (nn >> 7) * 256 + (n0 < FF ? 0 : 128) + (nn & 127);
;             transpose_item(p.w_up + (size_t)l * DM * FF2, FF2, p.norm_ffn + l * DM, (bf16_t*)(wb + WO_UP), DM, orow, kb * 32, n0, scr, lane); continue; } r -= WI_UP;
.LBB0_626:
	s_andn2_b64 vcc, exec, s[0:1]
	s_cbranch_vccnz .LBB0_636
	s_add_i32 s0, s16, 0xf680
	s_and_b32 s1, s0, 0xffff
	s_mul_i32 s1, s1, 0xba2f
	s_lshr_b32 s17, s1, 22
	s_mul_i32 s1, s17, 0x58
	v_readlane_b32 s52, v248, 54
	s_sub_i32 s18, s0, s1
	s_mul_i32 s1, s2, 0x1600000
	v_readlane_b32 s56, v248, 58
	s_mul_hi_i32 s0, s2, 0x1600000
	v_readlane_b32 s57, v248, 59
	s_add_u32 s19, s56, s1
	s_addc_u32 s20, s57, s0
	s_lshl_b32 s0, s2, 10
	s_ashr_i32 s1, s0, 31
	v_readlane_b32 s54, v248, 56
	s_lshl_b64 s[0:1], s[0:1], 2
	v_readlane_b32 s55, v248, 57
	s_add_u32 s8, s54, s0
	s_addc_u32 s9, s55, s1
	s_lshl_b32 s0, s18, 8
	s_lshl_b32 s17, s17, 5
	s_and_b32 s0, s0, 0x3ff00
	s_add_u32 s0, s19, s0
	v_or_b32_e32 v42, s17, v32
	s_addc_u32 s1, s20, 0
	v_lshlrev_b32_e32 v96, 2, v34
	v_lshl_add_u64 v[0:1], s[0:1], 0, v[96:97]
	s_movk_i32 s0, 0x5800
	v_mul_u32_u24_e32 v4, 0x1600, v42
	v_mad_u64_u32 v[2:3], s[0:1], v42, s0, v[0:1]
	v_lshlrev_b32_e32 v96, 2, v4
	v_lshl_add_u64 v[0:1], v[0:1], 0, v[96:97]
	s_mov_b32 s0, 0x16000
	v_add_co_u32_e32 v4, vcc, s0, v0
	s_mov_b32 s0, 0x2c000
	s_nop 0
	v_addc_co_u32_e32 v5, vcc, 0, v1, vcc
	global_load_dwordx4 v[28:31], v[2:3], off nt
	global_load_dwordx4 v[24:27], v[4:5], off nt
	v_add_co_u32_e32 v2, vcc, s0, v0
	s_mov_b32 s0, 0x42000
	s_nop 0
	v_addc_co_u32_e32 v3, vcc, 0, v1, vcc
	v_add_co_u32_e32 v4, vcc, s0, v0
	s_mov_b32 s0, 0x58000
	s_nop 0
	v_addc_co_u32_e32 v5, vcc, 0, v1, vcc
	global_load_dwordx4 v[20:23], v[2:3], off nt
	global_load_dwordx4 v[16:19], v[4:5], off nt
	v_add_co_u32_e32 v2, vcc, s0, v0
	v_readlane_b32 s20, v247, 6
	s_nop 0
	v_addc_co_u32_e32 v3, vcc, 0, v1, vcc
	v_add_co_u32_e32 v4, vcc, 0x6e000, v0
	v_readlane_b32 s21, v247, 7
	s_nop 0
	v_addc_co_u32_e32 v5, vcc, 0, v1, vcc
	global_load_dwordx4 v[12:15], v[2:3], off nt
	global_load_dwordx4 v[8:11], v[4:5], off nt
	v_add_co_u32_e32 v2, vcc, 0x84000, v0
	v_cndmask_b32_e64 v40, 0, 1, s[20:21]
	s_nop 0
	v_addc_co_u32_e32 v3, vcc, 0, v1, vcc
	v_add_co_u32_e32 v0, vcc, 0x9a000, v0
	v_mov_b32_e32 v38, 1.0
	s_nop 0
	v_addc_co_u32_e32 v1, vcc, 0, v1, vcc
	global_load_dwordx4 v[4:7], v[2:3], off nt
	s_nop 0
	global_load_dwordx4 v[0:3], v[0:1], off nt
	v_cmp_ne_u32_e64 s[0:1], 1, v40
	s_andn2_b64 vcc, exec, s[20:21]
	v_add_lshl_u32 v41, v32, s17, 2
	v_mov_b32_e32 v40, 1.0
	v_readlane_b32 s53, v248, 55
	v_readlane_b32 s58, v248, 60
	v_readlane_b32 s59, v248, 61
	v_readlane_b32 s60, v248, 62
	v_readlane_b32 s61, v248, 63
	v_readlane_b32 s62, v247, 0
	v_readlane_b32 s63, v247, 1
	v_readlane_b32 s64, v247, 2
	v_readlane_b32 s65, v247, 3
	v_readlane_b32 s66, v247, 4
	v_readlane_b32 s67, v247, 5
	s_cbranch_vccnz .LBB0_629
	v_lshlrev_b32_e32 v40, 2, v42
	global_load_dword v40, v40, s[8:9]
	s_waitcnt vmcnt(0)
	v_pk_mul_f32 v[28:29], v[28:29], v[40:41] op_sel_hi:[1,0]
	v_pk_mul_f32 v[30:31], v[30:31], v[40:41] op_sel_hi:[1,0]
	global_load_dword v40, v41, s[8:9] offset:16

; #define LAS __attribute__((address_space(3)))
; __device__ __forceinline__ void transpose_item(const float* W, int N, const float* ks, bf16_t* WT, int ldo, int orow0, int k0, int n0, LAS float* scr, int lane) {
;     f32x4 v[8];
; #pragma unroll
;     for (int i = 0; i < 8; ++i) v[i] = *(const f32x4*)(W + (size_t)(k0 + i * 4 + (lane >> 4)) * N + n0 + 4 * (lane & 15));
; #pragma unroll
;     for (int i = 0; i < 8; ++i) { const int kk = i * 4 + (lane >> 4); const float sc = ks ? ks[k0 + kk] : 1.0f; LAS float* d = scr + kk * 65 + 4 * (lane & 15);
;         d[0] = v[i][0] * sc; d[1] = v[i][1] * sc; d[2] = v[i][2] * sc; d[3] = v[i][3] * sc; }
; __device__ __forceinline__ void convert_weights(const Params& p, LAS unsigned char* lds, int first, int last, int worker, int nworkers) {
;     ...
;     for (int it = first + worker; it < last; it += nworkers) {
;         const int l = it / WI_L; int r = it % WI_L;
;         unsigned char* wb = p.ws + WS_W + (size_t)l * W_LAYER;
;         if (r < WI_IN) { const int kb = r / 52, nb = r % 52; transpose_item(p.w_in + (size_t)l * DM * INW, INW, p.norm_mix + l * DM, (bf16_t*)(wb + WO_IN), DM, nb * 64, kb * 32, nb * 64, scr, lane); continue; } r -= WI_IN;
.LBB0_643:
	s_andn2_b64 vcc, exec, s[0:1]
	s_cbranch_vccnz .LBB0_620
	s_mul_i32 s0, s16, 0x4ec5
	s_lshr_b32 s1, s0, 31
	s_ashr_i32 s0, s0, 20
	s_add_i32 s3, s0, s1
	s_mul_i32 s0, s3, 52
	v_readlane_b32 s52, v249, 4
	s_sub_i32 s0, s16, s0
	s_mul_i32 s1, s2, 0xd00000
	v_readlane_b32 s66, v249, 18
	s_sext_i32_i16 s16, s0
	s_mul_hi_i32 s0, s2, 0xd00000
	v_readlane_b32 s67, v249, 19
	s_add_u32 s18, s66, s1
	s_addc_u32 s19, s67, s0
	s_lshl_b32 s0, s2, 10
	s_ashr_i32 s1, s0, 31
	v_readlane_b32 s64, v249, 16
	s_lshl_b64 s[0:1], s[0:1], 2
	v_readlane_b32 s65, v249, 17
	s_add_u32 s8, s64, s0
	s_addc_u32 s9, s65, s1
	s_lshl_b32 s0, s16, 6
	s_ashr_i32 s1, s0, 31
	s_lshl_b32 s2, s3, 5
	s_lshl_b64 s[16:17], s[0:1], 2
	v_or_b32_e32 v40, s2, v32
	s_add_u32 s16, s18, s16
	s_addc_u32 s17, s19, s17
	v_lshlrev_b32_e32 v96, 2, v34
	v_mul_i32_i24_e32 v4, 0xd00, v40
	v_lshl_add_u64 v[0:1], s[16:17], 0, v[96:97]
	v_mul_hi_i32_i24_e32 v3, 0x3400, v40
	v_mul_i32_i24_e32 v2, 0x3400, v40
	v_ashrrev_i32_e32 v5, 31, v4
	v_lshl_add_u64 v[2:3], v[0:1], 0, v[2:3]
	v_lshl_add_u64 v[0:1], v[4:5], 2, v[0:1]
	s_mov_b32 s1, 0xd000
	v_add_co_u32_e32 v4, vcc, s1, v0
	s_mov_b32 s1, 0x1a000
	s_nop 0
	v_addc_co_u32_e32 v5, vcc, 0, v1, vcc
	global_load_dwordx4 v[28:31], v[2:3], off nt
	global_load_dwordx4 v[24:27], v[4:5], off nt
	v_add_co_u32_e32 v2, vcc, s1, v0
	s_mov_b32 s1, 0x27000
	s_nop 0
	v_addc_co_u32_e32 v3, vcc, 0, v1, vcc
	v_add_co_u32_e32 v4, vcc, s1, v0
	s_mov_b32 s1, 0x34000
	s_nop 0
	v_addc_co_u32_e32 v5, vcc, 0, v1, vcc
	global_load_dwordx4 v[20:23], v[2:3], off nt
	global_load_dwordx4 v[16:19], v[4:5], off nt
	v_add_co_u32_e32 v2, vcc, s1, v0
	v_mov_b32_e32 v38, 1.0
	s_nop 0
	v_addc_co_u32_e32 v3, vcc, 0, v1, vcc
	v_add_co_u32_e32 v4, vcc, 0x41000, v0
	v_mov_b32_e32 v42, 1.0
	s_nop 0
	v_addc_co_u32_e32 v5, vcc, 0, v1, vcc
	global_load_dwordx4 v[12:15], v[2:3], off nt
	global_load_dwordx4 v[8:11], v[4:5], off nt
	v_add_co_u32_e32 v2, vcc, 0x4e000, v0
	v_readlane_b32 s53, v249, 5
	s_nop 0
	v_addc_co_u32_e32 v3, vcc, 0, v1, vcc
	v_add_co_u32_e32 v0, vcc, 0x5b000, v0
	v_readlane_b32 s54, v249, 6
	s_nop 0
	v_addc_co_u32_e32 v1, vcc, 0, v1, vcc
	global_load_dwordx4 v[4:7], v[2:3], off nt
	s_nop 0
	global_load_dwordx4 v[0:3], v[0:1], off nt
	s_and_b64 vcc, exec, s[46:47]
	v_readlane_b32 s55, v249, 7
	v_readlane_b32 s56, v249, 8
	v_readlane_b32 s57, v249, 9
	v_readlane_b32 s58, v249, 10
	v_readlane_b32 s59, v249, 11
	v_readlane_b32 s60, v249, 12
	v_readlane_b32 s61, v249, 13
	v_readlane_b32 s62, v249, 14
	v_readlane_b32 s63, v249, 15
	s_cbranch_vccnz .LBB0_646
	v_ashrrev_i32_e32 v41, 31, v40
	v_lshl_add_u64 v[40:41], v[40:41], 2, s[8:9]
	global_load_dword v40, v[40:41], off
	s_ashr_i32 s3, s2, 31
	s_waitcnt vmcnt(0)
	v_pk_mul_f32 v[28:29], v[28:29], v[40:41] op_sel_hi:[1,0]
	v_pk_mul_f32 v[30:31], v[30:31], v[40:41] op_sel_hi:[1,0]
	v_lshl_add_u64 v[40:41], s[2:3], 0, v[32:33]
	v_lshl_add_u64 v[40:41], v[40:41], 2, s[8:9]
	global_load_dword v42, v[40:41], off offset:16
